# gelu peepholes, final form: select at 172 of 192 sites, abs at 173; early placement only with no s_waitcnt in between (no load can be pending on the destination); s_nop restored where a removed instru
# speedup vs baseline: 1.0043x; 1.0043x over previous
.LBB0_443:
	s_waitcnt vmcnt(0)
	v_mov_b32_e32 v55, v0
	s_mov_b64 s[12:13], s[74:75]
	v_readfirstlane_b32 s0, v55
	s_ashr_i32 s10, s0, 6
	s_add_u32 s4, s12, 0x696e000
	v_bfe_u32 v3, v55, 4, 2
	s_addc_u32 s5, s13, 0
	s_lshl_b32 s11, s10, 4
	s_ashr_i32 s71, s70, 31
	v_or_b32_e32 v16, s11, v3
	s_lshl_b64 s[6:7], s[70:71], 7
	v_ashrrev_i32_e32 v17, 31, v16
	v_lshl_add_u64 v[4:5], s[6:7], 0, v[16:17]
	v_and_b32_e32 v54, 15, v55
	v_lshlrev_b64 v[4:5], 11, v[4:5]
	v_lshl_add_u64 v[4:5], s[4:5], 0, v[4:5]
	v_lshlrev_b32_e32 v6, 4, v54
	s_waitcnt lgkmcnt(0)
	v_mov_b32_e32 v7, v2
	v_lshl_add_u64 v[20:21], v[4:5], 0, v[6:7]
	s_barrier
	global_load_dwordx4 v[8:11], v[20:21], off
	global_load_dwordx4 v[4:7], v[20:21], off offset:256
	v_mov_b64_e32 v[18:19], s[44:45]
	v_mov_b32_e32 v13, v2
	s_waitcnt vmcnt(1)
	v_lshlrev_b32_e32 v24, 16, v10
	v_and_b32_e32 v25, 0xffff0000, v10
	v_and_b32_e32 v15, 0xffff0000, v8
	v_and_b32_e32 v23, 0xffff0000, v9
	v_lshlrev_b32_e32 v22, 16, v9
	v_lshlrev_b32_e32 v14, 16, v8
	v_lshlrev_b32_e32 v8, 16, v11
	v_and_b32_e32 v9, 0xffff0000, v11
	v_fma_f32 v10, |v24|, s40, 1.0
	v_fma_f32 v11, |v25|, s40, 1.0
	v_fma_f32 v28, |v14|, s40, 1.0
	v_fma_f32 v29, |v15|, s40, 1.0
	v_rcp_f32_e32 v10, v10
	v_rcp_f32_e32 v11, v11
	v_fma_f32 v32, |v22|, s40, 1.0
	v_fma_f32 v33, |v23|, s40, 1.0
	v_rcp_f32_e32 v28, v28
	v_rcp_f32_e32 v29, v29
	v_rcp_f32_e32 v32, v32
	v_rcp_f32_e32 v33, v33
	v_pk_mul_f32 v[26:27], v[24:25], v[24:25]
	v_pk_mul_f32 v[30:31], v[14:15], v[14:15]
	v_pk_mul_f32 v[26:27], v[26:27], s[64:65] op_sel_hi:[1,0]
	v_pk_fma_f32 v[36:37], v[10:11], s[42:43], v[18:19] op_sel_hi:[1,0,0]
	v_pk_mul_f32 v[34:35], v[22:23], v[22:23]
	v_pk_mul_f32 v[30:31], v[30:31], s[64:65] op_sel_hi:[1,0]
	v_exp_f32_e32 v26, v26
	v_exp_f32_e32 v27, v27
	v_pk_fma_f32 v[38:39], v[28:29], s[42:43], v[18:19] op_sel_hi:[1,0,0]
	v_pk_fma_f32 v[36:37], v[10:11], v[36:37], s[48:49] op_sel_hi:[1,1,0]
	v_pk_mul_f32 v[34:35], v[34:35], s[64:65] op_sel_hi:[1,0]
	v_exp_f32_e32 v30, v30
	v_exp_f32_e32 v31, v31
	v_pk_fma_f32 v[40:41], v[32:33], s[42:43], v[18:19] op_sel_hi:[1,0,0]
	v_pk_fma_f32 v[38:39], v[28:29], v[38:39], s[48:49] op_sel_hi:[1,1,0]
	v_pk_fma_f32 v[36:37], v[10:11], v[36:37], s[50:51] op_sel_hi:[1,1,0]
	v_exp_f32_e32 v34, v34
	v_exp_f32_e32 v35, v35
	v_pk_fma_f32 v[40:41], v[32:33], v[40:41], s[48:49] op_sel_hi:[1,1,0]
	v_pk_fma_f32 v[38:39], v[28:29], v[38:39], s[50:51] op_sel_hi:[1,1,0]
	v_pk_fma_f32 v[36:37], v[10:11], v[36:37], s[56:57] op_sel_hi:[1,1,0]
	v_pk_fma_f32 v[40:41], v[32:33], v[40:41], s[50:51] op_sel_hi:[1,1,0]
	v_pk_fma_f32 v[38:39], v[28:29], v[38:39], s[56:57] op_sel_hi:[1,1,0]
	v_pk_mul_f32 v[10:11], v[10:11], v[36:37]
	v_pk_fma_f32 v[40:41], v[32:33], v[40:41], s[56:57] op_sel_hi:[1,1,0]
	v_pk_mul_f32 v[28:29], v[28:29], v[38:39]
	v_pk_mul_f32 v[10:11], v[26:27], v[10:11]
	v_pk_mul_f32 v[32:33], v[32:33], v[40:41]
	v_pk_mul_f32 v[26:27], v[30:31], v[28:29]
	v_max_f32_e32 v80, 0, v24
	v_fma_f32 v37, -|v24|, v10, v80
	v_max_f32_e32 v81, 0, v25
	v_fma_f32 v11, -|v25|, v11, v81
	v_pk_mul_f32 v[28:29], v[34:35], v[32:33]
	v_max_f32_e32 v82, 0, v22
	v_fma_f32 v25, -|v22|, v28, v82
	v_max_f32_e32 v83, 0, v23
	v_fma_f32 v23, -|v23|, v29, v83
	v_max_f32_e32 v84, 0, v14
	v_fma_f32 v24, -|v14|, v26, v84
	v_max_f32_e32 v85, 0, v15
	v_fma_f32 v15, -|v15|, v27, v85
	v_mul_f32_e32 v36, v37, v37
	v_mov_b32_e32 v14, v25
	v_mul_f32_e32 v10, v11, v11
	v_mul_f32_e32 v26, v24, v24
	v_pk_add_f32 v[10:11], v[36:37], v[10:11]
	v_mov_b32_e32 v27, v25
	v_mul_f32_e32 v22, v15, v15
	v_mul_f32_e32 v12, v23, v23
	v_pk_add_f32 v[22:23], v[26:27], v[22:23]
	v_pk_mul_f32 v[26:27], v[24:25], v[14:15] op_sel:[1,0] op_sel_hi:[0,1]
	v_pk_add_f32 v[14:15], v[24:25], v[14:15] op_sel:[1,0] op_sel_hi:[0,1]
	v_mov_b32_e32 v27, v15
	v_fma_f32 v14, |v8|, s40, 1.0
	v_fma_f32 v15, |v9|, s40, 1.0
	v_pk_add_f32 v[12:13], v[26:27], v[12:13]
	v_rcp_f32_e32 v14, v14
	v_rcp_f32_e32 v15, v15
	v_pk_add_f32 v[12:13], v[22:23], v[12:13]
	v_pk_add_f32 v[22:23], v[10:11], v[12:13]
	v_pk_mul_f32 v[12:13], v[8:9], v[8:9]
	v_pk_fma_f32 v[10:11], v[14:15], s[42:43], v[18:19] op_sel_hi:[1,0,0]
	v_pk_mul_f32 v[12:13], v[12:13], s[64:65] op_sel_hi:[1,0]
	v_pk_fma_f32 v[10:11], v[14:15], v[10:11], s[48:49] op_sel_hi:[1,1,0]
	v_exp_f32_e32 v12, v12
	v_exp_f32_e32 v13, v13
	v_pk_fma_f32 v[10:11], v[14:15], v[10:11], s[50:51] op_sel_hi:[1,1,0]
	s_waitcnt vmcnt(0)
	v_lshlrev_b32_e32 v36, 16, v6
	v_pk_fma_f32 v[10:11], v[14:15], v[10:11], s[56:57] op_sel_hi:[1,1,0]
	v_and_b32_e32 v37, 0xffff0000, v6
	v_pk_mul_f32 v[10:11], v[14:15], v[10:11]
	v_pk_mul_f32 v[10:11], v[12:13], v[10:11]
	v_max_f32_e32 v86, 0, v8
	v_fma_f32 v15, -|v8|, v10, v86
	v_max_f32_e32 v90, 0, v9
	v_fma_f32 v9, -|v9|, v11, v90
	v_fma_f32 v32, |v36|, s40, 1.0
	v_fma_f32 v33, |v37|, s40, 1.0
	v_lshlrev_b32_e32 v12, 16, v4
	v_and_b32_e32 v10, 0x7fffffff, v12
	v_and_b32_e32 v13, 0xffff0000, v4
	v_and_b32_e32 v11, 0x7fffffff, v13
	v_pk_fma_f32 v[10:11], v[10:11], s[40:41], 1.0 op_sel_hi:[1,0,0]
	v_mul_f32_e32 v14, v15, v15
	v_rcp_f32_e32 v10, v10
	v_rcp_f32_e32 v11, v11
	v_mul_f32_e32 v8, v9, v9
	v_pk_add_f32 v[24:25], v[14:15], v[8:9]
	v_pk_mul_f32 v[14:15], v[12:13], v[12:13]
	v_pk_fma_f32 v[8:9], v[10:11], s[42:43], v[18:19] op_sel_hi:[1,0,0]
	v_pk_mul_f32 v[14:15], v[14:15], s[64:65] op_sel_hi:[1,0]
	v_pk_fma_f32 v[8:9], v[10:11], v[8:9], s[48:49] op_sel_hi:[1,1,0]
	v_exp_f32_e32 v14, v14
	v_exp_f32_e32 v15, v15
	v_pk_fma_f32 v[8:9], v[10:11], v[8:9], s[50:51] op_sel_hi:[1,1,0]
	v_lshlrev_b32_e32 v4, 16, v5
	v_pk_fma_f32 v[8:9], v[10:11], v[8:9], s[56:57] op_sel_hi:[1,1,0]
	v_and_b32_e32 v5, 0xffff0000, v5
	v_pk_mul_f32 v[8:9], v[10:11], v[8:9]
	v_pk_mul_f32 v[14:15], v[14:15], v[8:9]
	global_load_dwordx4 v[8:11], v[20:21], off offset:512
	v_fma_f32 v30, |v4|, s40, 1.0
	v_fma_f32 v31, |v5|, s40, 1.0
	v_rcp_f32_e32 v30, v30
	v_rcp_f32_e32 v31, v31
	v_max_f32_e32 v91, 0, v12
	v_fma_f32 v27, -|v12|, v14, v91
	v_max_f32_e32 v92, 0, v13
	v_fma_f32 v29, -|v13|, v15, v92
	v_rcp_f32_e32 v34, v32
	v_rcp_f32_e32 v35, v33
	v_pk_fma_f32 v[12:13], v[30:31], s[42:43], v[18:19] op_sel_hi:[1,0,0]
	v_mul_f32_e32 v26, v27, v27
	v_pk_mul_f32 v[14:15], v[4:5], v[4:5]
	v_pk_fma_f32 v[12:13], v[30:31], v[12:13], s[48:49] op_sel_hi:[1,1,0]
	v_pk_mul_f32 v[14:15], v[14:15], s[64:65] op_sel_hi:[1,0]
	v_pk_fma_f32 v[12:13], v[30:31], v[12:13], s[50:51] op_sel_hi:[1,1,0]
	v_exp_f32_e32 v14, v14
	v_exp_f32_e32 v15, v15
	v_pk_fma_f32 v[12:13], v[30:31], v[12:13], s[56:57] op_sel_hi:[1,1,0]
	v_pk_mul_f32 v[12:13], v[30:31], v[12:13]
	v_mul_f32_e32 v28, v29, v29
	v_pk_mul_f32 v[12:13], v[14:15], v[12:13]
	v_pk_add_f32 v[22:23], v[24:25], v[22:23]
	v_max_f32_e32 v93, 0, v4
	v_fma_f32 v31, -|v4|, v12, v93
	v_max_f32_e32 v94, 0, v5
	v_fma_f32 v33, -|v5|, v13, v94
	v_pk_add_f32 v[24:25], v[26:27], v[28:29]
	v_pk_fma_f32 v[4:5], v[34:35], s[42:43], v[18:19] op_sel_hi:[1,0,0]
	v_lshlrev_b32_e32 v14, 16, v7
	v_pk_mul_f32 v[12:13], v[36:37], v[36:37]
	v_pk_fma_f32 v[4:5], v[34:35], v[4:5], s[48:49] op_sel_hi:[1,1,0]
	v_pk_mul_f32 v[12:13], v[12:13], s[64:65] op_sel_hi:[1,0]
	v_pk_fma_f32 v[4:5], v[34:35], v[4:5], s[50:51] op_sel_hi:[1,1,0]
	v_exp_f32_e32 v12, v12
	v_exp_f32_e32 v13, v13
	v_and_b32_e32 v15, 0xffff0000, v7
	v_pk_fma_f32 v[4:5], v[34:35], v[4:5], s[56:57] op_sel_hi:[1,1,0]
	v_pk_mul_f32 v[4:5], v[34:35], v[4:5]
	v_fma_f32 v6, |v14|, s40, 1.0
	v_fma_f32 v7, |v15|, s40, 1.0
	v_pk_mul_f32 v[4:5], v[12:13], v[4:5]
	v_rcp_f32_e32 v6, v6
	v_rcp_f32_e32 v7, v7
	v_max_f32_e32 v95, 0, v36
	v_fma_f32 v35, -|v36|, v4, v95
	v_max_f32_e32 v96, 0, v37
	v_fma_f32 v37, -|v37|, v5, v96
	v_mul_f32_e32 v30, v31, v31
	v_mul_f32_e32 v32, v33, v33
	v_mul_f32_e32 v34, v35, v35
	v_pk_add_f32 v[22:23], v[24:25], v[22:23]
	v_pk_mul_f32 v[12:13], v[14:15], v[14:15]
	v_pk_fma_f32 v[4:5], v[6:7], s[42:43], v[18:19] op_sel_hi:[1,0,0]
	v_pk_mul_f32 v[12:13], v[12:13], s[64:65] op_sel_hi:[1,0]
	v_pk_fma_f32 v[4:5], v[6:7], v[4:5], s[48:49] op_sel_hi:[1,1,0]
	v_exp_f32_e32 v12, v12
	v_exp_f32_e32 v13, v13
	v_pk_fma_f32 v[4:5], v[6:7], v[4:5], s[50:51] op_sel_hi:[1,1,0]
	v_cmp_gt_f32_e32 vcc, 0, v14
	v_pk_fma_f32 v[4:5], v[6:7], v[4:5], s[56:57] op_sel_hi:[1,1,0]
	v_mul_f32_e32 v36, v37, v37
	v_pk_mul_f32 v[4:5], v[6:7], v[4:5]
	v_pk_add_f32 v[24:25], v[30:31], v[32:33]
	v_pk_mul_f32 v[4:5], v[12:13], v[4:5]
	v_pk_add_f32 v[22:23], v[24:25], v[22:23]
	v_pk_mul_f32 v[12:13], v[14:15], v[4:5]
	v_pk_fma_f32 v[40:41], v[14:15], v[4:5], v[14:15] neg_lo:[1,0,0] neg_hi:[1,0,0]
	global_load_dwordx4 v[4:7], v[20:21], off offset:768
	v_cndmask_b32_e32 v39, v40, v12, vcc
	v_cmp_gt_f32_e32 vcc, 0, v15
	v_mul_f32_e32 v38, v39, v39
	s_waitcnt vmcnt(1)
	v_lshlrev_b32_e32 v44, 16, v8
	v_and_b32_e32 v45, 0xffff0000, v8
	v_fma_f32 v42, |v44|, s40, 1.0
	v_fma_f32 v43, |v45|, s40, 1.0
	v_pk_mul_f32 v[14:15], v[44:45], v[44:45]
	v_rcp_f32_e32 v42, v42
	v_rcp_f32_e32 v43, v43
	v_cndmask_b32_e32 v41, v41, v13, vcc
	v_pk_mul_f32 v[14:15], v[14:15], s[64:65] op_sel_hi:[1,0]
	v_lshlrev_b32_e32 v46, 16, v9
	v_pk_fma_f32 v[12:13], v[42:43], s[42:43], v[18:19] op_sel_hi:[1,0,0]
	v_exp_f32_e32 v14, v14
	v_pk_fma_f32 v[12:13], v[42:43], v[12:13], s[48:49] op_sel_hi:[1,1,0]
	v_exp_f32_e32 v15, v15
	v_and_b32_e32 v47, 0xffff0000, v9
	v_pk_fma_f32 v[12:13], v[42:43], v[12:13], s[50:51] op_sel_hi:[1,1,0]
	v_pk_fma_f32 v[12:13], v[42:43], v[12:13], s[56:57] op_sel_hi:[1,1,0]
	v_fma_f32 v8, |v46|, s40, 1.0
	v_fma_f32 v9, |v47|, s40, 1.0
	v_pk_mul_f32 v[12:13], v[42:43], v[12:13]
	v_rcp_f32_e32 v48, v8
	v_rcp_f32_e32 v49, v9
	v_pk_mul_f32 v[12:13], v[14:15], v[12:13]
	v_max_f32_e32 v99, 0, v44
	v_fma_f32 v43, -|v44|, v12, v99
	v_max_f32_e32 v100, 0, v45
	v_fma_f32 v9, -|v45|, v13, v100
	v_lshlrev_b32_e32 v50, 16, v10
	v_and_b32_e32 v51, 0xffff0000, v10
	v_lshlrev_b32_e32 v10, 16, v11
	v_pk_fma_f32 v[12:13], v[48:49], s[42:43], v[18:19] op_sel_hi:[1,0,0]
	v_pk_mul_f32 v[14:15], v[46:47], v[46:47]
	v_pk_fma_f32 v[12:13], v[48:49], v[12:13], s[48:49] op_sel_hi:[1,1,0]
	v_pk_mul_f32 v[14:15], v[14:15], s[64:65] op_sel_hi:[1,0]
	v_pk_fma_f32 v[12:13], v[48:49], v[12:13], s[50:51] op_sel_hi:[1,1,0]
	v_exp_f32_e32 v14, v14
	v_exp_f32_e32 v15, v15
	v_pk_fma_f32 v[12:13], v[48:49], v[12:13], s[56:57] op_sel_hi:[1,1,0]
	v_pk_mul_f32 v[12:13], v[48:49], v[12:13]
	v_fma_f32 v48, |v50|, s40, 1.0
	v_fma_f32 v49, |v51|, s40, 1.0
	v_pk_mul_f32 v[12:13], v[14:15], v[12:13]
	v_rcp_f32_e32 v48, v48
	v_rcp_f32_e32 v49, v49
	v_max_f32_e32 v104, 0, v46
	v_fma_f32 v45, -|v46|, v12, v104
	v_max_f32_e32 v105, 0, v47
	v_fma_f32 v47, -|v47|, v13, v105
	v_and_b32_e32 v11, 0xffff0000, v11
	v_pk_mul_f32 v[14:15], v[50:51], v[50:51]
	v_pk_fma_f32 v[12:13], v[48:49], s[42:43], v[18:19] op_sel_hi:[1,0,0]
	v_pk_mul_f32 v[14:15], v[14:15], s[64:65] op_sel_hi:[1,0]
	v_pk_fma_f32 v[12:13], v[48:49], v[12:13], s[48:49] op_sel_hi:[1,1,0]
	v_exp_f32_e32 v14, v14
	v_exp_f32_e32 v15, v15
	v_pk_fma_f32 v[12:13], v[48:49], v[12:13], s[50:51] op_sel_hi:[1,1,0]
	v_fma_f32 v52, |v10|, s40, 1.0
	v_fma_f32 v53, |v11|, s40, 1.0
	v_pk_fma_f32 v[12:13], v[48:49], v[12:13], s[56:57] op_sel_hi:[1,1,0]
	v_rcp_f32_e32 v52, v52
	v_pk_mul_f32 v[12:13], v[48:49], v[12:13]
	v_rcp_f32_e32 v53, v53
	v_pk_mul_f32 v[12:13], v[14:15], v[12:13]
	v_max_f32_e32 v106, 0, v50
	v_mul_f32_e32 v40, v41, v41
	v_fma_f32 v49, -|v50|, v12, v106
	v_max_f32_e32 v107, 0, v51
	s_waitcnt vmcnt(0)
	v_lshlrev_b32_e32 v56, 16, v4
	v_and_b32_e32 v57, 0xffff0000, v4
	v_fma_f32 v51, -|v51|, v13, v107
	v_pk_mul_f32 v[14:15], v[10:11], v[10:11]
	v_pk_fma_f32 v[12:13], v[52:53], s[42:43], v[18:19] op_sel_hi:[1,0,0]
	v_pk_mul_f32 v[14:15], v[14:15], s[64:65] op_sel_hi:[1,0]
	v_pk_fma_f32 v[12:13], v[52:53], v[12:13], s[48:49] op_sel_hi:[1,1,0]
	v_exp_f32_e32 v14, v14
	v_exp_f32_e32 v15, v15
	v_pk_fma_f32 v[12:13], v[52:53], v[12:13], s[50:51] op_sel_hi:[1,1,0]
	v_pk_fma_f32 v[12:13], v[52:53], v[12:13], s[56:57] op_sel_hi:[1,1,0]
	v_pk_mul_f32 v[12:13], v[52:53], v[12:13]
	v_fma_f32 v58, |v56|, s40, 1.0
	v_fma_f32 v59, |v57|, s40, 1.0
	v_pk_mul_f32 v[12:13], v[14:15], v[12:13]
	v_rcp_f32_e32 v58, v58
	v_rcp_f32_e32 v59, v59
	v_max_f32_e32 v108, 0, v10
	v_fma_f32 v53, -|v10|, v12, v108
	v_max_f32_e32 v109, 0, v11
	v_fma_f32 v11, -|v11|, v13, v109
	v_lshlrev_b32_e32 v4, 16, v5
	v_and_b32_e32 v5, 0xffff0000, v5
	v_pk_mul_f32 v[14:15], v[56:57], v[56:57]
	v_pk_fma_f32 v[12:13], v[58:59], s[42:43], v[18:19] op_sel_hi:[1,0,0]
	v_pk_mul_f32 v[14:15], v[14:15], s[64:65] op_sel_hi:[1,0]
	v_pk_fma_f32 v[12:13], v[58:59], v[12:13], s[48:49] op_sel_hi:[1,1,0]
	v_exp_f32_e32 v14, v14
	v_exp_f32_e32 v15, v15
	v_pk_fma_f32 v[12:13], v[58:59], v[12:13], s[50:51] op_sel_hi:[1,1,0]
	v_fma_f32 v60, |v4|, s40, 1.0
	v_fma_f32 v61, |v5|, s40, 1.0
	v_pk_fma_f32 v[12:13], v[58:59], v[12:13], s[56:57] op_sel_hi:[1,1,0]
	v_rcp_f32_e32 v60, v60
	v_pk_mul_f32 v[12:13], v[58:59], v[12:13]
	v_rcp_f32_e32 v61, v61
	v_pk_mul_f32 v[12:13], v[14:15], v[12:13]
	v_max_f32_e32 v110, 0, v56
	v_fma_f32 v59, -|v56|, v12, v110
	v_max_f32_e32 v111, 0, v57
	v_fma_f32 v57, -|v57|, v13, v111
	v_pk_add_f32 v[24:25], v[34:35], v[36:37]
	v_mul_f32_e32 v42, v43, v43
	v_mul_f32_e32 v8, v9, v9
	v_pk_fma_f32 v[12:13], v[60:61], s[42:43], v[18:19] op_sel_hi:[1,0,0]
	v_pk_mul_f32 v[14:15], v[4:5], v[4:5]
	v_pk_fma_f32 v[12:13], v[60:61], v[12:13], s[48:49] op_sel_hi:[1,1,0]
	v_pk_mul_f32 v[14:15], v[14:15], s[64:65] op_sel_hi:[1,0]
	v_pk_fma_f32 v[12:13], v[60:61], v[12:13], s[50:51] op_sel_hi:[1,1,0]
	v_exp_f32_e32 v62, v14
	v_exp_f32_e32 v63, v15
	v_pk_fma_f32 v[64:65], v[60:61], v[12:13], s[56:57] op_sel_hi:[1,1,0]
	global_load_dwordx4 v[12:15], v[20:21], off offset:1024
	v_pk_add_f32 v[22:23], v[24:25], v[22:23]
	v_pk_add_f32 v[24:25], v[38:39], v[40:41]
	v_mul_f32_e32 v44, v45, v45
	v_mul_f32_e32 v46, v47, v47
	v_pk_add_f32 v[22:23], v[24:25], v[22:23]
	v_pk_add_f32 v[8:9], v[42:43], v[8:9]
	v_mul_f32_e32 v48, v49, v49
	v_mul_f32_e32 v50, v51, v51
	v_pk_mul_f32 v[60:61], v[60:61], v[64:65]
	v_pk_add_f32 v[8:9], v[8:9], v[22:23]
	v_pk_add_f32 v[22:23], v[44:45], v[46:47]
	v_pk_mul_f32 v[60:61], v[62:63], v[60:61]
	v_pk_add_f32 v[8:9], v[22:23], v[8:9]
	v_pk_add_f32 v[22:23], v[48:49], v[50:51]
	v_lshlrev_b32_e32 v24, 16, v6
	v_and_b32_e32 v25, 0xffff0000, v6
	v_max_f32_e32 v112, 0, v4
	v_fma_f32 v65, -|v4|, v60, v112
	v_max_f32_e32 v113, 0, v5
	v_fma_f32 v5, -|v5|, v61, v113
	v_pk_add_f32 v[8:9], v[22:23], v[8:9]
	v_mul_f32_e32 v52, v53, v53
	v_mul_f32_e32 v10, v11, v11
	v_fma_f32 v22, |v24|, s40, 1.0
	v_fma_f32 v23, |v25|, s40, 1.0
	v_mul_f32_e32 v58, v59, v59
	v_mul_f32_e32 v56, v57, v57
	v_pk_add_f32 v[10:11], v[52:53], v[10:11]
	v_rcp_f32_e32 v26, v22
	v_rcp_f32_e32 v27, v23
	v_mul_f32_e32 v64, v65, v65
	v_mul_f32_e32 v4, v5, v5
	v_pk_add_f32 v[8:9], v[10:11], v[8:9]
	v_pk_add_f32 v[10:11], v[58:59], v[56:57]
	v_pk_add_f32 v[4:5], v[64:65], v[4:5]
	v_pk_add_f32 v[8:9], v[10:11], v[8:9]
	v_pk_add_f32 v[22:23], v[4:5], v[8:9]
	v_pk_mul_f32 v[8:9], v[24:25], v[24:25]
	v_pk_fma_f32 v[4:5], v[26:27], s[42:43], v[18:19] op_sel_hi:[1,0,0]
	v_pk_mul_f32 v[8:9], v[8:9], s[64:65] op_sel_hi:[1,0]
	v_pk_fma_f32 v[4:5], v[26:27], v[4:5], s[48:49] op_sel_hi:[1,1,0]
	v_exp_f32_e32 v8, v8
	v_exp_f32_e32 v9, v9
	v_pk_fma_f32 v[4:5], v[26:27], v[4:5], s[50:51] op_sel_hi:[1,1,0]
	v_lshlrev_b32_e32 v6, 16, v7
	v_pk_fma_f32 v[4:5], v[26:27], v[4:5], s[56:57] op_sel_hi:[1,1,0]
	v_and_b32_e32 v7, 0xffff0000, v7
	v_pk_mul_f32 v[4:5], v[26:27], v[4:5]
	s_nop 0
	v_pk_mul_f32 v[4:5], v[8:9], v[4:5]
	s_nop 0
	v_max_f32_e32 v114, 0, v24
	v_fma_f32 v11, -|v24|, v4, v114
	v_max_f32_e32 v115, 0, v25
	v_fma_f32 v5, -|v25|, v5, v115
	s_nop 0
	v_mul_f32_e32 v10, v11, v11
	v_fma_f32 v8, |v6|, s40, 1.0
	v_fma_f32 v9, |v7|, s40, 1.0
	v_mul_f32_e32 v4, v5, v5
	v_rcp_f32_e32 v8, v8
	v_rcp_f32_e32 v9, v9
	v_pk_add_f32 v[24:25], v[10:11], v[4:5]
	v_pk_mul_f32 v[10:11], v[6:7], v[6:7]
	v_pk_fma_f32 v[4:5], v[8:9], s[42:43], v[18:19] op_sel_hi:[1,0,0]
	v_pk_mul_f32 v[10:11], v[10:11], s[64:65] op_sel_hi:[1,0]
	v_pk_fma_f32 v[4:5], v[8:9], v[4:5], s[48:49] op_sel_hi:[1,1,0]
	v_exp_f32_e32 v10, v10
	v_exp_f32_e32 v11, v11
	v_pk_fma_f32 v[4:5], v[8:9], v[4:5], s[50:51] op_sel_hi:[1,1,0]
	v_pk_add_f32 v[22:23], v[24:25], v[22:23]
	v_pk_fma_f32 v[4:5], v[8:9], v[4:5], s[56:57] op_sel_hi:[1,1,0]
	s_nop 0
	v_pk_mul_f32 v[4:5], v[8:9], v[4:5]
	s_nop 0
	v_pk_mul_f32 v[4:5], v[10:11], v[4:5]
	global_load_dwordx4 v[8:11], v[20:21], off offset:1280
	s_waitcnt vmcnt(1)
	v_lshlrev_b32_e32 v32, 16, v12
	v_and_b32_e32 v33, 0xffff0000, v12
	v_fma_f32 v30, |v32|, s40, 1.0
	v_fma_f32 v31, |v33|, s40, 1.0
	v_rcp_f32_e32 v30, v30
	v_rcp_f32_e32 v31, v31
	v_max_f32_e32 v116, 0, v6
	v_fma_f32 v27, -|v6|, v4, v116
	v_max_f32_e32 v117, 0, v7
	v_fma_f32 v29, -|v7|, v5, v117
	v_lshlrev_b32_e32 v34, 16, v13
	v_pk_mul_f32 v[6:7], v[32:33], v[32:33]
	v_and_b32_e32 v35, 0xffff0000, v13
	v_pk_fma_f32 v[4:5], v[30:31], s[42:43], v[18:19] op_sel_hi:[1,0,0]
	v_pk_mul_f32 v[6:7], v[6:7], s[64:65] op_sel_hi:[1,0]
	v_pk_fma_f32 v[4:5], v[30:31], v[4:5], s[48:49] op_sel_hi:[1,1,0]
	v_exp_f32_e32 v6, v6
	v_exp_f32_e32 v7, v7
	v_pk_fma_f32 v[4:5], v[30:31], v[4:5], s[50:51] op_sel_hi:[1,1,0]
	v_pk_fma_f32 v[4:5], v[30:31], v[4:5], s[56:57] op_sel_hi:[1,1,0]
	v_fma_f32 v12, |v34|, s40, 1.0
	v_fma_f32 v13, |v35|, s40, 1.0
	v_pk_mul_f32 v[4:5], v[30:31], v[4:5]
	v_rcp_f32_e32 v36, v12
	v_rcp_f32_e32 v37, v13
	v_pk_mul_f32 v[4:5], v[6:7], v[4:5]
	v_max_f32_e32 v80, 0, v32
	v_fma_f32 v31, -|v32|, v4, v80
	v_max_f32_e32 v81, 0, v33
	v_fma_f32 v13, -|v33|, v5, v81
	v_lshlrev_b32_e32 v38, 16, v14
	v_and_b32_e32 v39, 0xffff0000, v14
	v_lshlrev_b32_e32 v40, 16, v15
	v_pk_fma_f32 v[4:5], v[36:37], s[42:43], v[18:19] op_sel_hi:[1,0,0]
	v_pk_mul_f32 v[6:7], v[34:35], v[34:35]
	v_pk_fma_f32 v[4:5], v[36:37], v[4:5], s[48:49] op_sel_hi:[1,1,0]
	v_pk_mul_f32 v[6:7], v[6:7], s[64:65] op_sel_hi:[1,0]
	v_pk_fma_f32 v[4:5], v[36:37], v[4:5], s[50:51] op_sel_hi:[1,1,0]
	v_exp_f32_e32 v6, v6
	v_exp_f32_e32 v7, v7
	v_pk_fma_f32 v[4:5], v[36:37], v[4:5], s[56:57] op_sel_hi:[1,1,0]
	v_pk_mul_f32 v[4:5], v[36:37], v[4:5]
	v_fma_f32 v36, |v38|, s40, 1.0
	v_fma_f32 v37, |v39|, s40, 1.0
	v_pk_mul_f32 v[4:5], v[6:7], v[4:5]
	v_rcp_f32_e32 v36, v36
	v_rcp_f32_e32 v37, v37
	v_max_f32_e32 v82, 0, v34
	v_fma_f32 v33, -|v34|, v4, v82
	v_max_f32_e32 v83, 0, v35
	v_fma_f32 v35, -|v35|, v5, v83
	v_and_b32_e32 v41, 0xffff0000, v15
	v_pk_mul_f32 v[6:7], v[38:39], v[38:39]
	v_pk_fma_f32 v[4:5], v[36:37], s[42:43], v[18:19] op_sel_hi:[1,0,0]
	v_pk_mul_f32 v[6:7], v[6:7], s[64:65] op_sel_hi:[1,0]
	v_pk_fma_f32 v[4:5], v[36:37], v[4:5], s[48:49] op_sel_hi:[1,1,0]
	v_exp_f32_e32 v6, v6
	v_exp_f32_e32 v7, v7
	v_pk_fma_f32 v[4:5], v[36:37], v[4:5], s[50:51] op_sel_hi:[1,1,0]
	v_fma_f32 v14, |v40|, s40, 1.0
	v_fma_f32 v15, |v41|, s40, 1.0
	v_pk_fma_f32 v[4:5], v[36:37], v[4:5], s[56:57] op_sel_hi:[1,1,0]
	v_rcp_f32_e32 v42, v14
	v_pk_mul_f32 v[4:5], v[36:37], v[4:5]
	v_rcp_f32_e32 v43, v15
	v_pk_mul_f32 v[4:5], v[6:7], v[4:5]
	v_max_f32_e32 v84, 0, v38
	v_mul_f32_e32 v26, v27, v27
	v_fma_f32 v37, -|v38|, v4, v84
	v_max_f32_e32 v85, 0, v39
	s_waitcnt vmcnt(0)
	v_lshlrev_b32_e32 v44, 16, v8
	v_and_b32_e32 v45, 0xffff0000, v8
	v_fma_f32 v15, -|v39|, v5, v85
	v_pk_fma_f32 v[4:5], v[42:43], s[42:43], v[18:19] op_sel_hi:[1,0,0]
	v_pk_mul_f32 v[6:7], v[40:41], v[40:41]
	v_pk_fma_f32 v[4:5], v[42:43], v[4:5], s[48:49] op_sel_hi:[1,1,0]
	v_pk_mul_f32 v[6:7], v[6:7], s[64:65] op_sel_hi:[1,0]
	v_pk_fma_f32 v[4:5], v[42:43], v[4:5], s[50:51] op_sel_hi:[1,1,0]
	v_exp_f32_e32 v6, v6
	v_exp_f32_e32 v7, v7
	v_pk_fma_f32 v[4:5], v[42:43], v[4:5], s[56:57] op_sel_hi:[1,1,0]
	v_pk_mul_f32 v[4:5], v[42:43], v[4:5]
	v_fma_f32 v42, |v44|, s40, 1.0
	v_fma_f32 v43, |v45|, s40, 1.0
	v_pk_mul_f32 v[4:5], v[6:7], v[4:5]
	v_rcp_f32_e32 v42, v42
	v_rcp_f32_e32 v43, v43
	v_max_f32_e32 v86, 0, v40
	v_fma_f32 v39, -|v40|, v4, v86
	v_max_f32_e32 v90, 0, v41
	v_fma_f32 v41, -|v41|, v5, v90
	v_lshlrev_b32_e32 v50, 16, v9
	v_and_b32_e32 v51, 0xffff0000, v9
	v_pk_mul_f32 v[6:7], v[44:45], v[44:45]
	v_pk_fma_f32 v[4:5], v[42:43], s[42:43], v[18:19] op_sel_hi:[1,0,0]
	v_pk_mul_f32 v[6:7], v[6:7], s[64:65] op_sel_hi:[1,0]
	v_pk_fma_f32 v[4:5], v[42:43], v[4:5], s[48:49] op_sel_hi:[1,1,0]
	v_exp_f32_e32 v6, v6
	v_exp_f32_e32 v7, v7
	v_pk_fma_f32 v[4:5], v[42:43], v[4:5], s[50:51] op_sel_hi:[1,1,0]
	v_pk_fma_f32 v[4:5], v[42:43], v[4:5], s[56:57] op_sel_hi:[1,1,0]
	v_fma_f32 v8, |v50|, s40, 1.0
	v_fma_f32 v9, |v51|, s40, 1.0
	v_pk_mul_f32 v[4:5], v[42:43], v[4:5]
	v_rcp_f32_e32 v52, v8
	v_pk_mul_f32 v[42:43], v[6:7], v[4:5]
	global_load_dwordx4 v[4:7], v[20:21], off offset:1536
	v_rcp_f32_e32 v53, v9
	v_max_f32_e32 v92, 0, v45
	v_fma_f32 v9, -|v45|, v43, v92
	v_max_f32_e32 v91, 0, v44
	v_fma_f32 v43, -|v44|, v42, v91
	v_lshlrev_b32_e32 v58, 16, v11
	v_and_b32_e32 v59, 0xffff0000, v11
	v_pk_fma_f32 v[44:45], v[52:53], s[42:43], v[18:19] op_sel_hi:[1,0,0]
	v_and_b32_e32 v11, 0x7fffffff, v59
	v_pk_fma_f32 v[44:45], v[52:53], v[44:45], s[48:49] op_sel_hi:[1,1,0]
	v_pk_mul_f32 v[46:47], v[50:51], v[50:51]
	v_pk_fma_f32 v[44:45], v[52:53], v[44:45], s[50:51] op_sel_hi:[1,1,0]
	v_pk_mul_f32 v[46:47], v[46:47], s[64:65] op_sel_hi:[1,0]
	v_pk_fma_f32 v[44:45], v[52:53], v[44:45], s[56:57] op_sel_hi:[1,1,0]
	v_exp_f32_e32 v46, v46
	v_exp_f32_e32 v47, v47
	v_pk_mul_f32 v[44:45], v[52:53], v[44:45]
	v_lshlrev_b32_e32 v52, 16, v10
	v_and_b32_e32 v53, 0xffff0000, v10
	v_fma_f32 v56, |v52|, s40, 1.0
	v_fma_f32 v57, |v53|, s40, 1.0
	v_pk_mul_f32 v[44:45], v[46:47], v[44:45]
	v_rcp_f32_e32 v56, v56
	v_rcp_f32_e32 v57, v57
	v_max_f32_e32 v94, 0, v51
	v_fma_f32 v47, -|v51|, v45, v94
	v_max_f32_e32 v93, 0, v50
	v_fma_f32 v45, -|v50|, v44, v93
	v_and_b32_e32 v10, 0x7fffffff, v58
	v_pk_fma_f32 v[10:11], v[10:11], s[40:41], 1.0 op_sel_hi:[1,0,0]
	v_pk_mul_f32 v[50:51], v[52:53], v[52:53]
	v_rcp_f32_e32 v60, v10
	v_pk_fma_f32 v[48:49], v[56:57], s[42:43], v[18:19] op_sel_hi:[1,0,0]
	v_pk_mul_f32 v[50:51], v[50:51], s[64:65] op_sel_hi:[1,0]
	v_pk_fma_f32 v[48:49], v[56:57], v[48:49], s[48:49] op_sel_hi:[1,1,0]
	v_exp_f32_e32 v50, v50
	v_exp_f32_e32 v51, v51
	v_pk_fma_f32 v[48:49], v[56:57], v[48:49], s[50:51] op_sel_hi:[1,1,0]
	v_rcp_f32_e32 v61, v11
	v_pk_fma_f32 v[48:49], v[56:57], v[48:49], s[56:57] op_sel_hi:[1,1,0]
	v_pk_mul_f32 v[48:49], v[56:57], v[48:49]
	v_mul_f32_e32 v28, v29, v29
	v_pk_mul_f32 v[48:49], v[50:51], v[48:49]
	v_mul_f32_e32 v30, v31, v31
	v_max_f32_e32 v96, 0, v53
	v_fma_f32 v11, -|v53|, v49, v96
	v_max_f32_e32 v95, 0, v52
	v_fma_f32 v49, -|v52|, v48, v95
	v_mul_f32_e32 v12, v13, v13
	v_pk_mul_f32 v[52:53], v[58:59], v[58:59]
	v_pk_add_f32 v[24:25], v[26:27], v[28:29]
	v_pk_fma_f32 v[50:51], v[60:61], s[42:43], v[18:19] op_sel_hi:[1,0,0]
	v_pk_mul_f32 v[52:53], v[52:53], s[64:65] op_sel_hi:[1,0]
	v_pk_fma_f32 v[50:51], v[60:61], v[50:51], s[48:49] op_sel_hi:[1,1,0]
	v_exp_f32_e32 v52, v52
	v_exp_f32_e32 v53, v53
	v_pk_fma_f32 v[50:51], v[60:61], v[50:51], s[50:51] op_sel_hi:[1,1,0]
	v_pk_fma_f32 v[50:51], v[60:61], v[50:51], s[56:57] op_sel_hi:[1,1,0]
	v_mul_f32_e32 v32, v33, v33
	v_pk_mul_f32 v[50:51], v[60:61], v[50:51]
	v_mul_f32_e32 v34, v35, v35
	v_pk_mul_f32 v[50:51], v[52:53], v[50:51]
	v_pk_add_f32 v[22:23], v[24:25], v[22:23]
	v_max_f32_e32 v97, 0, v58
	v_fma_f32 v63, -|v58|, v50, v97
	v_max_f32_e32 v98, 0, v59
	v_fma_f32 v57, -|v59|, v51, v98
	global_load_dwordx4 v[50:53], v[20:21], off offset:1792
	v_pk_add_f32 v[12:13], v[30:31], v[12:13]
	v_mul_f32_e32 v36, v37, v37
	s_waitcnt vmcnt(1)
	v_lshlrev_b32_e32 v20, 16, v4
	v_and_b32_e32 v21, 0xffff0000, v4
	v_fma_f32 v64, |v20|, s40, 1.0
	v_fma_f32 v65, |v21|, s40, 1.0
	v_pk_mul_f32 v[60:61], v[20:21], v[20:21]
	v_rcp_f32_e32 v64, v64
	v_rcp_f32_e32 v65, v65
	v_mul_f32_e32 v14, v15, v15
	v_pk_mul_f32 v[60:61], v[60:61], s[64:65] op_sel_hi:[1,0]
	v_pk_add_f32 v[12:13], v[12:13], v[22:23]
	v_pk_fma_f32 v[58:59], v[64:65], s[42:43], v[18:19] op_sel_hi:[1,0,0]
	v_pk_add_f32 v[22:23], v[32:33], v[34:35]
	v_mul_f32_e32 v38, v39, v39
	v_mul_f32_e32 v40, v41, v41
	v_pk_fma_f32 v[58:59], v[64:65], v[58:59], s[48:49] op_sel_hi:[1,1,0]
	v_exp_f32_e32 v60, v60
	v_exp_f32_e32 v61, v61
	v_pk_add_f32 v[12:13], v[22:23], v[12:13]
	v_pk_add_f32 v[14:15], v[36:37], v[14:15]
	v_mul_f32_e32 v42, v43, v43
	v_mul_f32_e32 v8, v9, v9
	v_pk_fma_f32 v[58:59], v[64:65], v[58:59], s[50:51] op_sel_hi:[1,1,0]
	v_pk_add_f32 v[12:13], v[14:15], v[12:13]
	v_pk_add_f32 v[14:15], v[38:39], v[40:41]
	v_mul_f32_e32 v44, v45, v45
	v_mul_f32_e32 v46, v47, v47
	v_pk_fma_f32 v[58:59], v[64:65], v[58:59], s[56:57] op_sel_hi:[1,1,0]
	v_pk_add_f32 v[12:13], v[14:15], v[12:13]
	v_pk_add_f32 v[8:9], v[42:43], v[8:9]
	v_pk_mul_f32 v[58:59], v[64:65], v[58:59]
	v_pk_add_f32 v[8:9], v[8:9], v[12:13]
	v_pk_add_f32 v[12:13], v[44:45], v[46:47]
	v_lshlrev_b32_e32 v4, 16, v5
	v_and_b32_e32 v5, 0xffff0000, v5
	v_pk_mul_f32 v[58:59], v[60:61], v[58:59]
	v_pk_add_f32 v[8:9], v[12:13], v[8:9]
	v_max_f32_e32 v99, 0, v20
	v_fma_f32 v65, -|v20|, v58, v99
	v_max_f32_e32 v100, 0, v21
	v_fma_f32 v21, -|v21|, v59, v100
	v_fma_f32 v12, |v4|, s40, 1.0
	v_fma_f32 v13, |v5|, s40, 1.0
	v_mul_f32_e32 v48, v49, v49
	v_mul_f32_e32 v10, v11, v11
	v_rcp_f32_e32 v12, v12
	v_rcp_f32_e32 v13, v13
	v_mul_f32_e32 v62, v63, v63
	v_mul_f32_e32 v56, v57, v57
	v_pk_add_f32 v[10:11], v[48:49], v[10:11]
	v_mul_f32_e32 v64, v65, v65
	v_mul_f32_e32 v20, v21, v21
	v_pk_add_f32 v[8:9], v[10:11], v[8:9]
	v_pk_add_f32 v[10:11], v[62:63], v[56:57]
	v_pk_mul_f32 v[14:15], v[4:5], v[4:5]
	v_pk_add_f32 v[8:9], v[10:11], v[8:9]
	v_pk_add_f32 v[10:11], v[64:65], v[20:21]
	v_pk_mul_f32 v[14:15], v[14:15], s[64:65] op_sel_hi:[1,0]
	v_pk_add_f32 v[8:9], v[10:11], v[8:9]
	v_pk_fma_f32 v[10:11], v[12:13], s[42:43], v[18:19] op_sel_hi:[1,0,0]
	v_exp_f32_e32 v14, v14
	v_pk_fma_f32 v[10:11], v[12:13], v[10:11], s[48:49] op_sel_hi:[1,1,0]
	v_exp_f32_e32 v15, v15
	v_pk_fma_f32 v[10:11], v[12:13], v[10:11], s[50:51] op_sel_hi:[1,1,0]
	v_pk_fma_f32 v[10:11], v[12:13], v[10:11], s[56:57] op_sel_hi:[1,1,0]
	s_waitcnt vmcnt(0)
	v_lshlrev_b32_e32 v24, 16, v50
	v_pk_mul_f32 v[10:11], v[12:13], v[10:11]
	v_and_b32_e32 v25, 0xffff0000, v50
	v_pk_mul_f32 v[10:11], v[14:15], v[10:11]
	v_and_b32_e32 v27, 0x7fffffff, v25
	v_max_f32_e32 v104, 0, v4
	v_fma_f32 v15, -|v4|, v10, v104
	v_max_f32_e32 v105, 0, v5
	v_fma_f32 v5, -|v5|, v11, v105
	v_and_b32_e32 v26, 0x7fffffff, v24
	v_lshlrev_b32_e32 v10, 16, v6
	v_and_b32_e32 v12, 0x7fffffff, v10
	v_and_b32_e32 v11, 0xffff0000, v6
	v_and_b32_e32 v13, 0x7fffffff, v11
	v_pk_fma_f32 v[12:13], v[12:13], s[40:41], 1.0 op_sel_hi:[1,0,0]
	v_mul_f32_e32 v14, v15, v15
	v_rcp_f32_e32 v12, v12
	v_rcp_f32_e32 v13, v13
	v_mul_f32_e32 v4, v5, v5
	v_pk_mul_f32 v[20:21], v[10:11], v[10:11]
	v_pk_add_f32 v[4:5], v[14:15], v[4:5]
	v_pk_fma_f32 v[14:15], v[12:13], s[42:43], v[18:19] op_sel_hi:[1,0,0]
	v_pk_mul_f32 v[20:21], v[20:21], s[64:65] op_sel_hi:[1,0]
	v_pk_fma_f32 v[14:15], v[12:13], v[14:15], s[48:49] op_sel_hi:[1,1,0]
	v_exp_f32_e32 v20, v20
	v_exp_f32_e32 v21, v21
	v_pk_fma_f32 v[14:15], v[12:13], v[14:15], s[50:51] op_sel_hi:[1,1,0]
	v_lshlrev_b32_e32 v6, 16, v7
	v_and_b32_e32 v7, 0xffff0000, v7
	v_pk_fma_f32 v[14:15], v[12:13], v[14:15], s[56:57] op_sel_hi:[1,1,0]
	v_pk_mul_f32 v[12:13], v[12:13], v[14:15]
	v_fma_f32 v22, |v6|, s40, 1.0
	v_fma_f32 v23, |v7|, s40, 1.0
	v_pk_mul_f32 v[12:13], v[20:21], v[12:13]
	v_rcp_f32_e32 v22, v22
	v_rcp_f32_e32 v23, v23
	v_max_f32_e32 v106, 0, v10
	v_fma_f32 v21, -|v10|, v12, v106
	v_max_f32_e32 v107, 0, v11
	v_fma_f32 v11, -|v11|, v13, v107
	v_pk_fma_f32 v[26:27], v[26:27], s[40:41], 1.0 op_sel_hi:[1,0,0]
	v_lshlrev_b32_e32 v28, 16, v51
	v_rcp_f32_e32 v26, v26
	v_rcp_f32_e32 v27, v27
	v_pk_mul_f32 v[14:15], v[6:7], v[6:7]
	v_pk_fma_f32 v[12:13], v[22:23], s[42:43], v[18:19] op_sel_hi:[1,0,0]
	v_pk_mul_f32 v[14:15], v[14:15], s[64:65] op_sel_hi:[1,0]
	v_pk_fma_f32 v[12:13], v[22:23], v[12:13], s[48:49] op_sel_hi:[1,1,0]
	v_exp_f32_e32 v14, v14
	v_exp_f32_e32 v15, v15
	v_pk_fma_f32 v[12:13], v[22:23], v[12:13], s[50:51] op_sel_hi:[1,1,0]
	v_pk_fma_f32 v[12:13], v[22:23], v[12:13], s[56:57] op_sel_hi:[1,1,0]
	v_and_b32_e32 v29, 0xffff0000, v51
	v_pk_mul_f32 v[12:13], v[22:23], v[12:13]
	v_pk_mul_f32 v[12:13], v[14:15], v[12:13]
	v_max_f32_e32 v108, 0, v6
	v_fma_f32 v23, -|v6|, v12, v108
	v_max_f32_e32 v109, 0, v7
	v_fma_f32 v7, -|v7|, v13, v109
	v_fma_f32 v30, |v28|, s40, 1.0
	v_fma_f32 v31, |v29|, s40, 1.0
	v_rcp_f32_e32 v30, v30
	v_rcp_f32_e32 v31, v31
	v_pk_mul_f32 v[14:15], v[24:25], v[24:25]
	v_pk_fma_f32 v[12:13], v[26:27], s[42:43], v[18:19] op_sel_hi:[1,0,0]
	v_pk_mul_f32 v[14:15], v[14:15], s[64:65] op_sel_hi:[1,0]
	v_pk_fma_f32 v[12:13], v[26:27], v[12:13], s[48:49] op_sel_hi:[1,1,0]
	v_exp_f32_e32 v14, v14
	v_exp_f32_e32 v15, v15
	v_pk_fma_f32 v[12:13], v[26:27], v[12:13], s[50:51] op_sel_hi:[1,1,0]
	v_pk_fma_f32 v[12:13], v[26:27], v[12:13], s[56:57] op_sel_hi:[1,1,0]
	v_lshlrev_b32_e32 v32, 16, v52
	v_pk_mul_f32 v[12:13], v[26:27], v[12:13]
	v_and_b32_e32 v33, 0xffff0000, v52
	v_pk_mul_f32 v[12:13], v[14:15], v[12:13]
	v_max_f32_e32 v110, 0, v24
	v_fma_f32 v27, -|v24|, v12, v110
	v_max_f32_e32 v111, 0, v25
	v_fma_f32 v13, -|v25|, v13, v111
	v_pk_mul_f32 v[24:25], v[28:29], v[28:29]
	v_fma_f32 v34, |v32|, s40, 1.0
	v_fma_f32 v35, |v33|, s40, 1.0
	v_pk_fma_f32 v[14:15], v[30:31], s[42:43], v[18:19] op_sel_hi:[1,0,0]
	v_pk_mul_f32 v[24:25], v[24:25], s[64:65] op_sel_hi:[1,0]
	v_pk_fma_f32 v[14:15], v[30:31], v[14:15], s[48:49] op_sel_hi:[1,1,0]
	v_exp_f32_e32 v24, v24
	v_exp_f32_e32 v25, v25
	v_pk_fma_f32 v[14:15], v[30:31], v[14:15], s[50:51] op_sel_hi:[1,1,0]
	v_rcp_f32_e32 v34, v34
	v_pk_fma_f32 v[14:15], v[30:31], v[14:15], s[56:57] op_sel_hi:[1,1,0]
	v_rcp_f32_e32 v35, v35
	v_pk_mul_f32 v[14:15], v[30:31], v[14:15]
	v_pk_mul_f32 v[14:15], v[24:25], v[14:15]
	v_lshlrev_b32_e32 v36, 16, v53
	v_max_f32_e32 v112, 0, v28
	v_fma_f32 v31, -|v28|, v14, v112
	v_max_f32_e32 v113, 0, v29
	v_fma_f32 v15, -|v29|, v15, v113
	v_and_b32_e32 v37, 0xffff0000, v53
	v_pk_mul_f32 v[28:29], v[32:33], v[32:33]
	v_pk_fma_f32 v[24:25], v[34:35], s[42:43], v[18:19] op_sel_hi:[1,0,0]
	v_pk_mul_f32 v[28:29], v[28:29], s[64:65] op_sel_hi:[1,0]
	v_pk_fma_f32 v[24:25], v[34:35], v[24:25], s[48:49] op_sel_hi:[1,1,0]
	v_exp_f32_e32 v28, v28
	v_exp_f32_e32 v29, v29
	v_pk_fma_f32 v[24:25], v[34:35], v[24:25], s[50:51] op_sel_hi:[1,1,0]
	v_pk_fma_f32 v[24:25], v[34:35], v[24:25], s[56:57] op_sel_hi:[1,1,0]
	v_fma_f32 v38, |v36|, s40, 1.0
	v_fma_f32 v39, |v37|, s40, 1.0
	v_pk_mul_f32 v[24:25], v[34:35], v[24:25]
	v_rcp_f32_e32 v38, v38
	v_pk_mul_f32 v[24:25], v[28:29], v[24:25]
	v_rcp_f32_e32 v39, v39
	v_max_f32_e32 v114, 0, v32
	v_fma_f32 v35, -|v32|, v24, v114
	v_max_f32_e32 v115, 0, v33
	v_fma_f32 v25, -|v33|, v25, v115
	v_pk_fma_f32 v[18:19], v[38:39], s[42:43], v[18:19] op_sel_hi:[1,0,0]
	v_mul_f32_e32 v20, v21, v21
	v_pk_fma_f32 v[18:19], v[38:39], v[18:19], s[48:49] op_sel_hi:[1,1,0]
	v_mul_f32_e32 v10, v11, v11
	v_pk_mul_f32 v[28:29], v[36:37], v[36:37]
	v_pk_fma_f32 v[18:19], v[38:39], v[18:19], s[50:51] op_sel_hi:[1,1,0]
	v_pk_mul_f32 v[28:29], v[28:29], s[64:65] op_sel_hi:[1,0]
	v_pk_fma_f32 v[18:19], v[38:39], v[18:19], s[56:57] op_sel_hi:[1,1,0]
	v_exp_f32_e32 v28, v28
	v_exp_f32_e32 v29, v29
	v_pk_mul_f32 v[18:19], v[38:39], v[18:19]
	v_mul_f32_e32 v22, v23, v23
	v_mul_f32_e32 v6, v7, v7
	v_pk_mul_f32 v[18:19], v[28:29], v[18:19]
	v_pk_add_f32 v[4:5], v[4:5], v[8:9]
	v_pk_add_f32 v[8:9], v[20:21], v[10:11]
	v_mul_f32_e32 v26, v27, v27
	v_mul_f32_e32 v12, v13, v13
	v_max_f32_e32 v116, 0, v36
	v_fma_f32 v33, -|v36|, v18, v116
	v_max_f32_e32 v117, 0, v37
	v_fma_f32 v19, -|v37|, v19, v117
	v_pk_add_f32 v[4:5], v[8:9], v[4:5]
	v_pk_add_f32 v[6:7], v[22:23], v[6:7]
	v_mul_f32_e32 v30, v31, v31
	v_mul_f32_e32 v14, v15, v15
	v_pk_add_f32 v[4:5], v[6:7], v[4:5]
	v_pk_add_f32 v[6:7], v[26:27], v[12:13]
	v_mul_f32_e32 v34, v35, v35
	v_mul_f32_e32 v24, v25, v25
	v_pk_add_f32 v[4:5], v[6:7], v[4:5]
	v_pk_add_f32 v[6:7], v[30:31], v[14:15]
	v_mul_f32_e32 v32, v33, v33
	v_mul_f32_e32 v18, v19, v19
	v_cmp_lt_i32_e32 vcc, v167, v161
	v_pk_add_f32 v[4:5], v[6:7], v[4:5]
	v_pk_add_f32 v[6:7], v[34:35], v[24:25]
	v_cndmask_b32_e32 v17, v160, v167, vcc
	v_pk_add_f32 v[4:5], v[6:7], v[4:5]
	v_pk_add_f32 v[6:7], v[32:33], v[18:19]
	v_lshlrev_b32_e32 v56, 2, v17
	v_pk_add_f32 v[4:5], v[6:7], v[4:5]
	ds_bpermute_b32 v7, v56, v5
	ds_bpermute_b32 v6, v56, v4
	v_cmp_lt_i32_e32 vcc, v166, v161
	s_waitcnt lgkmcnt(0)
	v_pk_add_f32 v[4:5], v[4:5], v[6:7]
	v_cndmask_b32_e32 v8, v160, v166, vcc
	v_lshlrev_b32_e32 v57, 2, v8
	ds_bpermute_b32 v7, v57, v5
	ds_bpermute_b32 v6, v57, v4
	v_cmp_lt_i32_e32 vcc, v165, v161
	s_waitcnt lgkmcnt(0)
	v_pk_add_f32 v[4:5], v[4:5], v[6:7]
	v_cndmask_b32_e32 v8, v160, v165, vcc
	v_lshlrev_b32_e32 v58, 2, v8
	ds_bpermute_b32 v7, v58, v5
	ds_bpermute_b32 v6, v58, v4
	v_cmp_lt_i32_e32 vcc, v164, v161
	s_waitcnt lgkmcnt(0)
	v_pk_add_f32 v[4:5], v[4:5], v[6:7]
	v_cndmask_b32_e32 v6, v160, v164, vcc
	v_lshlrev_b32_e32 v59, 2, v6
	ds_bpermute_b32 v7, v59, v5
	ds_bpermute_b32 v6, v59, v4
	v_cmp_eq_u32_e32 vcc, 0, v54
	s_and_saveexec_b64 s[8:9], vcc
	s_cbranch_execz .LBB0_445
	s_waitcnt lgkmcnt(0)
	v_pk_add_f32 v[4:5], v[4:5], v[6:7]
	s_nop 0
	v_pk_mul_f32 v[4:5], v[4:5], s[66:67] op_sel_hi:[1,0]
	s_nop 0
	v_fma_f32 v4, -v5, v5, v4
	v_max_f32_e32 v4, 0, v4
	v_add_f32_e32 v4, 0x358637bd, v4
	v_mul_f32_e32 v6, 0x4b800000, v4
	v_cmp_gt_f32_e64 s[0:1], s36, v4
	s_nop 1
	v_cndmask_b32_e64 v4, v4, v6, s[0:1]
	v_rsq_f32_e32 v4, v4
	v_lshl_add_u32 v6, v16, 2, 0
	v_add_u32_e32 v7, 0x11000, v6
	ds_write_b32 v7, v5
	v_mul_f32_e32 v5, 0x45800000, v4
	v_cndmask_b32_e64 v4, v4, v5, s[0:1]
	v_add_u32_e32 v5, 0x11200, v6
	ds_write_b32 v5, v4
.LBB0_445:
	s_or_b64 exec, exec, s[8:9]
	v_or_b32_e32 v20, 4, v16
	v_ashrrev_i32_e32 v21, 31, v20
	v_lshl_add_u64 v[4:5], s[6:7], 0, v[20:21]
	s_waitcnt lgkmcnt(0)
	v_lshlrev_b32_e32 v6, 3, v54
	v_lshlrev_b64 v[4:5], 11, v[4:5]
	v_lshl_add_u64 v[4:5], s[4:5], 0, v[4:5]
	v_lshlrev_b32_e32 v18, 1, v6
	v_mov_b32_e32 v19, v2
	v_lshl_add_u64 v[24:25], v[4:5], 0, v[18:19]
	global_load_dwordx4 v[8:11], v[24:25], off
	global_load_dwordx4 v[4:7], v[24:25], off offset:256
	v_mov_b64_e32 v[22:23], s[44:45]
	v_mov_b32_e32 v13, v2
	s_waitcnt vmcnt(1)
	v_lshlrev_b32_e32 v28, 16, v10
	v_and_b32_e32 v29, 0xffff0000, v10
	v_and_b32_e32 v15, 0xffff0000, v8
	v_and_b32_e32 v27, 0xffff0000, v9
	v_lshlrev_b32_e32 v26, 16, v9
	v_lshlrev_b32_e32 v14, 16, v8
	v_lshlrev_b32_e32 v8, 16, v11
	v_and_b32_e32 v9, 0xffff0000, v11
	v_fma_f32 v10, |v28|, s40, 1.0
	v_fma_f32 v11, |v29|, s40, 1.0
	v_fma_f32 v32, |v14|, s40, 1.0
	v_fma_f32 v33, |v15|, s40, 1.0
	v_rcp_f32_e32 v10, v10
	v_rcp_f32_e32 v11, v11
	v_fma_f32 v36, |v26|, s40, 1.0
	v_fma_f32 v37, |v27|, s40, 1.0
	v_rcp_f32_e32 v32, v32
	v_rcp_f32_e32 v33, v33
	v_rcp_f32_e32 v36, v36
	v_rcp_f32_e32 v37, v37
	v_pk_mul_f32 v[30:31], v[28:29], v[28:29]
	v_pk_mul_f32 v[34:35], v[14:15], v[14:15]
	v_pk_mul_f32 v[30:31], v[30:31], s[64:65] op_sel_hi:[1,0]
	v_pk_fma_f32 v[44:45], v[10:11], s[42:43], v[22:23] op_sel_hi:[1,0,0]
	v_pk_mul_f32 v[38:39], v[26:27], v[26:27]
	v_pk_mul_f32 v[34:35], v[34:35], s[64:65] op_sel_hi:[1,0]
	v_exp_f32_e32 v30, v30
	v_exp_f32_e32 v31, v31
	v_pk_fma_f32 v[46:47], v[32:33], s[42:43], v[22:23] op_sel_hi:[1,0,0]
	v_pk_fma_f32 v[44:45], v[10:11], v[44:45], s[48:49] op_sel_hi:[1,1,0]
	v_pk_mul_f32 v[38:39], v[38:39], s[64:65] op_sel_hi:[1,0]
	v_exp_f32_e32 v34, v34
	v_exp_f32_e32 v35, v35
	v_pk_fma_f32 v[48:49], v[36:37], s[42:43], v[22:23] op_sel_hi:[1,0,0]
	v_pk_fma_f32 v[46:47], v[32:33], v[46:47], s[48:49] op_sel_hi:[1,1,0]
	v_pk_fma_f32 v[44:45], v[10:11], v[44:45], s[50:51] op_sel_hi:[1,1,0]
	v_exp_f32_e32 v38, v38
	v_exp_f32_e32 v39, v39
	v_pk_fma_f32 v[48:49], v[36:37], v[48:49], s[48:49] op_sel_hi:[1,1,0]
	v_pk_fma_f32 v[46:47], v[32:33], v[46:47], s[50:51] op_sel_hi:[1,1,0]
	v_pk_fma_f32 v[44:45], v[10:11], v[44:45], s[56:57] op_sel_hi:[1,1,0]
	v_pk_fma_f32 v[48:49], v[36:37], v[48:49], s[50:51] op_sel_hi:[1,1,0]
	v_pk_fma_f32 v[46:47], v[32:33], v[46:47], s[56:57] op_sel_hi:[1,1,0]
	v_pk_mul_f32 v[10:11], v[10:11], v[44:45]
	v_pk_fma_f32 v[48:49], v[36:37], v[48:49], s[56:57] op_sel_hi:[1,1,0]
	v_pk_mul_f32 v[32:33], v[32:33], v[46:47]
	v_pk_mul_f32 v[10:11], v[30:31], v[10:11]
	v_pk_mul_f32 v[36:37], v[36:37], v[48:49]
	v_pk_mul_f32 v[30:31], v[34:35], v[32:33]
	v_max_f32_e32 v80, 0, v28
	v_fma_f32 v45, -|v28|, v10, v80
	v_max_f32_e32 v81, 0, v29
	v_fma_f32 v11, -|v29|, v11, v81
	v_pk_mul_f32 v[32:33], v[38:39], v[36:37]
	v_max_f32_e32 v82, 0, v26
	v_fma_f32 v29, -|v26|, v32, v82
	v_max_f32_e32 v83, 0, v27
	v_fma_f32 v27, -|v27|, v33, v83
	v_max_f32_e32 v84, 0, v14
	v_fma_f32 v28, -|v14|, v30, v84
	v_max_f32_e32 v85, 0, v15
	v_fma_f32 v15, -|v15|, v31, v85
	v_fma_f32 v40, |v8|, s40, 1.0
	v_fma_f32 v41, |v9|, s40, 1.0
	v_mul_f32_e32 v30, v28, v28
	v_mov_b32_e32 v14, v29
	v_mov_b32_e32 v31, v29
	v_mul_f32_e32 v26, v15, v15
	v_rcp_f32_e32 v40, v40
	v_rcp_f32_e32 v41, v41
	v_mul_f32_e32 v12, v27, v27
	v_pk_add_f32 v[26:27], v[30:31], v[26:27]
	v_pk_mul_f32 v[30:31], v[28:29], v[14:15] op_sel:[1,0] op_sel_hi:[0,1]
	v_pk_add_f32 v[14:15], v[28:29], v[14:15] op_sel:[1,0] op_sel_hi:[0,1]
	v_mov_b32_e32 v31, v15
	v_mul_f32_e32 v44, v45, v45
	v_mul_f32_e32 v10, v11, v11
	v_pk_add_f32 v[12:13], v[30:31], v[12:13]
	v_pk_mul_f32 v[42:43], v[8:9], v[8:9]
	v_pk_add_f32 v[10:11], v[44:45], v[10:11]
	v_pk_add_f32 v[12:13], v[26:27], v[12:13]
	v_pk_fma_f32 v[50:51], v[40:41], s[42:43], v[22:23] op_sel_hi:[1,0,0]
	v_pk_add_f32 v[26:27], v[10:11], v[12:13]
	v_pk_mul_f32 v[10:11], v[42:43], s[64:65] op_sel_hi:[1,0]
	v_pk_fma_f32 v[50:51], v[40:41], v[50:51], s[48:49] op_sel_hi:[1,1,0]
	v_exp_f32_e32 v10, v10
	v_exp_f32_e32 v11, v11
	v_pk_fma_f32 v[12:13], v[40:41], v[50:51], s[50:51] op_sel_hi:[1,1,0]
	v_pk_fma_f32 v[12:13], v[40:41], v[12:13], s[56:57] op_sel_hi:[1,1,0]
	s_nop 0
	v_pk_mul_f32 v[12:13], v[40:41], v[12:13]
	s_waitcnt vmcnt(0)
	v_lshlrev_b32_e32 v40, 16, v6
	v_pk_mul_f32 v[10:11], v[10:11], v[12:13]
	v_and_b32_e32 v41, 0xffff0000, v6
	v_max_f32_e32 v86, 0, v8
	v_fma_f32 v15, -|v8|, v10, v86
	v_max_f32_e32 v90, 0, v9
	v_fma_f32 v9, -|v9|, v11, v90
	v_and_b32_e32 v37, 0x7fffffff, v41
	v_lshlrev_b32_e32 v12, 16, v4
	v_and_b32_e32 v10, 0x7fffffff, v12
	v_and_b32_e32 v13, 0xffff0000, v4
	v_and_b32_e32 v11, 0x7fffffff, v13
	v_pk_fma_f32 v[10:11], v[10:11], s[40:41], 1.0 op_sel_hi:[1,0,0]
	v_mul_f32_e32 v14, v15, v15
	v_rcp_f32_e32 v10, v10
	v_rcp_f32_e32 v11, v11
	v_mul_f32_e32 v8, v9, v9
	v_pk_add_f32 v[28:29], v[14:15], v[8:9]
	v_pk_mul_f32 v[14:15], v[12:13], v[12:13]
	v_pk_fma_f32 v[8:9], v[10:11], s[42:43], v[22:23] op_sel_hi:[1,0,0]
	v_pk_mul_f32 v[14:15], v[14:15], s[64:65] op_sel_hi:[1,0]
	v_pk_fma_f32 v[8:9], v[10:11], v[8:9], s[48:49] op_sel_hi:[1,1,0]
	v_exp_f32_e32 v14, v14
	v_exp_f32_e32 v15, v15
	v_pk_fma_f32 v[8:9], v[10:11], v[8:9], s[50:51] op_sel_hi:[1,1,0]
	v_lshlrev_b32_e32 v4, 16, v5
	v_pk_fma_f32 v[8:9], v[10:11], v[8:9], s[56:57] op_sel_hi:[1,1,0]
	v_and_b32_e32 v5, 0xffff0000, v5
	v_pk_mul_f32 v[8:9], v[10:11], v[8:9]
	v_pk_mul_f32 v[14:15], v[14:15], v[8:9]
	global_load_dwordx4 v[8:11], v[24:25], off offset:512
	v_fma_f32 v34, |v4|, s40, 1.0
	v_fma_f32 v35, |v5|, s40, 1.0
	v_rcp_f32_e32 v34, v34
	v_rcp_f32_e32 v35, v35
	v_max_f32_e32 v91, 0, v12
	v_fma_f32 v31, -|v12|, v14, v91
	v_max_f32_e32 v92, 0, v13
	v_fma_f32 v33, -|v13|, v15, v92
	v_and_b32_e32 v36, 0x7fffffff, v40
	v_pk_fma_f32 v[36:37], v[36:37], s[40:41], 1.0 op_sel_hi:[1,0,0]
	v_pk_fma_f32 v[12:13], v[34:35], s[42:43], v[22:23] op_sel_hi:[1,0,0]
	v_rcp_f32_e32 v38, v36
	v_pk_mul_f32 v[14:15], v[4:5], v[4:5]
	v_pk_fma_f32 v[12:13], v[34:35], v[12:13], s[48:49] op_sel_hi:[1,1,0]
	v_pk_mul_f32 v[14:15], v[14:15], s[64:65] op_sel_hi:[1,0]
	v_pk_fma_f32 v[12:13], v[34:35], v[12:13], s[50:51] op_sel_hi:[1,1,0]
	v_exp_f32_e32 v14, v14
	v_exp_f32_e32 v15, v15
	v_pk_fma_f32 v[12:13], v[34:35], v[12:13], s[56:57] op_sel_hi:[1,1,0]
	v_rcp_f32_e32 v39, v37
	v_pk_mul_f32 v[12:13], v[34:35], v[12:13]
	v_pk_mul_f32 v[12:13], v[14:15], v[12:13]
	v_mul_f32_e32 v30, v31, v31
	v_max_f32_e32 v93, 0, v4
	v_fma_f32 v35, -|v4|, v12, v93
	v_max_f32_e32 v94, 0, v5
	v_fma_f32 v37, -|v5|, v13, v94
	v_mul_f32_e32 v32, v33, v33
	v_pk_fma_f32 v[4:5], v[38:39], s[42:43], v[22:23] op_sel_hi:[1,0,0]
	v_lshlrev_b32_e32 v14, 16, v7
	v_pk_mul_f32 v[12:13], v[40:41], v[40:41]
	v_pk_fma_f32 v[4:5], v[38:39], v[4:5], s[48:49] op_sel_hi:[1,1,0]
	v_pk_mul_f32 v[12:13], v[12:13], s[64:65] op_sel_hi:[1,0]
	v_pk_fma_f32 v[4:5], v[38:39], v[4:5], s[50:51] op_sel_hi:[1,1,0]
	v_exp_f32_e32 v12, v12
	v_exp_f32_e32 v13, v13
	v_and_b32_e32 v15, 0xffff0000, v7
	v_pk_fma_f32 v[4:5], v[38:39], v[4:5], s[56:57] op_sel_hi:[1,1,0]
	v_pk_mul_f32 v[4:5], v[38:39], v[4:5]
	v_fma_f32 v6, |v14|, s40, 1.0
	v_fma_f32 v7, |v15|, s40, 1.0
	v_pk_mul_f32 v[4:5], v[12:13], v[4:5]
	v_rcp_f32_e32 v6, v6
	v_rcp_f32_e32 v7, v7
	v_max_f32_e32 v95, 0, v40
	v_fma_f32 v39, -|v40|, v4, v95
	v_max_f32_e32 v96, 0, v41
	v_fma_f32 v41, -|v41|, v5, v96
	v_mul_f32_e32 v34, v35, v35
	v_mul_f32_e32 v36, v37, v37
	v_pk_add_f32 v[26:27], v[28:29], v[26:27]
	v_pk_add_f32 v[28:29], v[30:31], v[32:33]
	v_pk_mul_f32 v[12:13], v[14:15], v[14:15]
	v_pk_fma_f32 v[4:5], v[6:7], s[42:43], v[22:23] op_sel_hi:[1,0,0]
	v_pk_mul_f32 v[12:13], v[12:13], s[64:65] op_sel_hi:[1,0]
	v_pk_fma_f32 v[4:5], v[6:7], v[4:5], s[48:49] op_sel_hi:[1,1,0]
	v_exp_f32_e32 v12, v12
	v_exp_f32_e32 v13, v13
	v_pk_fma_f32 v[4:5], v[6:7], v[4:5], s[50:51] op_sel_hi:[1,1,0]
	v_cmp_gt_f32_e64 s[0:1], 0, v14
	v_pk_fma_f32 v[4:5], v[6:7], v[4:5], s[56:57] op_sel_hi:[1,1,0]
	v_mul_f32_e32 v38, v39, v39
	v_pk_mul_f32 v[4:5], v[6:7], v[4:5]
	v_mul_f32_e32 v40, v41, v41
	v_pk_mul_f32 v[4:5], v[12:13], v[4:5]
	v_pk_add_f32 v[26:27], v[28:29], v[26:27]
	v_pk_mul_f32 v[12:13], v[14:15], v[4:5]
	v_pk_fma_f32 v[44:45], v[14:15], v[4:5], v[14:15] neg_lo:[1,0,0] neg_hi:[1,0,0]
	global_load_dwordx4 v[4:7], v[24:25], off offset:768
	v_cndmask_b32_e64 v43, v44, v12, s[0:1]
	v_cmp_gt_f32_e64 s[0:1], 0, v15
	v_pk_add_f32 v[28:29], v[34:35], v[36:37]
	s_waitcnt vmcnt(1)
	v_lshlrev_b32_e32 v48, 16, v8
	v_and_b32_e32 v49, 0xffff0000, v8
	v_fma_f32 v46, |v48|, s40, 1.0
	v_fma_f32 v47, |v49|, s40, 1.0
	v_pk_mul_f32 v[14:15], v[48:49], v[48:49]
	v_rcp_f32_e32 v46, v46
	v_rcp_f32_e32 v47, v47
	v_cndmask_b32_e64 v45, v45, v13, s[0:1]
	v_pk_mul_f32 v[14:15], v[14:15], s[64:65] op_sel_hi:[1,0]
	v_lshlrev_b32_e32 v50, 16, v9
	v_pk_fma_f32 v[12:13], v[46:47], s[42:43], v[22:23] op_sel_hi:[1,0,0]
	v_exp_f32_e32 v14, v14
	v_pk_fma_f32 v[12:13], v[46:47], v[12:13], s[48:49] op_sel_hi:[1,1,0]
	v_exp_f32_e32 v15, v15
	v_and_b32_e32 v51, 0xffff0000, v9
	v_pk_fma_f32 v[12:13], v[46:47], v[12:13], s[50:51] op_sel_hi:[1,1,0]
	v_pk_fma_f32 v[12:13], v[46:47], v[12:13], s[56:57] op_sel_hi:[1,1,0]
	v_fma_f32 v8, |v50|, s40, 1.0
	v_fma_f32 v9, |v51|, s40, 1.0
	v_pk_mul_f32 v[12:13], v[46:47], v[12:13]
	v_rcp_f32_e32 v52, v8
	v_rcp_f32_e32 v53, v9
	v_pk_mul_f32 v[12:13], v[14:15], v[12:13]
	v_max_f32_e32 v99, 0, v48
	v_fma_f32 v47, -|v48|, v12, v99
	v_max_f32_e32 v100, 0, v49
	v_fma_f32 v9, -|v49|, v13, v100
	v_lshlrev_b32_e32 v60, 16, v10
	v_and_b32_e32 v61, 0xffff0000, v10
	v_lshlrev_b32_e32 v10, 16, v11
	v_pk_fma_f32 v[12:13], v[52:53], s[42:43], v[22:23] op_sel_hi:[1,0,0]
	v_pk_mul_f32 v[14:15], v[50:51], v[50:51]
	v_pk_fma_f32 v[12:13], v[52:53], v[12:13], s[48:49] op_sel_hi:[1,1,0]
	v_pk_mul_f32 v[14:15], v[14:15], s[64:65] op_sel_hi:[1,0]
	v_pk_fma_f32 v[12:13], v[52:53], v[12:13], s[50:51] op_sel_hi:[1,1,0]
	v_exp_f32_e32 v14, v14
	v_exp_f32_e32 v15, v15
	v_pk_fma_f32 v[12:13], v[52:53], v[12:13], s[56:57] op_sel_hi:[1,1,0]
	v_pk_mul_f32 v[12:13], v[52:53], v[12:13]
	v_fma_f32 v52, |v60|, s40, 1.0
	v_fma_f32 v53, |v61|, s40, 1.0
	v_pk_mul_f32 v[12:13], v[14:15], v[12:13]
	v_rcp_f32_e32 v52, v52
	v_rcp_f32_e32 v53, v53
	v_max_f32_e32 v104, 0, v50
	v_fma_f32 v49, -|v50|, v12, v104
	v_max_f32_e32 v105, 0, v51
	v_fma_f32 v51, -|v51|, v13, v105
	v_and_b32_e32 v11, 0xffff0000, v11
	v_pk_mul_f32 v[14:15], v[60:61], v[60:61]
	v_pk_fma_f32 v[12:13], v[52:53], s[42:43], v[22:23] op_sel_hi:[1,0,0]
	v_pk_mul_f32 v[14:15], v[14:15], s[64:65] op_sel_hi:[1,0]
	v_pk_fma_f32 v[12:13], v[52:53], v[12:13], s[48:49] op_sel_hi:[1,1,0]
	v_exp_f32_e32 v14, v14
	v_exp_f32_e32 v15, v15
	v_pk_fma_f32 v[12:13], v[52:53], v[12:13], s[50:51] op_sel_hi:[1,1,0]
	v_fma_f32 v62, |v10|, s40, 1.0
	v_fma_f32 v63, |v11|, s40, 1.0
	v_pk_fma_f32 v[12:13], v[52:53], v[12:13], s[56:57] op_sel_hi:[1,1,0]
	v_rcp_f32_e32 v62, v62
	v_pk_mul_f32 v[12:13], v[52:53], v[12:13]
	v_rcp_f32_e32 v63, v63
	v_pk_mul_f32 v[12:13], v[14:15], v[12:13]
	v_max_f32_e32 v106, 0, v60
	v_mul_f32_e32 v42, v43, v43
	v_fma_f32 v53, -|v60|, v12, v106
	v_max_f32_e32 v107, 0, v61
	s_waitcnt vmcnt(0)
	v_lshlrev_b32_e32 v64, 16, v4
	v_and_b32_e32 v65, 0xffff0000, v4
	v_fma_f32 v61, -|v61|, v13, v107
	v_pk_mul_f32 v[14:15], v[10:11], v[10:11]
	v_pk_fma_f32 v[12:13], v[62:63], s[42:43], v[22:23] op_sel_hi:[1,0,0]
	v_pk_mul_f32 v[14:15], v[14:15], s[64:65] op_sel_hi:[1,0]
	v_pk_fma_f32 v[12:13], v[62:63], v[12:13], s[48:49] op_sel_hi:[1,1,0]
	v_exp_f32_e32 v14, v14
	v_exp_f32_e32 v15, v15
	v_pk_fma_f32 v[12:13], v[62:63], v[12:13], s[50:51] op_sel_hi:[1,1,0]
	v_pk_fma_f32 v[12:13], v[62:63], v[12:13], s[56:57] op_sel_hi:[1,1,0]
	v_pk_mul_f32 v[12:13], v[62:63], v[12:13]
	v_fma_f32 v66, |v64|, s40, 1.0
	v_fma_f32 v67, |v65|, s40, 1.0
	v_pk_mul_f32 v[12:13], v[14:15], v[12:13]
	v_rcp_f32_e32 v66, v66
	v_rcp_f32_e32 v67, v67
	v_max_f32_e32 v108, 0, v10
	v_fma_f32 v63, -|v10|, v12, v108
	v_max_f32_e32 v109, 0, v11
	v_fma_f32 v11, -|v11|, v13, v109
	v_lshlrev_b32_e32 v4, 16, v5
	v_and_b32_e32 v5, 0xffff0000, v5
	v_pk_mul_f32 v[14:15], v[64:65], v[64:65]
	v_pk_fma_f32 v[12:13], v[66:67], s[42:43], v[22:23] op_sel_hi:[1,0,0]
	v_pk_mul_f32 v[14:15], v[14:15], s[64:65] op_sel_hi:[1,0]
	v_pk_fma_f32 v[12:13], v[66:67], v[12:13], s[48:49] op_sel_hi:[1,1,0]
	v_exp_f32_e32 v14, v14
	v_exp_f32_e32 v15, v15
	v_pk_fma_f32 v[12:13], v[66:67], v[12:13], s[50:51] op_sel_hi:[1,1,0]
	v_fma_f32 v68, |v4|, s40, 1.0
	v_fma_f32 v69, |v5|, s40, 1.0
	v_pk_fma_f32 v[12:13], v[66:67], v[12:13], s[56:57] op_sel_hi:[1,1,0]
	v_rcp_f32_e32 v68, v68
	v_pk_mul_f32 v[12:13], v[66:67], v[12:13]
	v_rcp_f32_e32 v69, v69
	v_pk_mul_f32 v[12:13], v[14:15], v[12:13]
	v_max_f32_e32 v110, 0, v64
	v_fma_f32 v67, -|v64|, v12, v110
	v_max_f32_e32 v111, 0, v65
	v_fma_f32 v65, -|v65|, v13, v111
	v_mul_f32_e32 v44, v45, v45
	v_pk_add_f32 v[26:27], v[28:29], v[26:27]
	v_pk_add_f32 v[28:29], v[38:39], v[40:41]
	v_pk_fma_f32 v[12:13], v[68:69], s[42:43], v[22:23] op_sel_hi:[1,0,0]
	v_pk_mul_f32 v[14:15], v[4:5], v[4:5]
	v_pk_fma_f32 v[12:13], v[68:69], v[12:13], s[48:49] op_sel_hi:[1,1,0]
	v_pk_mul_f32 v[14:15], v[14:15], s[64:65] op_sel_hi:[1,0]
	v_pk_fma_f32 v[12:13], v[68:69], v[12:13], s[50:51] op_sel_hi:[1,1,0]
	v_exp_f32_e32 v70, v14
	v_exp_f32_e32 v71, v15
	v_pk_fma_f32 v[72:73], v[68:69], v[12:13], s[56:57] op_sel_hi:[1,1,0]
	global_load_dwordx4 v[12:15], v[24:25], off offset:1024
	v_mul_f32_e32 v46, v47, v47
	v_mul_f32_e32 v8, v9, v9
	v_pk_add_f32 v[26:27], v[28:29], v[26:27]
	v_pk_add_f32 v[28:29], v[42:43], v[44:45]
	v_mul_f32_e32 v48, v49, v49
	v_mul_f32_e32 v50, v51, v51
	v_pk_add_f32 v[26:27], v[28:29], v[26:27]
	v_pk_add_f32 v[8:9], v[46:47], v[8:9]
	v_mul_f32_e32 v52, v53, v53
	v_mul_f32_e32 v60, v61, v61
	v_pk_mul_f32 v[68:69], v[68:69], v[72:73]
	v_pk_add_f32 v[8:9], v[8:9], v[26:27]
	v_pk_add_f32 v[26:27], v[48:49], v[50:51]
	v_pk_mul_f32 v[68:69], v[70:71], v[68:69]
	v_pk_add_f32 v[8:9], v[26:27], v[8:9]
	v_pk_add_f32 v[26:27], v[52:53], v[60:61]
	v_lshlrev_b32_e32 v28, 16, v6
	v_and_b32_e32 v29, 0xffff0000, v6
	v_max_f32_e32 v112, 0, v4
	v_fma_f32 v73, -|v4|, v68, v112
	v_max_f32_e32 v113, 0, v5
	v_fma_f32 v5, -|v5|, v69, v113
	v_pk_add_f32 v[8:9], v[26:27], v[8:9]
	v_mul_f32_e32 v62, v63, v63
	v_mul_f32_e32 v10, v11, v11
	v_fma_f32 v26, |v28|, s40, 1.0
	v_fma_f32 v27, |v29|, s40, 1.0
	v_mul_f32_e32 v66, v67, v67
	v_mul_f32_e32 v64, v65, v65
	v_pk_add_f32 v[10:11], v[62:63], v[10:11]
	v_rcp_f32_e32 v30, v26
	v_rcp_f32_e32 v31, v27
	v_mul_f32_e32 v72, v73, v73
	v_mul_f32_e32 v4, v5, v5
	v_pk_add_f32 v[8:9], v[10:11], v[8:9]
	v_pk_add_f32 v[10:11], v[66:67], v[64:65]
	v_pk_add_f32 v[4:5], v[72:73], v[4:5]
	v_pk_add_f32 v[8:9], v[10:11], v[8:9]
	v_pk_add_f32 v[26:27], v[4:5], v[8:9]
	v_pk_mul_f32 v[8:9], v[28:29], v[28:29]
	v_pk_fma_f32 v[4:5], v[30:31], s[42:43], v[22:23] op_sel_hi:[1,0,0]
	v_pk_mul_f32 v[8:9], v[8:9], s[64:65] op_sel_hi:[1,0]
	v_pk_fma_f32 v[4:5], v[30:31], v[4:5], s[48:49] op_sel_hi:[1,1,0]
	v_exp_f32_e32 v8, v8
	v_exp_f32_e32 v9, v9
	v_pk_fma_f32 v[4:5], v[30:31], v[4:5], s[50:51] op_sel_hi:[1,1,0]
	v_lshlrev_b32_e32 v6, 16, v7
	v_pk_fma_f32 v[4:5], v[30:31], v[4:5], s[56:57] op_sel_hi:[1,1,0]
	v_and_b32_e32 v7, 0xffff0000, v7
	v_pk_mul_f32 v[4:5], v[30:31], v[4:5]
	s_nop 0
	v_pk_mul_f32 v[4:5], v[8:9], v[4:5]
	s_nop 0
	v_max_f32_e32 v114, 0, v28
	v_fma_f32 v11, -|v28|, v4, v114
	v_max_f32_e32 v115, 0, v29
	v_fma_f32 v5, -|v29|, v5, v115
	s_nop 0
	v_mul_f32_e32 v10, v11, v11
	v_fma_f32 v8, |v6|, s40, 1.0
	v_fma_f32 v9, |v7|, s40, 1.0
	v_mul_f32_e32 v4, v5, v5
	v_rcp_f32_e32 v8, v8
	v_rcp_f32_e32 v9, v9
	v_pk_add_f32 v[28:29], v[10:11], v[4:5]
	v_pk_mul_f32 v[10:11], v[6:7], v[6:7]
	v_pk_fma_f32 v[4:5], v[8:9], s[42:43], v[22:23] op_sel_hi:[1,0,0]
	v_pk_mul_f32 v[10:11], v[10:11], s[64:65] op_sel_hi:[1,0]
	v_pk_fma_f32 v[4:5], v[8:9], v[4:5], s[48:49] op_sel_hi:[1,1,0]
	v_exp_f32_e32 v10, v10
	v_exp_f32_e32 v11, v11
	v_pk_fma_f32 v[4:5], v[8:9], v[4:5], s[50:51] op_sel_hi:[1,1,0]
	v_pk_add_f32 v[26:27], v[28:29], v[26:27]
	v_pk_fma_f32 v[4:5], v[8:9], v[4:5], s[56:57] op_sel_hi:[1,1,0]
	s_nop 0
	v_pk_mul_f32 v[4:5], v[8:9], v[4:5]
	s_nop 0
	v_pk_mul_f32 v[4:5], v[10:11], v[4:5]
	global_load_dwordx4 v[8:11], v[24:25], off offset:1280
	s_waitcnt vmcnt(1)
	v_lshlrev_b32_e32 v36, 16, v12
	v_and_b32_e32 v37, 0xffff0000, v12
	v_fma_f32 v34, |v36|, s40, 1.0
	v_fma_f32 v35, |v37|, s40, 1.0
	v_rcp_f32_e32 v34, v34
	v_rcp_f32_e32 v35, v35
	v_max_f32_e32 v116, 0, v6
	v_fma_f32 v31, -|v6|, v4, v116
	v_max_f32_e32 v117, 0, v7
	v_fma_f32 v33, -|v7|, v5, v117
	v_lshlrev_b32_e32 v38, 16, v13
	v_pk_mul_f32 v[6:7], v[36:37], v[36:37]
	v_and_b32_e32 v39, 0xffff0000, v13
	v_pk_fma_f32 v[4:5], v[34:35], s[42:43], v[22:23] op_sel_hi:[1,0,0]
	v_pk_mul_f32 v[6:7], v[6:7], s[64:65] op_sel_hi:[1,0]
	v_pk_fma_f32 v[4:5], v[34:35], v[4:5], s[48:49] op_sel_hi:[1,1,0]
	v_exp_f32_e32 v6, v6
	v_exp_f32_e32 v7, v7
	v_pk_fma_f32 v[4:5], v[34:35], v[4:5], s[50:51] op_sel_hi:[1,1,0]
	v_pk_fma_f32 v[4:5], v[34:35], v[4:5], s[56:57] op_sel_hi:[1,1,0]
	v_fma_f32 v12, |v38|, s40, 1.0
	v_fma_f32 v13, |v39|, s40, 1.0
	v_pk_mul_f32 v[4:5], v[34:35], v[4:5]
	v_rcp_f32_e32 v40, v12
	v_rcp_f32_e32 v41, v13
	v_pk_mul_f32 v[4:5], v[6:7], v[4:5]
	v_max_f32_e32 v80, 0, v36
	v_fma_f32 v35, -|v36|, v4, v80
	v_max_f32_e32 v81, 0, v37
	v_fma_f32 v13, -|v37|, v5, v81
	v_lshlrev_b32_e32 v42, 16, v14
	v_and_b32_e32 v43, 0xffff0000, v14
	v_lshlrev_b32_e32 v44, 16, v15
	v_pk_fma_f32 v[4:5], v[40:41], s[42:43], v[22:23] op_sel_hi:[1,0,0]
	v_pk_mul_f32 v[6:7], v[38:39], v[38:39]
	v_pk_fma_f32 v[4:5], v[40:41], v[4:5], s[48:49] op_sel_hi:[1,1,0]
	v_pk_mul_f32 v[6:7], v[6:7], s[64:65] op_sel_hi:[1,0]
	v_pk_fma_f32 v[4:5], v[40:41], v[4:5], s[50:51] op_sel_hi:[1,1,0]
	v_exp_f32_e32 v6, v6
	v_exp_f32_e32 v7, v7
	v_pk_fma_f32 v[4:5], v[40:41], v[4:5], s[56:57] op_sel_hi:[1,1,0]
	v_pk_mul_f32 v[4:5], v[40:41], v[4:5]
	v_fma_f32 v40, |v42|, s40, 1.0
	v_fma_f32 v41, |v43|, s40, 1.0
	v_pk_mul_f32 v[4:5], v[6:7], v[4:5]
	v_rcp_f32_e32 v40, v40
	v_rcp_f32_e32 v41, v41
	v_max_f32_e32 v82, 0, v38
	v_fma_f32 v37, -|v38|, v4, v82
	v_max_f32_e32 v83, 0, v39
	v_fma_f32 v39, -|v39|, v5, v83
	v_and_b32_e32 v45, 0xffff0000, v15
	v_pk_mul_f32 v[6:7], v[42:43], v[42:43]
	v_pk_fma_f32 v[4:5], v[40:41], s[42:43], v[22:23] op_sel_hi:[1,0,0]
	v_pk_mul_f32 v[6:7], v[6:7], s[64:65] op_sel_hi:[1,0]
	v_pk_fma_f32 v[4:5], v[40:41], v[4:5], s[48:49] op_sel_hi:[1,1,0]
	v_exp_f32_e32 v6, v6
	v_exp_f32_e32 v7, v7
	v_pk_fma_f32 v[4:5], v[40:41], v[4:5], s[50:51] op_sel_hi:[1,1,0]
	v_fma_f32 v14, |v44|, s40, 1.0
	v_fma_f32 v15, |v45|, s40, 1.0
	v_pk_fma_f32 v[4:5], v[40:41], v[4:5], s[56:57] op_sel_hi:[1,1,0]
	v_rcp_f32_e32 v46, v14
	v_pk_mul_f32 v[4:5], v[40:41], v[4:5]
	v_rcp_f32_e32 v47, v15
	v_pk_mul_f32 v[4:5], v[6:7], v[4:5]
	v_max_f32_e32 v84, 0, v42
	v_mul_f32_e32 v30, v31, v31
	v_fma_f32 v41, -|v42|, v4, v84
	v_max_f32_e32 v85, 0, v43
	s_waitcnt vmcnt(0)
	v_lshlrev_b32_e32 v48, 16, v8
	v_and_b32_e32 v49, 0xffff0000, v8
	v_fma_f32 v15, -|v43|, v5, v85
	v_pk_fma_f32 v[4:5], v[46:47], s[42:43], v[22:23] op_sel_hi:[1,0,0]
	v_pk_mul_f32 v[6:7], v[44:45], v[44:45]
	v_pk_fma_f32 v[4:5], v[46:47], v[4:5], s[48:49] op_sel_hi:[1,1,0]
	v_pk_mul_f32 v[6:7], v[6:7], s[64:65] op_sel_hi:[1,0]
	v_pk_fma_f32 v[4:5], v[46:47], v[4:5], s[50:51] op_sel_hi:[1,1,0]
	v_exp_f32_e32 v6, v6
	v_exp_f32_e32 v7, v7
	v_pk_fma_f32 v[4:5], v[46:47], v[4:5], s[56:57] op_sel_hi:[1,1,0]
	v_pk_mul_f32 v[4:5], v[46:47], v[4:5]
	v_fma_f32 v46, |v48|, s40, 1.0
	v_fma_f32 v47, |v49|, s40, 1.0
	v_pk_mul_f32 v[4:5], v[6:7], v[4:5]
	v_rcp_f32_e32 v46, v46
	v_rcp_f32_e32 v47, v47
	v_max_f32_e32 v86, 0, v44
	v_fma_f32 v43, -|v44|, v4, v86
	v_max_f32_e32 v90, 0, v45
	v_fma_f32 v45, -|v45|, v5, v90
	v_lshlrev_b32_e32 v60, 16, v9
	v_and_b32_e32 v61, 0xffff0000, v9
	v_pk_mul_f32 v[6:7], v[48:49], v[48:49]
	v_pk_fma_f32 v[4:5], v[46:47], s[42:43], v[22:23] op_sel_hi:[1,0,0]
	v_pk_mul_f32 v[6:7], v[6:7], s[64:65] op_sel_hi:[1,0]
	v_pk_fma_f32 v[4:5], v[46:47], v[4:5], s[48:49] op_sel_hi:[1,1,0]
	v_exp_f32_e32 v6, v6
	v_exp_f32_e32 v7, v7
	v_pk_fma_f32 v[4:5], v[46:47], v[4:5], s[50:51] op_sel_hi:[1,1,0]
	v_pk_fma_f32 v[4:5], v[46:47], v[4:5], s[56:57] op_sel_hi:[1,1,0]
	v_fma_f32 v8, |v60|, s40, 1.0
	v_fma_f32 v9, |v61|, s40, 1.0
	v_pk_mul_f32 v[4:5], v[46:47], v[4:5]
	v_rcp_f32_e32 v62, v8
	v_pk_mul_f32 v[46:47], v[6:7], v[4:5]
	global_load_dwordx4 v[4:7], v[24:25], off offset:1536
	v_rcp_f32_e32 v63, v9
	v_max_f32_e32 v92, 0, v49
	v_fma_f32 v9, -|v49|, v47, v92
	v_max_f32_e32 v91, 0, v48
	v_fma_f32 v47, -|v48|, v46, v91
	v_lshlrev_b32_e32 v66, 16, v11
	v_and_b32_e32 v67, 0xffff0000, v11
	v_pk_fma_f32 v[48:49], v[62:63], s[42:43], v[22:23] op_sel_hi:[1,0,0]
	v_and_b32_e32 v11, 0x7fffffff, v67
	v_pk_fma_f32 v[48:49], v[62:63], v[48:49], s[48:49] op_sel_hi:[1,1,0]
	v_pk_mul_f32 v[50:51], v[60:61], v[60:61]
	v_pk_fma_f32 v[48:49], v[62:63], v[48:49], s[50:51] op_sel_hi:[1,1,0]
	v_pk_mul_f32 v[50:51], v[50:51], s[64:65] op_sel_hi:[1,0]
	v_pk_fma_f32 v[48:49], v[62:63], v[48:49], s[56:57] op_sel_hi:[1,1,0]
	v_exp_f32_e32 v50, v50
	v_exp_f32_e32 v51, v51
	v_pk_mul_f32 v[48:49], v[62:63], v[48:49]
	v_lshlrev_b32_e32 v62, 16, v10
	v_and_b32_e32 v63, 0xffff0000, v10
	v_fma_f32 v64, |v62|, s40, 1.0
	v_fma_f32 v65, |v63|, s40, 1.0
	v_pk_mul_f32 v[48:49], v[50:51], v[48:49]
	v_rcp_f32_e32 v64, v64
	v_rcp_f32_e32 v65, v65
	v_max_f32_e32 v94, 0, v61
	v_fma_f32 v51, -|v61|, v49, v94
	v_max_f32_e32 v93, 0, v60
	v_fma_f32 v49, -|v60|, v48, v93
	v_and_b32_e32 v10, 0x7fffffff, v66
	v_pk_fma_f32 v[10:11], v[10:11], s[40:41], 1.0 op_sel_hi:[1,0,0]
	v_pk_mul_f32 v[60:61], v[62:63], v[62:63]
	v_rcp_f32_e32 v68, v10
	v_pk_fma_f32 v[52:53], v[64:65], s[42:43], v[22:23] op_sel_hi:[1,0,0]
	v_pk_mul_f32 v[60:61], v[60:61], s[64:65] op_sel_hi:[1,0]
	v_pk_fma_f32 v[52:53], v[64:65], v[52:53], s[48:49] op_sel_hi:[1,1,0]
	v_exp_f32_e32 v60, v60
	v_exp_f32_e32 v61, v61
	v_pk_fma_f32 v[52:53], v[64:65], v[52:53], s[50:51] op_sel_hi:[1,1,0]
	v_rcp_f32_e32 v69, v11
	v_pk_fma_f32 v[52:53], v[64:65], v[52:53], s[56:57] op_sel_hi:[1,1,0]
	v_pk_mul_f32 v[52:53], v[64:65], v[52:53]
	v_mul_f32_e32 v32, v33, v33
	v_pk_mul_f32 v[52:53], v[60:61], v[52:53]
	v_mul_f32_e32 v34, v35, v35
	v_max_f32_e32 v96, 0, v63
	v_fma_f32 v11, -|v63|, v53, v96
	v_max_f32_e32 v95, 0, v62
	v_fma_f32 v53, -|v62|, v52, v95
	v_mul_f32_e32 v12, v13, v13
	v_pk_mul_f32 v[62:63], v[66:67], v[66:67]
	v_pk_add_f32 v[28:29], v[30:31], v[32:33]
	v_pk_fma_f32 v[60:61], v[68:69], s[42:43], v[22:23] op_sel_hi:[1,0,0]
	v_pk_mul_f32 v[62:63], v[62:63], s[64:65] op_sel_hi:[1,0]
	v_pk_fma_f32 v[60:61], v[68:69], v[60:61], s[48:49] op_sel_hi:[1,1,0]
	v_exp_f32_e32 v62, v62
	v_exp_f32_e32 v63, v63
	v_pk_fma_f32 v[60:61], v[68:69], v[60:61], s[50:51] op_sel_hi:[1,1,0]
	v_pk_fma_f32 v[60:61], v[68:69], v[60:61], s[56:57] op_sel_hi:[1,1,0]
	v_mul_f32_e32 v36, v37, v37
	v_pk_mul_f32 v[60:61], v[68:69], v[60:61]
	v_mul_f32_e32 v38, v39, v39
	v_pk_mul_f32 v[60:61], v[62:63], v[60:61]
	v_pk_add_f32 v[26:27], v[28:29], v[26:27]
	v_max_f32_e32 v97, 0, v66
	v_fma_f32 v71, -|v66|, v60, v97
	v_max_f32_e32 v98, 0, v67
	v_fma_f32 v65, -|v67|, v61, v98
	global_load_dwordx4 v[60:63], v[24:25], off offset:1792
	v_pk_add_f32 v[12:13], v[34:35], v[12:13]
	v_mul_f32_e32 v40, v41, v41
	s_waitcnt vmcnt(1)
	v_lshlrev_b32_e32 v24, 16, v4
	v_and_b32_e32 v25, 0xffff0000, v4
	v_fma_f32 v72, |v24|, s40, 1.0
	v_fma_f32 v73, |v25|, s40, 1.0
	v_pk_mul_f32 v[68:69], v[24:25], v[24:25]
	v_rcp_f32_e32 v72, v72
	v_rcp_f32_e32 v73, v73
	v_mul_f32_e32 v14, v15, v15
	v_pk_mul_f32 v[68:69], v[68:69], s[64:65] op_sel_hi:[1,0]
	v_pk_add_f32 v[12:13], v[12:13], v[26:27]
	v_pk_fma_f32 v[66:67], v[72:73], s[42:43], v[22:23] op_sel_hi:[1,0,0]
	v_pk_add_f32 v[26:27], v[36:37], v[38:39]
	v_mul_f32_e32 v42, v43, v43
	v_mul_f32_e32 v44, v45, v45
	v_pk_fma_f32 v[66:67], v[72:73], v[66:67], s[48:49] op_sel_hi:[1,1,0]
	v_exp_f32_e32 v68, v68
	v_exp_f32_e32 v69, v69
	v_pk_add_f32 v[12:13], v[26:27], v[12:13]
	v_pk_add_f32 v[14:15], v[40:41], v[14:15]
	v_mul_f32_e32 v46, v47, v47
	v_mul_f32_e32 v8, v9, v9
	v_pk_fma_f32 v[66:67], v[72:73], v[66:67], s[50:51] op_sel_hi:[1,1,0]
	v_pk_add_f32 v[12:13], v[14:15], v[12:13]
	v_pk_add_f32 v[14:15], v[42:43], v[44:45]
	v_mul_f32_e32 v48, v49, v49
	v_mul_f32_e32 v50, v51, v51
	v_pk_fma_f32 v[66:67], v[72:73], v[66:67], s[56:57] op_sel_hi:[1,1,0]
	v_pk_add_f32 v[12:13], v[14:15], v[12:13]
	v_pk_add_f32 v[8:9], v[46:47], v[8:9]
	v_pk_mul_f32 v[66:67], v[72:73], v[66:67]
	v_pk_add_f32 v[8:9], v[8:9], v[12:13]
	v_pk_add_f32 v[12:13], v[48:49], v[50:51]
	v_lshlrev_b32_e32 v4, 16, v5
	v_and_b32_e32 v5, 0xffff0000, v5
	v_pk_mul_f32 v[66:67], v[68:69], v[66:67]
	v_pk_add_f32 v[8:9], v[12:13], v[8:9]
	v_max_f32_e32 v99, 0, v24
	v_fma_f32 v73, -|v24|, v66, v99
	v_max_f32_e32 v100, 0, v25
	v_fma_f32 v25, -|v25|, v67, v100
	v_fma_f32 v12, |v4|, s40, 1.0
	v_fma_f32 v13, |v5|, s40, 1.0
	v_mul_f32_e32 v52, v53, v53
	v_mul_f32_e32 v10, v11, v11
	v_rcp_f32_e32 v12, v12
	v_rcp_f32_e32 v13, v13
	v_mul_f32_e32 v70, v71, v71
	v_mul_f32_e32 v64, v65, v65
	v_pk_add_f32 v[10:11], v[52:53], v[10:11]
	v_mul_f32_e32 v72, v73, v73
	v_mul_f32_e32 v24, v25, v25
	v_pk_add_f32 v[8:9], v[10:11], v[8:9]
	v_pk_add_f32 v[10:11], v[70:71], v[64:65]
	v_pk_mul_f32 v[14:15], v[4:5], v[4:5]
	v_pk_add_f32 v[8:9], v[10:11], v[8:9]
	v_pk_add_f32 v[10:11], v[72:73], v[24:25]
	v_pk_mul_f32 v[14:15], v[14:15], s[64:65] op_sel_hi:[1,0]
	v_pk_add_f32 v[8:9], v[10:11], v[8:9]
	v_pk_fma_f32 v[10:11], v[12:13], s[42:43], v[22:23] op_sel_hi:[1,0,0]
	v_exp_f32_e32 v14, v14
	v_pk_fma_f32 v[10:11], v[12:13], v[10:11], s[48:49] op_sel_hi:[1,1,0]
	v_exp_f32_e32 v15, v15
	v_pk_fma_f32 v[10:11], v[12:13], v[10:11], s[50:51] op_sel_hi:[1,1,0]
	v_pk_fma_f32 v[10:11], v[12:13], v[10:11], s[56:57] op_sel_hi:[1,1,0]
	s_waitcnt vmcnt(0)
	v_lshlrev_b32_e32 v28, 16, v60
	v_pk_mul_f32 v[10:11], v[12:13], v[10:11]
	v_and_b32_e32 v29, 0xffff0000, v60
	v_pk_mul_f32 v[10:11], v[14:15], v[10:11]
	v_and_b32_e32 v31, 0x7fffffff, v29
	v_max_f32_e32 v104, 0, v4
	v_fma_f32 v15, -|v4|, v10, v104
	v_max_f32_e32 v105, 0, v5
	v_fma_f32 v5, -|v5|, v11, v105
	v_and_b32_e32 v30, 0x7fffffff, v28
	v_lshlrev_b32_e32 v10, 16, v6
	v_and_b32_e32 v12, 0x7fffffff, v10
	v_and_b32_e32 v11, 0xffff0000, v6
	v_and_b32_e32 v13, 0x7fffffff, v11
	v_pk_fma_f32 v[12:13], v[12:13], s[40:41], 1.0 op_sel_hi:[1,0,0]
	v_mul_f32_e32 v14, v15, v15
	v_rcp_f32_e32 v12, v12
	v_rcp_f32_e32 v13, v13
	v_mul_f32_e32 v4, v5, v5
	v_pk_mul_f32 v[24:25], v[10:11], v[10:11]
	v_pk_add_f32 v[4:5], v[14:15], v[4:5]
	v_pk_fma_f32 v[14:15], v[12:13], s[42:43], v[22:23] op_sel_hi:[1,0,0]
	v_pk_mul_f32 v[24:25], v[24:25], s[64:65] op_sel_hi:[1,0]
	v_pk_fma_f32 v[14:15], v[12:13], v[14:15], s[48:49] op_sel_hi:[1,1,0]
	v_exp_f32_e32 v24, v24
	v_exp_f32_e32 v25, v25
	v_pk_fma_f32 v[14:15], v[12:13], v[14:15], s[50:51] op_sel_hi:[1,1,0]
	v_lshlrev_b32_e32 v6, 16, v7
	v_and_b32_e32 v7, 0xffff0000, v7
	v_pk_fma_f32 v[14:15], v[12:13], v[14:15], s[56:57] op_sel_hi:[1,1,0]
	v_pk_mul_f32 v[12:13], v[12:13], v[14:15]
	v_fma_f32 v26, |v6|, s40, 1.0
	v_fma_f32 v27, |v7|, s40, 1.0
	v_pk_mul_f32 v[12:13], v[24:25], v[12:13]
	v_rcp_f32_e32 v26, v26
	v_rcp_f32_e32 v27, v27
	v_max_f32_e32 v106, 0, v10
	v_fma_f32 v25, -|v10|, v12, v106
	v_max_f32_e32 v107, 0, v11
	v_fma_f32 v11, -|v11|, v13, v107
	v_pk_fma_f32 v[30:31], v[30:31], s[40:41], 1.0 op_sel_hi:[1,0,0]
	v_lshlrev_b32_e32 v32, 16, v61
	v_rcp_f32_e32 v30, v30
	v_rcp_f32_e32 v31, v31
	v_pk_mul_f32 v[14:15], v[6:7], v[6:7]
	v_pk_fma_f32 v[12:13], v[26:27], s[42:43], v[22:23] op_sel_hi:[1,0,0]
	v_pk_mul_f32 v[14:15], v[14:15], s[64:65] op_sel_hi:[1,0]
	v_pk_fma_f32 v[12:13], v[26:27], v[12:13], s[48:49] op_sel_hi:[1,1,0]
	v_exp_f32_e32 v14, v14
	v_exp_f32_e32 v15, v15
	v_pk_fma_f32 v[12:13], v[26:27], v[12:13], s[50:51] op_sel_hi:[1,1,0]
	v_pk_fma_f32 v[12:13], v[26:27], v[12:13], s[56:57] op_sel_hi:[1,1,0]
	v_and_b32_e32 v33, 0xffff0000, v61
	v_pk_mul_f32 v[12:13], v[26:27], v[12:13]
	v_pk_mul_f32 v[12:13], v[14:15], v[12:13]
	v_max_f32_e32 v108, 0, v6
	v_fma_f32 v27, -|v6|, v12, v108
	v_max_f32_e32 v109, 0, v7
	v_fma_f32 v7, -|v7|, v13, v109
	v_fma_f32 v34, |v32|, s40, 1.0
	v_fma_f32 v35, |v33|, s40, 1.0
	v_rcp_f32_e32 v34, v34
	v_rcp_f32_e32 v35, v35
	v_pk_mul_f32 v[14:15], v[28:29], v[28:29]
	v_pk_fma_f32 v[12:13], v[30:31], s[42:43], v[22:23] op_sel_hi:[1,0,0]
	v_pk_mul_f32 v[14:15], v[14:15], s[64:65] op_sel_hi:[1,0]
	v_pk_fma_f32 v[12:13], v[30:31], v[12:13], s[48:49] op_sel_hi:[1,1,0]
	v_exp_f32_e32 v14, v14
	v_exp_f32_e32 v15, v15
	v_pk_fma_f32 v[12:13], v[30:31], v[12:13], s[50:51] op_sel_hi:[1,1,0]
	v_pk_fma_f32 v[12:13], v[30:31], v[12:13], s[56:57] op_sel_hi:[1,1,0]
	v_lshlrev_b32_e32 v36, 16, v62
	v_pk_mul_f32 v[12:13], v[30:31], v[12:13]
	v_and_b32_e32 v37, 0xffff0000, v62
	v_pk_mul_f32 v[12:13], v[14:15], v[12:13]
	v_max_f32_e32 v110, 0, v28
	v_fma_f32 v31, -|v28|, v12, v110
	v_max_f32_e32 v111, 0, v29
	v_fma_f32 v13, -|v29|, v13, v111
	v_pk_mul_f32 v[28:29], v[32:33], v[32:33]
	v_fma_f32 v38, |v36|, s40, 1.0
	v_fma_f32 v39, |v37|, s40, 1.0
	v_pk_fma_f32 v[14:15], v[34:35], s[42:43], v[22:23] op_sel_hi:[1,0,0]
	v_pk_mul_f32 v[28:29], v[28:29], s[64:65] op_sel_hi:[1,0]
	v_pk_fma_f32 v[14:15], v[34:35], v[14:15], s[48:49] op_sel_hi:[1,1,0]
	v_exp_f32_e32 v28, v28
	v_exp_f32_e32 v29, v29
	v_pk_fma_f32 v[14:15], v[34:35], v[14:15], s[50:51] op_sel_hi:[1,1,0]
	v_rcp_f32_e32 v38, v38
	v_pk_fma_f32 v[14:15], v[34:35], v[14:15], s[56:57] op_sel_hi:[1,1,0]
	v_rcp_f32_e32 v39, v39
	v_pk_mul_f32 v[14:15], v[34:35], v[14:15]
	v_pk_mul_f32 v[14:15], v[28:29], v[14:15]
	v_lshlrev_b32_e32 v40, 16, v63
	v_max_f32_e32 v112, 0, v32
	v_fma_f32 v35, -|v32|, v14, v112
	v_max_f32_e32 v113, 0, v33
	v_fma_f32 v15, -|v33|, v15, v113
	v_and_b32_e32 v41, 0xffff0000, v63
	v_pk_mul_f32 v[32:33], v[36:37], v[36:37]
	v_pk_fma_f32 v[28:29], v[38:39], s[42:43], v[22:23] op_sel_hi:[1,0,0]
	v_pk_mul_f32 v[32:33], v[32:33], s[64:65] op_sel_hi:[1,0]
	v_pk_fma_f32 v[28:29], v[38:39], v[28:29], s[48:49] op_sel_hi:[1,1,0]
	v_exp_f32_e32 v32, v32
	v_exp_f32_e32 v33, v33
	v_pk_fma_f32 v[28:29], v[38:39], v[28:29], s[50:51] op_sel_hi:[1,1,0]
	v_pk_fma_f32 v[28:29], v[38:39], v[28:29], s[56:57] op_sel_hi:[1,1,0]
	v_fma_f32 v42, |v40|, s40, 1.0
	v_fma_f32 v43, |v41|, s40, 1.0
	v_pk_mul_f32 v[28:29], v[38:39], v[28:29]
	v_rcp_f32_e32 v42, v42
	v_pk_mul_f32 v[28:29], v[32:33], v[28:29]
	v_rcp_f32_e32 v43, v43
	v_max_f32_e32 v114, 0, v36
	v_fma_f32 v39, -|v36|, v28, v114
	v_max_f32_e32 v115, 0, v37
	v_fma_f32 v29, -|v37|, v29, v115
	v_pk_fma_f32 v[22:23], v[42:43], s[42:43], v[22:23] op_sel_hi:[1,0,0]
	v_mul_f32_e32 v24, v25, v25
	v_pk_fma_f32 v[22:23], v[42:43], v[22:23], s[48:49] op_sel_hi:[1,1,0]
	v_mul_f32_e32 v10, v11, v11
	v_pk_mul_f32 v[32:33], v[40:41], v[40:41]
	v_pk_fma_f32 v[22:23], v[42:43], v[22:23], s[50:51] op_sel_hi:[1,1,0]
	v_pk_mul_f32 v[32:33], v[32:33], s[64:65] op_sel_hi:[1,0]
	v_pk_fma_f32 v[22:23], v[42:43], v[22:23], s[56:57] op_sel_hi:[1,1,0]
	v_exp_f32_e32 v32, v32
	v_exp_f32_e32 v33, v33
	v_pk_mul_f32 v[22:23], v[42:43], v[22:23]
	v_mul_f32_e32 v26, v27, v27
	v_mul_f32_e32 v6, v7, v7
	v_pk_mul_f32 v[22:23], v[32:33], v[22:23]
	v_pk_add_f32 v[4:5], v[4:5], v[8:9]
	v_pk_add_f32 v[8:9], v[24:25], v[10:11]
	v_mul_f32_e32 v30, v31, v31
	v_mul_f32_e32 v12, v13, v13
	v_max_f32_e32 v116, 0, v40
	v_fma_f32 v37, -|v40|, v22, v116
	v_max_f32_e32 v117, 0, v41
	v_fma_f32 v23, -|v41|, v23, v117
	v_pk_add_f32 v[4:5], v[8:9], v[4:5]
	v_pk_add_f32 v[6:7], v[26:27], v[6:7]
	v_mul_f32_e32 v34, v35, v35
	v_mul_f32_e32 v14, v15, v15
	v_pk_add_f32 v[4:5], v[6:7], v[4:5]
	v_pk_add_f32 v[6:7], v[30:31], v[12:13]
	v_mul_f32_e32 v38, v39, v39
	v_mul_f32_e32 v28, v29, v29
	v_pk_add_f32 v[4:5], v[6:7], v[4:5]
	v_pk_add_f32 v[6:7], v[34:35], v[14:15]
	v_mul_f32_e32 v36, v37, v37
	v_mul_f32_e32 v22, v23, v23
	v_pk_add_f32 v[4:5], v[6:7], v[4:5]
	v_pk_add_f32 v[6:7], v[38:39], v[28:29]
	s_nop 0
	v_pk_add_f32 v[4:5], v[6:7], v[4:5]
	v_pk_add_f32 v[6:7], v[36:37], v[22:23]
	s_nop 0
	v_pk_add_f32 v[4:5], v[6:7], v[4:5]
	ds_bpermute_b32 v7, v56, v5
	ds_bpermute_b32 v6, v56, v4
	s_waitcnt lgkmcnt(0)
	v_pk_add_f32 v[4:5], v[4:5], v[6:7]
	ds_bpermute_b32 v7, v57, v5
	ds_bpermute_b32 v6, v57, v4
	s_waitcnt lgkmcnt(0)
	v_pk_add_f32 v[4:5], v[4:5], v[6:7]
	ds_bpermute_b32 v7, v58, v5
	ds_bpermute_b32 v6, v58, v4
	s_waitcnt lgkmcnt(0)
	v_pk_add_f32 v[4:5], v[4:5], v[6:7]
	ds_bpermute_b32 v7, v59, v5
	ds_bpermute_b32 v6, v59, v4
	s_and_saveexec_b64 s[8:9], vcc
	s_cbranch_execz .LBB0_447
	s_waitcnt lgkmcnt(0)
	v_pk_add_f32 v[4:5], v[4:5], v[6:7]
	s_nop 0
	v_pk_mul_f32 v[4:5], v[4:5], s[66:67] op_sel_hi:[1,0]
	s_nop 0
	v_fma_f32 v4, -v5, v5, v4
	v_max_f32_e32 v4, 0, v4
	v_add_f32_e32 v4, 0x358637bd, v4
	v_mul_f32_e32 v6, 0x4b800000, v4
	v_cmp_gt_f32_e64 s[0:1], s36, v4
	s_nop 1
	v_cndmask_b32_e64 v4, v4, v6, s[0:1]
	v_rsq_f32_e32 v4, v4
	v_lshl_add_u32 v6, v20, 2, 0
	v_add_u32_e32 v7, 0x11000, v6
	ds_write_b32 v7, v5
	v_mul_f32_e32 v5, 0x45800000, v4
	v_cndmask_b32_e64 v4, v4, v5, s[0:1]
	v_add_u32_e32 v5, 0x11200, v6
	ds_write_b32 v5, v4
.LBB0_447:
	s_or_b64 exec, exec, s[8:9]
	v_or_b32_e32 v20, 8, v16
	v_ashrrev_i32_e32 v21, 31, v20
	v_lshl_add_u64 v[4:5], s[6:7], 0, v[20:21]
	v_lshlrev_b64 v[4:5], 11, v[4:5]
	v_lshl_add_u64 v[4:5], s[4:5], 0, v[4:5]
	v_lshl_add_u64 v[24:25], v[4:5], 0, v[18:19]
	global_load_dwordx4 v[8:11], v[24:25], off
	s_waitcnt lgkmcnt(0)
	global_load_dwordx4 v[4:7], v[24:25], off offset:256
	v_mov_b64_e32 v[22:23], s[44:45]
	v_mov_b32_e32 v13, v2
	s_waitcnt vmcnt(1)
	v_lshlrev_b32_e32 v28, 16, v10
	v_and_b32_e32 v29, 0xffff0000, v10
	v_and_b32_e32 v15, 0xffff0000, v8
	v_and_b32_e32 v27, 0xffff0000, v9
	v_lshlrev_b32_e32 v26, 16, v9
	v_lshlrev_b32_e32 v14, 16, v8
	v_lshlrev_b32_e32 v8, 16, v11
	v_and_b32_e32 v9, 0xffff0000, v11
	v_fma_f32 v10, |v28|, s40, 1.0
	v_fma_f32 v11, |v29|, s40, 1.0
	v_fma_f32 v32, |v14|, s40, 1.0
	v_fma_f32 v33, |v15|, s40, 1.0
	v_rcp_f32_e32 v10, v10
	v_rcp_f32_e32 v11, v11
	v_fma_f32 v36, |v26|, s40, 1.0
	v_fma_f32 v37, |v27|, s40, 1.0
	v_rcp_f32_e32 v32, v32
	v_rcp_f32_e32 v33, v33
	v_rcp_f32_e32 v36, v36
	v_rcp_f32_e32 v37, v37
	v_pk_mul_f32 v[30:31], v[28:29], v[28:29]
	v_pk_mul_f32 v[34:35], v[14:15], v[14:15]
	v_pk_mul_f32 v[30:31], v[30:31], s[64:65] op_sel_hi:[1,0]
	v_pk_fma_f32 v[44:45], v[10:11], s[42:43], v[22:23] op_sel_hi:[1,0,0]
	v_pk_mul_f32 v[38:39], v[26:27], v[26:27]
	v_pk_mul_f32 v[34:35], v[34:35], s[64:65] op_sel_hi:[1,0]
	v_exp_f32_e32 v30, v30
	v_exp_f32_e32 v31, v31
	v_pk_fma_f32 v[46:47], v[32:33], s[42:43], v[22:23] op_sel_hi:[1,0,0]
	v_pk_fma_f32 v[44:45], v[10:11], v[44:45], s[48:49] op_sel_hi:[1,1,0]
	v_pk_mul_f32 v[38:39], v[38:39], s[64:65] op_sel_hi:[1,0]
	v_exp_f32_e32 v34, v34
	v_exp_f32_e32 v35, v35
	v_pk_fma_f32 v[48:49], v[36:37], s[42:43], v[22:23] op_sel_hi:[1,0,0]
	v_pk_fma_f32 v[46:47], v[32:33], v[46:47], s[48:49] op_sel_hi:[1,1,0]
	v_pk_fma_f32 v[44:45], v[10:11], v[44:45], s[50:51] op_sel_hi:[1,1,0]
	v_exp_f32_e32 v38, v38
	v_exp_f32_e32 v39, v39
	v_pk_fma_f32 v[48:49], v[36:37], v[48:49], s[48:49] op_sel_hi:[1,1,0]
	v_pk_fma_f32 v[46:47], v[32:33], v[46:47], s[50:51] op_sel_hi:[1,1,0]
	v_pk_fma_f32 v[44:45], v[10:11], v[44:45], s[56:57] op_sel_hi:[1,1,0]
	v_pk_fma_f32 v[48:49], v[36:37], v[48:49], s[50:51] op_sel_hi:[1,1,0]
	v_pk_fma_f32 v[46:47], v[32:33], v[46:47], s[56:57] op_sel_hi:[1,1,0]
	v_pk_mul_f32 v[10:11], v[10:11], v[44:45]
	v_pk_fma_f32 v[48:49], v[36:37], v[48:49], s[56:57] op_sel_hi:[1,1,0]
	v_pk_mul_f32 v[32:33], v[32:33], v[46:47]
	v_pk_mul_f32 v[10:11], v[30:31], v[10:11]
	v_pk_mul_f32 v[36:37], v[36:37], v[48:49]
	v_pk_mul_f32 v[30:31], v[34:35], v[32:33]
	v_max_f32_e32 v80, 0, v28
	v_fma_f32 v45, -|v28|, v10, v80
	v_max_f32_e32 v81, 0, v29
	v_fma_f32 v11, -|v29|, v11, v81
	v_pk_mul_f32 v[32:33], v[38:39], v[36:37]
	v_max_f32_e32 v82, 0, v26
	v_fma_f32 v29, -|v26|, v32, v82
	v_max_f32_e32 v83, 0, v27
	v_fma_f32 v27, -|v27|, v33, v83
	v_max_f32_e32 v84, 0, v14
	v_fma_f32 v28, -|v14|, v30, v84
	v_max_f32_e32 v85, 0, v15
	v_fma_f32 v15, -|v15|, v31, v85
	v_fma_f32 v40, |v8|, s40, 1.0
	v_fma_f32 v41, |v9|, s40, 1.0
	v_mov_b32_e32 v14, v29
	v_rcp_f32_e32 v40, v40
	v_rcp_f32_e32 v41, v41
	v_mul_f32_e32 v30, v28, v28
	v_mov_b32_e32 v31, v29
	v_mul_f32_e32 v26, v15, v15
	v_mul_f32_e32 v12, v27, v27
	v_pk_add_f32 v[26:27], v[30:31], v[26:27]
	v_pk_mul_f32 v[30:31], v[28:29], v[14:15] op_sel:[1,0] op_sel_hi:[0,1]
	v_pk_add_f32 v[14:15], v[28:29], v[14:15] op_sel:[1,0] op_sel_hi:[0,1]
	v_pk_mul_f32 v[42:43], v[8:9], v[8:9]
	v_mov_b32_e32 v31, v15
	v_pk_mul_f32 v[42:43], v[42:43], s[64:65] op_sel_hi:[1,0]
	v_pk_fma_f32 v[50:51], v[40:41], s[42:43], v[22:23] op_sel_hi:[1,0,0]
	v_mul_f32_e32 v44, v45, v45
	v_mul_f32_e32 v10, v11, v11
	v_pk_add_f32 v[12:13], v[30:31], v[12:13]
	v_exp_f32_e32 v42, v42
	v_exp_f32_e32 v43, v43
	v_pk_fma_f32 v[50:51], v[40:41], v[50:51], s[48:49] op_sel_hi:[1,1,0]
	v_pk_add_f32 v[10:11], v[44:45], v[10:11]
	v_pk_add_f32 v[12:13], v[26:27], v[12:13]
	v_pk_add_f32 v[26:27], v[10:11], v[12:13]
	v_pk_fma_f32 v[10:11], v[40:41], v[50:51], s[50:51] op_sel_hi:[1,1,0]
	s_nop 0
	v_pk_fma_f32 v[10:11], v[40:41], v[10:11], s[56:57] op_sel_hi:[1,1,0]
	s_nop 0
	v_pk_mul_f32 v[10:11], v[40:41], v[10:11]
	s_waitcnt vmcnt(0)
	v_lshlrev_b32_e32 v40, 16, v6
	v_pk_mul_f32 v[10:11], v[42:43], v[10:11]
	v_and_b32_e32 v41, 0xffff0000, v6
	v_max_f32_e32 v86, 0, v8
	v_fma_f32 v15, -|v8|, v10, v86
	v_max_f32_e32 v90, 0, v9
	v_fma_f32 v9, -|v9|, v11, v90
	v_and_b32_e32 v37, 0x7fffffff, v41
	v_lshlrev_b32_e32 v12, 16, v4
	v_and_b32_e32 v10, 0x7fffffff, v12
	v_and_b32_e32 v13, 0xffff0000, v4
	v_and_b32_e32 v11, 0x7fffffff, v13
	v_pk_fma_f32 v[10:11], v[10:11], s[40:41], 1.0 op_sel_hi:[1,0,0]
	v_mul_f32_e32 v14, v15, v15
	v_rcp_f32_e32 v10, v10
	v_rcp_f32_e32 v11, v11
	v_mul_f32_e32 v8, v9, v9
	v_pk_add_f32 v[28:29], v[14:15], v[8:9]
	v_pk_mul_f32 v[14:15], v[12:13], v[12:13]
	v_pk_fma_f32 v[8:9], v[10:11], s[42:43], v[22:23] op_sel_hi:[1,0,0]
	v_pk_mul_f32 v[14:15], v[14:15], s[64:65] op_sel_hi:[1,0]
	v_pk_fma_f32 v[8:9], v[10:11], v[8:9], s[48:49] op_sel_hi:[1,1,0]
	v_exp_f32_e32 v14, v14
	v_exp_f32_e32 v15, v15
	v_pk_fma_f32 v[8:9], v[10:11], v[8:9], s[50:51] op_sel_hi:[1,1,0]
	v_lshlrev_b32_e32 v4, 16, v5
	v_pk_fma_f32 v[8:9], v[10:11], v[8:9], s[56:57] op_sel_hi:[1,1,0]
	v_and_b32_e32 v5, 0xffff0000, v5
	v_pk_mul_f32 v[8:9], v[10:11], v[8:9]
	v_pk_mul_f32 v[14:15], v[14:15], v[8:9]
	global_load_dwordx4 v[8:11], v[24:25], off offset:512
	v_fma_f32 v34, |v4|, s40, 1.0
	v_fma_f32 v35, |v5|, s40, 1.0
	v_rcp_f32_e32 v34, v34
	v_rcp_f32_e32 v35, v35
	v_max_f32_e32 v91, 0, v12
	v_fma_f32 v31, -|v12|, v14, v91
	v_max_f32_e32 v92, 0, v13
	v_fma_f32 v33, -|v13|, v15, v92
	v_and_b32_e32 v36, 0x7fffffff, v40
	v_pk_fma_f32 v[36:37], v[36:37], s[40:41], 1.0 op_sel_hi:[1,0,0]
	v_pk_fma_f32 v[12:13], v[34:35], s[42:43], v[22:23] op_sel_hi:[1,0,0]
	v_rcp_f32_e32 v38, v36
	v_pk_mul_f32 v[14:15], v[4:5], v[4:5]
	v_pk_fma_f32 v[12:13], v[34:35], v[12:13], s[48:49] op_sel_hi:[1,1,0]
	v_pk_mul_f32 v[14:15], v[14:15], s[64:65] op_sel_hi:[1,0]
	v_pk_fma_f32 v[12:13], v[34:35], v[12:13], s[50:51] op_sel_hi:[1,1,0]
	v_exp_f32_e32 v14, v14
	v_exp_f32_e32 v15, v15
	v_pk_fma_f32 v[12:13], v[34:35], v[12:13], s[56:57] op_sel_hi:[1,1,0]
	v_rcp_f32_e32 v39, v37
	v_pk_mul_f32 v[12:13], v[34:35], v[12:13]
	v_pk_mul_f32 v[12:13], v[14:15], v[12:13]
	v_mul_f32_e32 v30, v31, v31
	v_max_f32_e32 v93, 0, v4
	v_fma_f32 v35, -|v4|, v12, v93
	v_max_f32_e32 v94, 0, v5
	v_fma_f32 v37, -|v5|, v13, v94
	v_mul_f32_e32 v32, v33, v33
	v_pk_fma_f32 v[4:5], v[38:39], s[42:43], v[22:23] op_sel_hi:[1,0,0]
	v_lshlrev_b32_e32 v14, 16, v7
	v_pk_mul_f32 v[12:13], v[40:41], v[40:41]
	v_pk_fma_f32 v[4:5], v[38:39], v[4:5], s[48:49] op_sel_hi:[1,1,0]
	v_pk_mul_f32 v[12:13], v[12:13], s[64:65] op_sel_hi:[1,0]
	v_pk_fma_f32 v[4:5], v[38:39], v[4:5], s[50:51] op_sel_hi:[1,1,0]
	v_exp_f32_e32 v12, v12
	v_exp_f32_e32 v13, v13
	v_and_b32_e32 v15, 0xffff0000, v7
	v_pk_fma_f32 v[4:5], v[38:39], v[4:5], s[56:57] op_sel_hi:[1,1,0]
	v_pk_mul_f32 v[4:5], v[38:39], v[4:5]
	v_fma_f32 v6, |v14|, s40, 1.0
	v_fma_f32 v7, |v15|, s40, 1.0
	v_pk_mul_f32 v[4:5], v[12:13], v[4:5]
	v_rcp_f32_e32 v6, v6
	v_rcp_f32_e32 v7, v7
	v_max_f32_e32 v95, 0, v40
	v_fma_f32 v39, -|v40|, v4, v95
	v_max_f32_e32 v96, 0, v41
	v_fma_f32 v41, -|v41|, v5, v96
	v_mul_f32_e32 v34, v35, v35
	v_mul_f32_e32 v36, v37, v37
	v_pk_add_f32 v[26:27], v[28:29], v[26:27]
	v_pk_add_f32 v[28:29], v[30:31], v[32:33]
	v_pk_mul_f32 v[12:13], v[14:15], v[14:15]
	v_pk_fma_f32 v[4:5], v[6:7], s[42:43], v[22:23] op_sel_hi:[1,0,0]
	v_pk_mul_f32 v[12:13], v[12:13], s[64:65] op_sel_hi:[1,0]
	v_pk_fma_f32 v[4:5], v[6:7], v[4:5], s[48:49] op_sel_hi:[1,1,0]
	v_exp_f32_e32 v12, v12
	v_exp_f32_e32 v13, v13
	v_pk_fma_f32 v[4:5], v[6:7], v[4:5], s[50:51] op_sel_hi:[1,1,0]
	v_cmp_gt_f32_e64 s[0:1], 0, v14
	v_pk_fma_f32 v[4:5], v[6:7], v[4:5], s[56:57] op_sel_hi:[1,1,0]
	v_mul_f32_e32 v38, v39, v39
	v_pk_mul_f32 v[4:5], v[6:7], v[4:5]
	v_mul_f32_e32 v40, v41, v41
	v_pk_mul_f32 v[4:5], v[12:13], v[4:5]
	v_pk_add_f32 v[26:27], v[28:29], v[26:27]
	v_pk_mul_f32 v[12:13], v[14:15], v[4:5]
	v_pk_fma_f32 v[44:45], v[14:15], v[4:5], v[14:15] neg_lo:[1,0,0] neg_hi:[1,0,0]
	global_load_dwordx4 v[4:7], v[24:25], off offset:768
	v_cndmask_b32_e64 v43, v44, v12, s[0:1]
	v_cmp_gt_f32_e64 s[0:1], 0, v15
	v_pk_add_f32 v[28:29], v[34:35], v[36:37]
	s_waitcnt vmcnt(1)
	v_lshlrev_b32_e32 v48, 16, v8
	v_and_b32_e32 v49, 0xffff0000, v8
	v_fma_f32 v46, |v48|, s40, 1.0
	v_fma_f32 v47, |v49|, s40, 1.0
	v_pk_mul_f32 v[14:15], v[48:49], v[48:49]
	v_rcp_f32_e32 v46, v46
	v_rcp_f32_e32 v47, v47
	v_cndmask_b32_e64 v45, v45, v13, s[0:1]
	v_pk_mul_f32 v[14:15], v[14:15], s[64:65] op_sel_hi:[1,0]
	v_lshlrev_b32_e32 v50, 16, v9
	v_pk_fma_f32 v[12:13], v[46:47], s[42:43], v[22:23] op_sel_hi:[1,0,0]
	v_exp_f32_e32 v14, v14
	v_pk_fma_f32 v[12:13], v[46:47], v[12:13], s[48:49] op_sel_hi:[1,1,0]
	v_exp_f32_e32 v15, v15
	v_and_b32_e32 v51, 0xffff0000, v9
	v_pk_fma_f32 v[12:13], v[46:47], v[12:13], s[50:51] op_sel_hi:[1,1,0]
	v_pk_fma_f32 v[12:13], v[46:47], v[12:13], s[56:57] op_sel_hi:[1,1,0]
	v_fma_f32 v8, |v50|, s40, 1.0
	v_fma_f32 v9, |v51|, s40, 1.0
	v_pk_mul_f32 v[12:13], v[46:47], v[12:13]
	v_rcp_f32_e32 v52, v8
	v_rcp_f32_e32 v53, v9
	v_pk_mul_f32 v[12:13], v[14:15], v[12:13]
	v_max_f32_e32 v99, 0, v48
	v_fma_f32 v47, -|v48|, v12, v99
	v_max_f32_e32 v100, 0, v49
	v_fma_f32 v9, -|v49|, v13, v100
	v_lshlrev_b32_e32 v60, 16, v10
	v_and_b32_e32 v61, 0xffff0000, v10
	v_lshlrev_b32_e32 v10, 16, v11
	v_pk_fma_f32 v[12:13], v[52:53], s[42:43], v[22:23] op_sel_hi:[1,0,0]
	v_pk_mul_f32 v[14:15], v[50:51], v[50:51]
	v_pk_fma_f32 v[12:13], v[52:53], v[12:13], s[48:49] op_sel_hi:[1,1,0]
	v_pk_mul_f32 v[14:15], v[14:15], s[64:65] op_sel_hi:[1,0]
	v_pk_fma_f32 v[12:13], v[52:53], v[12:13], s[50:51] op_sel_hi:[1,1,0]
	v_exp_f32_e32 v14, v14
	v_exp_f32_e32 v15, v15
	v_pk_fma_f32 v[12:13], v[52:53], v[12:13], s[56:57] op_sel_hi:[1,1,0]
	v_pk_mul_f32 v[12:13], v[52:53], v[12:13]
	v_fma_f32 v52, |v60|, s40, 1.0
	v_fma_f32 v53, |v61|, s40, 1.0
	v_pk_mul_f32 v[12:13], v[14:15], v[12:13]
	v_rcp_f32_e32 v52, v52
	v_rcp_f32_e32 v53, v53
	v_max_f32_e32 v104, 0, v50
	v_fma_f32 v49, -|v50|, v12, v104
	v_max_f32_e32 v105, 0, v51
	v_fma_f32 v51, -|v51|, v13, v105
	v_and_b32_e32 v11, 0xffff0000, v11
	v_pk_mul_f32 v[14:15], v[60:61], v[60:61]
	v_pk_fma_f32 v[12:13], v[52:53], s[42:43], v[22:23] op_sel_hi:[1,0,0]
	v_pk_mul_f32 v[14:15], v[14:15], s[64:65] op_sel_hi:[1,0]
	v_pk_fma_f32 v[12:13], v[52:53], v[12:13], s[48:49] op_sel_hi:[1,1,0]
	v_exp_f32_e32 v14, v14
	v_exp_f32_e32 v15, v15
	v_pk_fma_f32 v[12:13], v[52:53], v[12:13], s[50:51] op_sel_hi:[1,1,0]
	v_fma_f32 v62, |v10|, s40, 1.0
	v_fma_f32 v63, |v11|, s40, 1.0
	v_pk_fma_f32 v[12:13], v[52:53], v[12:13], s[56:57] op_sel_hi:[1,1,0]
	v_rcp_f32_e32 v62, v62
	v_pk_mul_f32 v[12:13], v[52:53], v[12:13]
	v_rcp_f32_e32 v63, v63
	v_pk_mul_f32 v[12:13], v[14:15], v[12:13]
	v_max_f32_e32 v106, 0, v60
	v_mul_f32_e32 v42, v43, v43
	v_fma_f32 v53, -|v60|, v12, v106
	v_max_f32_e32 v107, 0, v61
	s_waitcnt vmcnt(0)
	v_lshlrev_b32_e32 v64, 16, v4
	v_and_b32_e32 v65, 0xffff0000, v4
	v_fma_f32 v61, -|v61|, v13, v107
	v_pk_mul_f32 v[14:15], v[10:11], v[10:11]
	v_pk_fma_f32 v[12:13], v[62:63], s[42:43], v[22:23] op_sel_hi:[1,0,0]
	v_pk_mul_f32 v[14:15], v[14:15], s[64:65] op_sel_hi:[1,0]
	v_pk_fma_f32 v[12:13], v[62:63], v[12:13], s[48:49] op_sel_hi:[1,1,0]
	v_exp_f32_e32 v14, v14
	v_exp_f32_e32 v15, v15
	v_pk_fma_f32 v[12:13], v[62:63], v[12:13], s[50:51] op_sel_hi:[1,1,0]
	v_pk_fma_f32 v[12:13], v[62:63], v[12:13], s[56:57] op_sel_hi:[1,1,0]
	v_pk_mul_f32 v[12:13], v[62:63], v[12:13]
	v_fma_f32 v66, |v64|, s40, 1.0
	v_fma_f32 v67, |v65|, s40, 1.0
	v_pk_mul_f32 v[12:13], v[14:15], v[12:13]
	v_rcp_f32_e32 v66, v66
	v_rcp_f32_e32 v67, v67
	v_max_f32_e32 v108, 0, v10
	v_fma_f32 v63, -|v10|, v12, v108
	v_max_f32_e32 v109, 0, v11
	v_fma_f32 v11, -|v11|, v13, v109
	v_lshlrev_b32_e32 v4, 16, v5
	v_and_b32_e32 v5, 0xffff0000, v5
	v_pk_mul_f32 v[14:15], v[64:65], v[64:65]
	v_pk_fma_f32 v[12:13], v[66:67], s[42:43], v[22:23] op_sel_hi:[1,0,0]
	v_pk_mul_f32 v[14:15], v[14:15], s[64:65] op_sel_hi:[1,0]
	v_pk_fma_f32 v[12:13], v[66:67], v[12:13], s[48:49] op_sel_hi:[1,1,0]
	v_exp_f32_e32 v14, v14
	v_exp_f32_e32 v15, v15
	v_pk_fma_f32 v[12:13], v[66:67], v[12:13], s[50:51] op_sel_hi:[1,1,0]
	v_fma_f32 v68, |v4|, s40, 1.0
	v_fma_f32 v69, |v5|, s40, 1.0
	v_pk_fma_f32 v[12:13], v[66:67], v[12:13], s[56:57] op_sel_hi:[1,1,0]
	v_rcp_f32_e32 v68, v68
	v_pk_mul_f32 v[12:13], v[66:67], v[12:13]
	v_rcp_f32_e32 v69, v69
	v_pk_mul_f32 v[12:13], v[14:15], v[12:13]
	v_max_f32_e32 v110, 0, v64
	v_fma_f32 v67, -|v64|, v12, v110
	v_max_f32_e32 v111, 0, v65
	v_fma_f32 v65, -|v65|, v13, v111
	v_mul_f32_e32 v44, v45, v45
	v_pk_add_f32 v[26:27], v[28:29], v[26:27]
	v_pk_add_f32 v[28:29], v[38:39], v[40:41]
	v_pk_fma_f32 v[12:13], v[68:69], s[42:43], v[22:23] op_sel_hi:[1,0,0]
	v_pk_mul_f32 v[14:15], v[4:5], v[4:5]
	v_pk_fma_f32 v[12:13], v[68:69], v[12:13], s[48:49] op_sel_hi:[1,1,0]
	v_pk_mul_f32 v[14:15], v[14:15], s[64:65] op_sel_hi:[1,0]
	v_pk_fma_f32 v[12:13], v[68:69], v[12:13], s[50:51] op_sel_hi:[1,1,0]
	v_exp_f32_e32 v70, v14
	v_exp_f32_e32 v71, v15
	v_pk_fma_f32 v[72:73], v[68:69], v[12:13], s[56:57] op_sel_hi:[1,1,0]
	global_load_dwordx4 v[12:15], v[24:25], off offset:1024
	v_mul_f32_e32 v46, v47, v47
	v_mul_f32_e32 v8, v9, v9
	v_pk_add_f32 v[26:27], v[28:29], v[26:27]
	v_pk_add_f32 v[28:29], v[42:43], v[44:45]
	v_mul_f32_e32 v48, v49, v49
	v_mul_f32_e32 v50, v51, v51
	v_pk_add_f32 v[26:27], v[28:29], v[26:27]
	v_pk_add_f32 v[8:9], v[46:47], v[8:9]
	v_mul_f32_e32 v52, v53, v53
	v_mul_f32_e32 v60, v61, v61
	v_pk_mul_f32 v[68:69], v[68:69], v[72:73]
	v_pk_add_f32 v[8:9], v[8:9], v[26:27]
	v_pk_add_f32 v[26:27], v[48:49], v[50:51]
	v_pk_mul_f32 v[68:69], v[70:71], v[68:69]
	v_pk_add_f32 v[8:9], v[26:27], v[8:9]
	v_pk_add_f32 v[26:27], v[52:53], v[60:61]
	v_lshlrev_b32_e32 v28, 16, v6
	v_and_b32_e32 v29, 0xffff0000, v6
	v_max_f32_e32 v112, 0, v4
	v_fma_f32 v73, -|v4|, v68, v112
	v_max_f32_e32 v113, 0, v5
	v_fma_f32 v5, -|v5|, v69, v113
	v_pk_add_f32 v[8:9], v[26:27], v[8:9]
	v_mul_f32_e32 v62, v63, v63
	v_mul_f32_e32 v10, v11, v11
	v_fma_f32 v26, |v28|, s40, 1.0
	v_fma_f32 v27, |v29|, s40, 1.0
	v_mul_f32_e32 v66, v67, v67
	v_mul_f32_e32 v64, v65, v65
	v_pk_add_f32 v[10:11], v[62:63], v[10:11]
	v_rcp_f32_e32 v30, v26
	v_rcp_f32_e32 v31, v27
	v_mul_f32_e32 v72, v73, v73
	v_mul_f32_e32 v4, v5, v5
	v_pk_add_f32 v[8:9], v[10:11], v[8:9]
	v_pk_add_f32 v[10:11], v[66:67], v[64:65]
	v_pk_add_f32 v[4:5], v[72:73], v[4:5]
	v_pk_add_f32 v[8:9], v[10:11], v[8:9]
	v_pk_add_f32 v[26:27], v[4:5], v[8:9]
	v_pk_mul_f32 v[8:9], v[28:29], v[28:29]
	v_pk_fma_f32 v[4:5], v[30:31], s[42:43], v[22:23] op_sel_hi:[1,0,0]
	v_pk_mul_f32 v[8:9], v[8:9], s[64:65] op_sel_hi:[1,0]
	v_pk_fma_f32 v[4:5], v[30:31], v[4:5], s[48:49] op_sel_hi:[1,1,0]
	v_exp_f32_e32 v8, v8
	v_exp_f32_e32 v9, v9
	v_pk_fma_f32 v[4:5], v[30:31], v[4:5], s[50:51] op_sel_hi:[1,1,0]
	v_lshlrev_b32_e32 v6, 16, v7
	v_pk_fma_f32 v[4:5], v[30:31], v[4:5], s[56:57] op_sel_hi:[1,1,0]
	v_and_b32_e32 v7, 0xffff0000, v7
	v_pk_mul_f32 v[4:5], v[30:31], v[4:5]
	s_nop 0
	v_pk_mul_f32 v[4:5], v[8:9], v[4:5]
	s_nop 0
	v_max_f32_e32 v114, 0, v28
	v_fma_f32 v11, -|v28|, v4, v114
	v_max_f32_e32 v115, 0, v29
	v_fma_f32 v5, -|v29|, v5, v115
	s_nop 0
	v_mul_f32_e32 v10, v11, v11
	v_fma_f32 v8, |v6|, s40, 1.0
	v_fma_f32 v9, |v7|, s40, 1.0
	v_mul_f32_e32 v4, v5, v5
	v_rcp_f32_e32 v8, v8
	v_rcp_f32_e32 v9, v9
	v_pk_add_f32 v[28:29], v[10:11], v[4:5]
	v_pk_mul_f32 v[10:11], v[6:7], v[6:7]
	v_pk_fma_f32 v[4:5], v[8:9], s[42:43], v[22:23] op_sel_hi:[1,0,0]
	v_pk_mul_f32 v[10:11], v[10:11], s[64:65] op_sel_hi:[1,0]
	v_pk_fma_f32 v[4:5], v[8:9], v[4:5], s[48:49] op_sel_hi:[1,1,0]
	v_exp_f32_e32 v10, v10
	v_exp_f32_e32 v11, v11
	v_pk_fma_f32 v[4:5], v[8:9], v[4:5], s[50:51] op_sel_hi:[1,1,0]
	v_pk_add_f32 v[26:27], v[28:29], v[26:27]
	v_pk_fma_f32 v[4:5], v[8:9], v[4:5], s[56:57] op_sel_hi:[1,1,0]
	s_nop 0
	v_pk_mul_f32 v[4:5], v[8:9], v[4:5]
	s_nop 0
	v_pk_mul_f32 v[4:5], v[10:11], v[4:5]
	global_load_dwordx4 v[8:11], v[24:25], off offset:1280
	s_waitcnt vmcnt(1)
	v_lshlrev_b32_e32 v36, 16, v12
	v_and_b32_e32 v37, 0xffff0000, v12
	v_fma_f32 v34, |v36|, s40, 1.0
	v_fma_f32 v35, |v37|, s40, 1.0
	v_rcp_f32_e32 v34, v34
	v_rcp_f32_e32 v35, v35
	v_max_f32_e32 v116, 0, v6
	v_fma_f32 v31, -|v6|, v4, v116
	v_max_f32_e32 v117, 0, v7
	v_fma_f32 v33, -|v7|, v5, v117
	v_lshlrev_b32_e32 v38, 16, v13
	v_pk_mul_f32 v[6:7], v[36:37], v[36:37]
	v_and_b32_e32 v39, 0xffff0000, v13
	v_pk_fma_f32 v[4:5], v[34:35], s[42:43], v[22:23] op_sel_hi:[1,0,0]
	v_pk_mul_f32 v[6:7], v[6:7], s[64:65] op_sel_hi:[1,0]
	v_pk_fma_f32 v[4:5], v[34:35], v[4:5], s[48:49] op_sel_hi:[1,1,0]
	v_exp_f32_e32 v6, v6
	v_exp_f32_e32 v7, v7
	v_pk_fma_f32 v[4:5], v[34:35], v[4:5], s[50:51] op_sel_hi:[1,1,0]
	v_pk_fma_f32 v[4:5], v[34:35], v[4:5], s[56:57] op_sel_hi:[1,1,0]
	v_fma_f32 v12, |v38|, s40, 1.0
	v_fma_f32 v13, |v39|, s40, 1.0
	v_pk_mul_f32 v[4:5], v[34:35], v[4:5]
	v_rcp_f32_e32 v40, v12
	v_rcp_f32_e32 v41, v13
	v_pk_mul_f32 v[4:5], v[6:7], v[4:5]
	v_max_f32_e32 v80, 0, v36
	v_fma_f32 v35, -|v36|, v4, v80
	v_max_f32_e32 v81, 0, v37
	v_fma_f32 v13, -|v37|, v5, v81
	v_lshlrev_b32_e32 v42, 16, v14
	v_and_b32_e32 v43, 0xffff0000, v14
	v_lshlrev_b32_e32 v44, 16, v15
	v_pk_fma_f32 v[4:5], v[40:41], s[42:43], v[22:23] op_sel_hi:[1,0,0]
	v_pk_mul_f32 v[6:7], v[38:39], v[38:39]
	v_pk_fma_f32 v[4:5], v[40:41], v[4:5], s[48:49] op_sel_hi:[1,1,0]
	v_pk_mul_f32 v[6:7], v[6:7], s[64:65] op_sel_hi:[1,0]
	v_pk_fma_f32 v[4:5], v[40:41], v[4:5], s[50:51] op_sel_hi:[1,1,0]
	v_exp_f32_e32 v6, v6
	v_exp_f32_e32 v7, v7
	v_pk_fma_f32 v[4:5], v[40:41], v[4:5], s[56:57] op_sel_hi:[1,1,0]
	v_pk_mul_f32 v[4:5], v[40:41], v[4:5]
	v_fma_f32 v40, |v42|, s40, 1.0
	v_fma_f32 v41, |v43|, s40, 1.0
	v_pk_mul_f32 v[4:5], v[6:7], v[4:5]
	v_rcp_f32_e32 v40, v40
	v_rcp_f32_e32 v41, v41
	v_max_f32_e32 v82, 0, v38
	v_fma_f32 v37, -|v38|, v4, v82
	v_max_f32_e32 v83, 0, v39
	v_fma_f32 v39, -|v39|, v5, v83
	v_and_b32_e32 v45, 0xffff0000, v15
	v_pk_mul_f32 v[6:7], v[42:43], v[42:43]
	v_pk_fma_f32 v[4:5], v[40:41], s[42:43], v[22:23] op_sel_hi:[1,0,0]
	v_pk_mul_f32 v[6:7], v[6:7], s[64:65] op_sel_hi:[1,0]
	v_pk_fma_f32 v[4:5], v[40:41], v[4:5], s[48:49] op_sel_hi:[1,1,0]
	v_exp_f32_e32 v6, v6
	v_exp_f32_e32 v7, v7
	v_pk_fma_f32 v[4:5], v[40:41], v[4:5], s[50:51] op_sel_hi:[1,1,0]
	v_fma_f32 v14, |v44|, s40, 1.0
	v_fma_f32 v15, |v45|, s40, 1.0
	v_pk_fma_f32 v[4:5], v[40:41], v[4:5], s[56:57] op_sel_hi:[1,1,0]
	v_rcp_f32_e32 v46, v14
	v_pk_mul_f32 v[4:5], v[40:41], v[4:5]
	v_rcp_f32_e32 v47, v15
	v_pk_mul_f32 v[4:5], v[6:7], v[4:5]
	v_max_f32_e32 v84, 0, v42
	v_mul_f32_e32 v30, v31, v31
	v_fma_f32 v41, -|v42|, v4, v84
	v_max_f32_e32 v85, 0, v43
	s_waitcnt vmcnt(0)
	v_lshlrev_b32_e32 v48, 16, v8
	v_and_b32_e32 v49, 0xffff0000, v8
	v_fma_f32 v15, -|v43|, v5, v85
	v_pk_fma_f32 v[4:5], v[46:47], s[42:43], v[22:23] op_sel_hi:[1,0,0]
	v_pk_mul_f32 v[6:7], v[44:45], v[44:45]
	v_pk_fma_f32 v[4:5], v[46:47], v[4:5], s[48:49] op_sel_hi:[1,1,0]
	v_pk_mul_f32 v[6:7], v[6:7], s[64:65] op_sel_hi:[1,0]
	v_pk_fma_f32 v[4:5], v[46:47], v[4:5], s[50:51] op_sel_hi:[1,1,0]
	v_exp_f32_e32 v6, v6
	v_exp_f32_e32 v7, v7
	v_pk_fma_f32 v[4:5], v[46:47], v[4:5], s[56:57] op_sel_hi:[1,1,0]
	v_pk_mul_f32 v[4:5], v[46:47], v[4:5]
	v_fma_f32 v46, |v48|, s40, 1.0
	v_fma_f32 v47, |v49|, s40, 1.0
	v_pk_mul_f32 v[4:5], v[6:7], v[4:5]
	v_rcp_f32_e32 v46, v46
	v_rcp_f32_e32 v47, v47
	v_max_f32_e32 v86, 0, v44
	v_fma_f32 v43, -|v44|, v4, v86
	v_max_f32_e32 v90, 0, v45
	v_fma_f32 v45, -|v45|, v5, v90
	v_lshlrev_b32_e32 v60, 16, v9
	v_and_b32_e32 v61, 0xffff0000, v9
	v_pk_mul_f32 v[6:7], v[48:49], v[48:49]
	v_pk_fma_f32 v[4:5], v[46:47], s[42:43], v[22:23] op_sel_hi:[1,0,0]
	v_pk_mul_f32 v[6:7], v[6:7], s[64:65] op_sel_hi:[1,0]
	v_pk_fma_f32 v[4:5], v[46:47], v[4:5], s[48:49] op_sel_hi:[1,1,0]
	v_exp_f32_e32 v6, v6
	v_exp_f32_e32 v7, v7
	v_pk_fma_f32 v[4:5], v[46:47], v[4:5], s[50:51] op_sel_hi:[1,1,0]
	v_pk_fma_f32 v[4:5], v[46:47], v[4:5], s[56:57] op_sel_hi:[1,1,0]
	v_fma_f32 v8, |v60|, s40, 1.0
	v_fma_f32 v9, |v61|, s40, 1.0
	v_pk_mul_f32 v[4:5], v[46:47], v[4:5]
	v_rcp_f32_e32 v62, v8
	v_pk_mul_f32 v[46:47], v[6:7], v[4:5]
	global_load_dwordx4 v[4:7], v[24:25], off offset:1536
	v_rcp_f32_e32 v63, v9
	v_max_f32_e32 v92, 0, v49
	v_fma_f32 v9, -|v49|, v47, v92
	v_max_f32_e32 v91, 0, v48
	v_fma_f32 v47, -|v48|, v46, v91
	v_lshlrev_b32_e32 v66, 16, v11
	v_and_b32_e32 v67, 0xffff0000, v11
	v_pk_fma_f32 v[48:49], v[62:63], s[42:43], v[22:23] op_sel_hi:[1,0,0]
	v_and_b32_e32 v11, 0x7fffffff, v67
	v_pk_fma_f32 v[48:49], v[62:63], v[48:49], s[48:49] op_sel_hi:[1,1,0]
	v_pk_mul_f32 v[50:51], v[60:61], v[60:61]
	v_pk_fma_f32 v[48:49], v[62:63], v[48:49], s[50:51] op_sel_hi:[1,1,0]
	v_pk_mul_f32 v[50:51], v[50:51], s[64:65] op_sel_hi:[1,0]
	v_pk_fma_f32 v[48:49], v[62:63], v[48:49], s[56:57] op_sel_hi:[1,1,0]
	v_exp_f32_e32 v50, v50
	v_exp_f32_e32 v51, v51
	v_pk_mul_f32 v[48:49], v[62:63], v[48:49]
	v_lshlrev_b32_e32 v62, 16, v10
	v_and_b32_e32 v63, 0xffff0000, v10
	v_fma_f32 v64, |v62|, s40, 1.0
	v_fma_f32 v65, |v63|, s40, 1.0
	v_pk_mul_f32 v[48:49], v[50:51], v[48:49]
	v_rcp_f32_e32 v64, v64
	v_rcp_f32_e32 v65, v65
	v_max_f32_e32 v94, 0, v61
	v_fma_f32 v51, -|v61|, v49, v94
	v_max_f32_e32 v93, 0, v60
	v_fma_f32 v49, -|v60|, v48, v93
	v_and_b32_e32 v10, 0x7fffffff, v66
	v_pk_fma_f32 v[10:11], v[10:11], s[40:41], 1.0 op_sel_hi:[1,0,0]
	v_pk_mul_f32 v[60:61], v[62:63], v[62:63]
	v_rcp_f32_e32 v68, v10
	v_pk_fma_f32 v[52:53], v[64:65], s[42:43], v[22:23] op_sel_hi:[1,0,0]
	v_pk_mul_f32 v[60:61], v[60:61], s[64:65] op_sel_hi:[1,0]
	v_pk_fma_f32 v[52:53], v[64:65], v[52:53], s[48:49] op_sel_hi:[1,1,0]
	v_exp_f32_e32 v60, v60
	v_exp_f32_e32 v61, v61
	v_pk_fma_f32 v[52:53], v[64:65], v[52:53], s[50:51] op_sel_hi:[1,1,0]
	v_rcp_f32_e32 v69, v11
	v_pk_fma_f32 v[52:53], v[64:65], v[52:53], s[56:57] op_sel_hi:[1,1,0]
	v_pk_mul_f32 v[52:53], v[64:65], v[52:53]
	v_mul_f32_e32 v32, v33, v33
	v_pk_mul_f32 v[52:53], v[60:61], v[52:53]
	v_mul_f32_e32 v34, v35, v35
	v_max_f32_e32 v96, 0, v63
	v_fma_f32 v11, -|v63|, v53, v96
	v_max_f32_e32 v95, 0, v62
	v_fma_f32 v53, -|v62|, v52, v95
	v_mul_f32_e32 v12, v13, v13
	v_pk_mul_f32 v[62:63], v[66:67], v[66:67]
	v_pk_add_f32 v[28:29], v[30:31], v[32:33]
	v_pk_fma_f32 v[60:61], v[68:69], s[42:43], v[22:23] op_sel_hi:[1,0,0]
	v_pk_mul_f32 v[62:63], v[62:63], s[64:65] op_sel_hi:[1,0]
	v_pk_fma_f32 v[60:61], v[68:69], v[60:61], s[48:49] op_sel_hi:[1,1,0]
	v_exp_f32_e32 v62, v62
	v_exp_f32_e32 v63, v63
	v_pk_fma_f32 v[60:61], v[68:69], v[60:61], s[50:51] op_sel_hi:[1,1,0]
	v_pk_fma_f32 v[60:61], v[68:69], v[60:61], s[56:57] op_sel_hi:[1,1,0]
	v_mul_f32_e32 v36, v37, v37
	v_pk_mul_f32 v[60:61], v[68:69], v[60:61]
	v_mul_f32_e32 v38, v39, v39
	v_pk_mul_f32 v[60:61], v[62:63], v[60:61]
	v_pk_add_f32 v[26:27], v[28:29], v[26:27]
	v_max_f32_e32 v97, 0, v66
	v_fma_f32 v71, -|v66|, v60, v97
	v_max_f32_e32 v98, 0, v67
	v_fma_f32 v65, -|v67|, v61, v98
	global_load_dwordx4 v[60:63], v[24:25], off offset:1792
	v_pk_add_f32 v[12:13], v[34:35], v[12:13]
	v_mul_f32_e32 v40, v41, v41
	s_waitcnt vmcnt(1)
	v_lshlrev_b32_e32 v24, 16, v4
	v_and_b32_e32 v25, 0xffff0000, v4
	v_fma_f32 v72, |v24|, s40, 1.0
	v_fma_f32 v73, |v25|, s40, 1.0
	v_pk_mul_f32 v[68:69], v[24:25], v[24:25]
	v_rcp_f32_e32 v72, v72
	v_rcp_f32_e32 v73, v73
	v_mul_f32_e32 v14, v15, v15
	v_pk_mul_f32 v[68:69], v[68:69], s[64:65] op_sel_hi:[1,0]
	v_pk_add_f32 v[12:13], v[12:13], v[26:27]
	v_pk_fma_f32 v[66:67], v[72:73], s[42:43], v[22:23] op_sel_hi:[1,0,0]
	v_pk_add_f32 v[26:27], v[36:37], v[38:39]
	v_mul_f32_e32 v42, v43, v43
	v_mul_f32_e32 v44, v45, v45
	v_pk_fma_f32 v[66:67], v[72:73], v[66:67], s[48:49] op_sel_hi:[1,1,0]
	v_exp_f32_e32 v68, v68
	v_exp_f32_e32 v69, v69
	v_pk_add_f32 v[12:13], v[26:27], v[12:13]
	v_pk_add_f32 v[14:15], v[40:41], v[14:15]
	v_mul_f32_e32 v46, v47, v47
	v_mul_f32_e32 v8, v9, v9
	v_pk_fma_f32 v[66:67], v[72:73], v[66:67], s[50:51] op_sel_hi:[1,1,0]
	v_pk_add_f32 v[12:13], v[14:15], v[12:13]
	v_pk_add_f32 v[14:15], v[42:43], v[44:45]
	v_mul_f32_e32 v48, v49, v49
	v_mul_f32_e32 v50, v51, v51
	v_pk_fma_f32 v[66:67], v[72:73], v[66:67], s[56:57] op_sel_hi:[1,1,0]
	v_pk_add_f32 v[12:13], v[14:15], v[12:13]
	v_pk_add_f32 v[8:9], v[46:47], v[8:9]
	v_pk_mul_f32 v[66:67], v[72:73], v[66:67]
	v_pk_add_f32 v[8:9], v[8:9], v[12:13]
	v_pk_add_f32 v[12:13], v[48:49], v[50:51]
	v_lshlrev_b32_e32 v4, 16, v5
	v_and_b32_e32 v5, 0xffff0000, v5
	v_pk_mul_f32 v[66:67], v[68:69], v[66:67]
	v_pk_add_f32 v[8:9], v[12:13], v[8:9]
	v_max_f32_e32 v99, 0, v24
	v_fma_f32 v73, -|v24|, v66, v99
	v_max_f32_e32 v100, 0, v25
	v_fma_f32 v25, -|v25|, v67, v100
	v_fma_f32 v12, |v4|, s40, 1.0
	v_fma_f32 v13, |v5|, s40, 1.0
	v_mul_f32_e32 v52, v53, v53
	v_mul_f32_e32 v10, v11, v11
	v_rcp_f32_e32 v12, v12
	v_rcp_f32_e32 v13, v13
	v_mul_f32_e32 v70, v71, v71
	v_mul_f32_e32 v64, v65, v65
	v_pk_add_f32 v[10:11], v[52:53], v[10:11]
	v_mul_f32_e32 v72, v73, v73
	v_mul_f32_e32 v24, v25, v25
	v_pk_add_f32 v[8:9], v[10:11], v[8:9]
	v_pk_add_f32 v[10:11], v[70:71], v[64:65]
	v_pk_mul_f32 v[14:15], v[4:5], v[4:5]
	v_pk_add_f32 v[8:9], v[10:11], v[8:9]
	v_pk_add_f32 v[10:11], v[72:73], v[24:25]
	v_pk_mul_f32 v[14:15], v[14:15], s[64:65] op_sel_hi:[1,0]
	v_pk_add_f32 v[8:9], v[10:11], v[8:9]
	v_pk_fma_f32 v[10:11], v[12:13], s[42:43], v[22:23] op_sel_hi:[1,0,0]
	v_exp_f32_e32 v14, v14
	v_pk_fma_f32 v[10:11], v[12:13], v[10:11], s[48:49] op_sel_hi:[1,1,0]
	v_exp_f32_e32 v15, v15
	v_pk_fma_f32 v[10:11], v[12:13], v[10:11], s[50:51] op_sel_hi:[1,1,0]
	v_pk_fma_f32 v[10:11], v[12:13], v[10:11], s[56:57] op_sel_hi:[1,1,0]
	s_waitcnt vmcnt(0)
	v_lshlrev_b32_e32 v28, 16, v60
	v_pk_mul_f32 v[10:11], v[12:13], v[10:11]
	v_and_b32_e32 v29, 0xffff0000, v60
	v_pk_mul_f32 v[10:11], v[14:15], v[10:11]
	v_and_b32_e32 v31, 0x7fffffff, v29
	v_max_f32_e32 v104, 0, v4
	v_fma_f32 v15, -|v4|, v10, v104
	v_max_f32_e32 v105, 0, v5
	v_fma_f32 v5, -|v5|, v11, v105
	v_and_b32_e32 v30, 0x7fffffff, v28
	v_lshlrev_b32_e32 v10, 16, v6
	v_and_b32_e32 v12, 0x7fffffff, v10
	v_and_b32_e32 v11, 0xffff0000, v6
	v_and_b32_e32 v13, 0x7fffffff, v11
	v_pk_fma_f32 v[12:13], v[12:13], s[40:41], 1.0 op_sel_hi:[1,0,0]
	v_mul_f32_e32 v14, v15, v15
	v_rcp_f32_e32 v12, v12
	v_rcp_f32_e32 v13, v13
	v_mul_f32_e32 v4, v5, v5
	v_pk_mul_f32 v[24:25], v[10:11], v[10:11]
	v_pk_add_f32 v[4:5], v[14:15], v[4:5]
	v_pk_fma_f32 v[14:15], v[12:13], s[42:43], v[22:23] op_sel_hi:[1,0,0]
	v_pk_mul_f32 v[24:25], v[24:25], s[64:65] op_sel_hi:[1,0]
	v_pk_fma_f32 v[14:15], v[12:13], v[14:15], s[48:49] op_sel_hi:[1,1,0]
	v_exp_f32_e32 v24, v24
	v_exp_f32_e32 v25, v25
	v_pk_fma_f32 v[14:15], v[12:13], v[14:15], s[50:51] op_sel_hi:[1,1,0]
	v_lshlrev_b32_e32 v6, 16, v7
	v_and_b32_e32 v7, 0xffff0000, v7
	v_pk_fma_f32 v[14:15], v[12:13], v[14:15], s[56:57] op_sel_hi:[1,1,0]
	v_pk_mul_f32 v[12:13], v[12:13], v[14:15]
	v_fma_f32 v26, |v6|, s40, 1.0
	v_fma_f32 v27, |v7|, s40, 1.0
	v_pk_mul_f32 v[12:13], v[24:25], v[12:13]
	v_rcp_f32_e32 v26, v26
	v_rcp_f32_e32 v27, v27
	v_max_f32_e32 v106, 0, v10
	v_fma_f32 v25, -|v10|, v12, v106
	v_max_f32_e32 v107, 0, v11
	v_fma_f32 v11, -|v11|, v13, v107
	v_pk_fma_f32 v[30:31], v[30:31], s[40:41], 1.0 op_sel_hi:[1,0,0]
	v_lshlrev_b32_e32 v32, 16, v61
	v_rcp_f32_e32 v30, v30
	v_rcp_f32_e32 v31, v31
	v_pk_mul_f32 v[14:15], v[6:7], v[6:7]
	v_pk_fma_f32 v[12:13], v[26:27], s[42:43], v[22:23] op_sel_hi:[1,0,0]
	v_pk_mul_f32 v[14:15], v[14:15], s[64:65] op_sel_hi:[1,0]
	v_pk_fma_f32 v[12:13], v[26:27], v[12:13], s[48:49] op_sel_hi:[1,1,0]
	v_exp_f32_e32 v14, v14
	v_exp_f32_e32 v15, v15
	v_pk_fma_f32 v[12:13], v[26:27], v[12:13], s[50:51] op_sel_hi:[1,1,0]
	v_pk_fma_f32 v[12:13], v[26:27], v[12:13], s[56:57] op_sel_hi:[1,1,0]
	v_and_b32_e32 v33, 0xffff0000, v61
	v_pk_mul_f32 v[12:13], v[26:27], v[12:13]
	v_pk_mul_f32 v[12:13], v[14:15], v[12:13]
	v_max_f32_e32 v108, 0, v6
	v_fma_f32 v27, -|v6|, v12, v108
	v_max_f32_e32 v109, 0, v7
	v_fma_f32 v7, -|v7|, v13, v109
	v_fma_f32 v34, |v32|, s40, 1.0
	v_fma_f32 v35, |v33|, s40, 1.0
	v_rcp_f32_e32 v34, v34
	v_rcp_f32_e32 v35, v35
	v_pk_mul_f32 v[14:15], v[28:29], v[28:29]
	v_pk_fma_f32 v[12:13], v[30:31], s[42:43], v[22:23] op_sel_hi:[1,0,0]
	v_pk_mul_f32 v[14:15], v[14:15], s[64:65] op_sel_hi:[1,0]
	v_pk_fma_f32 v[12:13], v[30:31], v[12:13], s[48:49] op_sel_hi:[1,1,0]
	v_exp_f32_e32 v14, v14
	v_exp_f32_e32 v15, v15
	v_pk_fma_f32 v[12:13], v[30:31], v[12:13], s[50:51] op_sel_hi:[1,1,0]
	v_pk_fma_f32 v[12:13], v[30:31], v[12:13], s[56:57] op_sel_hi:[1,1,0]
	v_lshlrev_b32_e32 v36, 16, v62
	v_pk_mul_f32 v[12:13], v[30:31], v[12:13]
	v_and_b32_e32 v37, 0xffff0000, v62
	v_pk_mul_f32 v[12:13], v[14:15], v[12:13]
	v_max_f32_e32 v110, 0, v28
	v_fma_f32 v31, -|v28|, v12, v110
	v_max_f32_e32 v111, 0, v29
	v_fma_f32 v13, -|v29|, v13, v111
	v_pk_mul_f32 v[28:29], v[32:33], v[32:33]
	v_fma_f32 v38, |v36|, s40, 1.0
	v_fma_f32 v39, |v37|, s40, 1.0
	v_pk_fma_f32 v[14:15], v[34:35], s[42:43], v[22:23] op_sel_hi:[1,0,0]
	v_pk_mul_f32 v[28:29], v[28:29], s[64:65] op_sel_hi:[1,0]
	v_pk_fma_f32 v[14:15], v[34:35], v[14:15], s[48:49] op_sel_hi:[1,1,0]
	v_exp_f32_e32 v28, v28
	v_exp_f32_e32 v29, v29
	v_pk_fma_f32 v[14:15], v[34:35], v[14:15], s[50:51] op_sel_hi:[1,1,0]
	v_rcp_f32_e32 v38, v38
	v_pk_fma_f32 v[14:15], v[34:35], v[14:15], s[56:57] op_sel_hi:[1,1,0]
	v_rcp_f32_e32 v39, v39
	v_pk_mul_f32 v[14:15], v[34:35], v[14:15]
	v_pk_mul_f32 v[14:15], v[28:29], v[14:15]
	v_lshlrev_b32_e32 v40, 16, v63
	v_max_f32_e32 v112, 0, v32
	v_fma_f32 v35, -|v32|, v14, v112
	v_max_f32_e32 v113, 0, v33
	v_fma_f32 v15, -|v33|, v15, v113
	v_and_b32_e32 v41, 0xffff0000, v63
	v_pk_mul_f32 v[32:33], v[36:37], v[36:37]
	v_pk_fma_f32 v[28:29], v[38:39], s[42:43], v[22:23] op_sel_hi:[1,0,0]
	v_pk_mul_f32 v[32:33], v[32:33], s[64:65] op_sel_hi:[1,0]
	v_pk_fma_f32 v[28:29], v[38:39], v[28:29], s[48:49] op_sel_hi:[1,1,0]
	v_exp_f32_e32 v32, v32
	v_exp_f32_e32 v33, v33
	v_pk_fma_f32 v[28:29], v[38:39], v[28:29], s[50:51] op_sel_hi:[1,1,0]
	v_pk_fma_f32 v[28:29], v[38:39], v[28:29], s[56:57] op_sel_hi:[1,1,0]
	v_fma_f32 v42, |v40|, s40, 1.0
	v_fma_f32 v43, |v41|, s40, 1.0
	v_pk_mul_f32 v[28:29], v[38:39], v[28:29]
	v_rcp_f32_e32 v42, v42
	v_pk_mul_f32 v[28:29], v[32:33], v[28:29]
	v_rcp_f32_e32 v43, v43
	v_max_f32_e32 v114, 0, v36
	v_fma_f32 v39, -|v36|, v28, v114
	v_max_f32_e32 v115, 0, v37
	v_fma_f32 v29, -|v37|, v29, v115
	v_pk_fma_f32 v[22:23], v[42:43], s[42:43], v[22:23] op_sel_hi:[1,0,0]
	v_mul_f32_e32 v24, v25, v25
	v_pk_fma_f32 v[22:23], v[42:43], v[22:23], s[48:49] op_sel_hi:[1,1,0]
	v_mul_f32_e32 v10, v11, v11
	v_pk_mul_f32 v[32:33], v[40:41], v[40:41]
	v_pk_fma_f32 v[22:23], v[42:43], v[22:23], s[50:51] op_sel_hi:[1,1,0]
	v_pk_mul_f32 v[32:33], v[32:33], s[64:65] op_sel_hi:[1,0]
	v_pk_fma_f32 v[22:23], v[42:43], v[22:23], s[56:57] op_sel_hi:[1,1,0]
	v_exp_f32_e32 v32, v32
	v_exp_f32_e32 v33, v33
	v_pk_mul_f32 v[22:23], v[42:43], v[22:23]
	v_mul_f32_e32 v26, v27, v27
	v_mul_f32_e32 v6, v7, v7
	v_pk_mul_f32 v[22:23], v[32:33], v[22:23]
	v_pk_add_f32 v[4:5], v[4:5], v[8:9]
	v_pk_add_f32 v[8:9], v[24:25], v[10:11]
	v_mul_f32_e32 v30, v31, v31
	v_mul_f32_e32 v12, v13, v13
	v_max_f32_e32 v116, 0, v40
	v_fma_f32 v37, -|v40|, v22, v116
	v_max_f32_e32 v117, 0, v41
	v_fma_f32 v23, -|v41|, v23, v117
	v_pk_add_f32 v[4:5], v[8:9], v[4:5]
	v_pk_add_f32 v[6:7], v[26:27], v[6:7]
	v_mul_f32_e32 v34, v35, v35
	v_mul_f32_e32 v14, v15, v15
	v_pk_add_f32 v[4:5], v[6:7], v[4:5]
	v_pk_add_f32 v[6:7], v[30:31], v[12:13]
	v_mul_f32_e32 v38, v39, v39
	v_mul_f32_e32 v28, v29, v29
	v_pk_add_f32 v[4:5], v[6:7], v[4:5]
	v_pk_add_f32 v[6:7], v[34:35], v[14:15]
	v_mul_f32_e32 v36, v37, v37
	v_mul_f32_e32 v22, v23, v23
	v_pk_add_f32 v[4:5], v[6:7], v[4:5]
	v_pk_add_f32 v[6:7], v[38:39], v[28:29]
	s_nop 0
	v_pk_add_f32 v[4:5], v[6:7], v[4:5]
	v_pk_add_f32 v[6:7], v[36:37], v[22:23]
	s_nop 0
	v_pk_add_f32 v[4:5], v[6:7], v[4:5]
	ds_bpermute_b32 v7, v56, v5
	ds_bpermute_b32 v6, v56, v4
	s_waitcnt lgkmcnt(0)
	v_pk_add_f32 v[4:5], v[4:5], v[6:7]
	ds_bpermute_b32 v7, v57, v5
	ds_bpermute_b32 v6, v57, v4
	s_waitcnt lgkmcnt(0)
	v_pk_add_f32 v[4:5], v[4:5], v[6:7]
	ds_bpermute_b32 v7, v58, v5
	ds_bpermute_b32 v6, v58, v4
	s_waitcnt lgkmcnt(0)
	v_pk_add_f32 v[4:5], v[4:5], v[6:7]
	ds_bpermute_b32 v7, v59, v5
	ds_bpermute_b32 v6, v59, v4
	s_and_saveexec_b64 s[8:9], vcc
	s_cbranch_execz .LBB0_449
	s_waitcnt lgkmcnt(0)
	v_pk_add_f32 v[4:5], v[4:5], v[6:7]
	s_nop 0
	v_pk_mul_f32 v[4:5], v[4:5], s[66:67] op_sel_hi:[1,0]
	s_nop 0
	v_fma_f32 v4, -v5, v5, v4
	v_max_f32_e32 v4, 0, v4
	v_add_f32_e32 v4, 0x358637bd, v4
	v_mul_f32_e32 v6, 0x4b800000, v4
	v_cmp_gt_f32_e64 s[0:1], s36, v4
	s_nop 1
	v_cndmask_b32_e64 v4, v4, v6, s[0:1]
	v_rsq_f32_e32 v4, v4
	v_lshl_add_u32 v6, v20, 2, 0
	v_add_u32_e32 v7, 0x11000, v6
	ds_write_b32 v7, v5
	v_mul_f32_e32 v5, 0x45800000, v4
	v_cndmask_b32_e64 v4, v4, v5, s[0:1]
	v_add_u32_e32 v5, 0x11200, v6
	ds_write_b32 v5, v4
.LBB0_449:
	s_or_b64 exec, exec, s[8:9]
	v_or_b32_e32 v16, 12, v16
	v_ashrrev_i32_e32 v17, 31, v16
	v_lshl_add_u64 v[4:5], s[6:7], 0, v[16:17]
	v_lshlrev_b64 v[4:5], 11, v[4:5]
	v_lshl_add_u64 v[4:5], s[4:5], 0, v[4:5]
	v_mov_b32_e32 v19, v2
	v_lshl_add_u64 v[20:21], v[4:5], 0, v[18:19]
	global_load_dwordx4 v[8:11], v[20:21], off
	s_waitcnt lgkmcnt(0)
	global_load_dwordx4 v[4:7], v[20:21], off offset:256
	v_mov_b64_e32 v[18:19], s[44:45]
	v_mov_b32_e32 v13, v2
	s_waitcnt vmcnt(1)
	v_lshlrev_b32_e32 v24, 16, v10
	v_and_b32_e32 v25, 0xffff0000, v10
	v_and_b32_e32 v15, 0xffff0000, v8
	v_and_b32_e32 v23, 0xffff0000, v9
	v_lshlrev_b32_e32 v22, 16, v9
	v_lshlrev_b32_e32 v14, 16, v8
	v_lshlrev_b32_e32 v8, 16, v11
	v_and_b32_e32 v9, 0xffff0000, v11
	v_fma_f32 v10, |v24|, s40, 1.0
	v_fma_f32 v11, |v25|, s40, 1.0
	v_fma_f32 v28, |v14|, s40, 1.0
	v_fma_f32 v29, |v15|, s40, 1.0
	v_rcp_f32_e32 v10, v10
	v_rcp_f32_e32 v11, v11
	v_fma_f32 v32, |v22|, s40, 1.0
	v_fma_f32 v33, |v23|, s40, 1.0
	v_rcp_f32_e32 v28, v28
	v_rcp_f32_e32 v29, v29
	v_rcp_f32_e32 v32, v32
	v_rcp_f32_e32 v33, v33
	v_pk_mul_f32 v[26:27], v[24:25], v[24:25]
	v_pk_mul_f32 v[30:31], v[14:15], v[14:15]
	v_pk_mul_f32 v[26:27], v[26:27], s[64:65] op_sel_hi:[1,0]
	v_pk_fma_f32 v[40:41], v[10:11], s[42:43], v[18:19] op_sel_hi:[1,0,0]
	v_pk_mul_f32 v[34:35], v[22:23], v[22:23]
	v_pk_mul_f32 v[30:31], v[30:31], s[64:65] op_sel_hi:[1,0]
	v_exp_f32_e32 v26, v26
	v_exp_f32_e32 v27, v27
	v_pk_fma_f32 v[42:43], v[28:29], s[42:43], v[18:19] op_sel_hi:[1,0,0]
	v_pk_fma_f32 v[40:41], v[10:11], v[40:41], s[48:49] op_sel_hi:[1,1,0]
	v_pk_mul_f32 v[34:35], v[34:35], s[64:65] op_sel_hi:[1,0]
	v_exp_f32_e32 v30, v30
	v_exp_f32_e32 v31, v31
	v_pk_fma_f32 v[44:45], v[32:33], s[42:43], v[18:19] op_sel_hi:[1,0,0]
	v_pk_fma_f32 v[42:43], v[28:29], v[42:43], s[48:49] op_sel_hi:[1,1,0]
	v_pk_fma_f32 v[40:41], v[10:11], v[40:41], s[50:51] op_sel_hi:[1,1,0]
	v_exp_f32_e32 v34, v34
	v_exp_f32_e32 v35, v35
	v_pk_fma_f32 v[44:45], v[32:33], v[44:45], s[48:49] op_sel_hi:[1,1,0]
	v_pk_fma_f32 v[42:43], v[28:29], v[42:43], s[50:51] op_sel_hi:[1,1,0]
	v_pk_fma_f32 v[40:41], v[10:11], v[40:41], s[56:57] op_sel_hi:[1,1,0]
	v_pk_fma_f32 v[44:45], v[32:33], v[44:45], s[50:51] op_sel_hi:[1,1,0]
	v_pk_fma_f32 v[42:43], v[28:29], v[42:43], s[56:57] op_sel_hi:[1,1,0]
	v_pk_mul_f32 v[10:11], v[10:11], v[40:41]
	v_pk_fma_f32 v[44:45], v[32:33], v[44:45], s[56:57] op_sel_hi:[1,1,0]
	v_pk_mul_f32 v[28:29], v[28:29], v[42:43]
	v_pk_mul_f32 v[10:11], v[26:27], v[10:11]
	v_pk_mul_f32 v[32:33], v[32:33], v[44:45]
	v_pk_mul_f32 v[26:27], v[30:31], v[28:29]
	v_max_f32_e32 v80, 0, v24
	v_fma_f32 v41, -|v24|, v10, v80
	v_max_f32_e32 v81, 0, v25
	v_fma_f32 v11, -|v25|, v11, v81
	v_pk_mul_f32 v[28:29], v[34:35], v[32:33]
	v_max_f32_e32 v82, 0, v22
	v_fma_f32 v25, -|v22|, v28, v82
	v_max_f32_e32 v83, 0, v23
	v_fma_f32 v23, -|v23|, v29, v83
	v_max_f32_e32 v84, 0, v14
	v_fma_f32 v24, -|v14|, v26, v84
	v_max_f32_e32 v85, 0, v15
	v_fma_f32 v15, -|v15|, v27, v85
	v_fma_f32 v36, |v8|, s40, 1.0
	v_fma_f32 v37, |v9|, s40, 1.0
	v_mov_b32_e32 v14, v25
	v_rcp_f32_e32 v36, v36
	v_rcp_f32_e32 v37, v37
	v_mul_f32_e32 v26, v24, v24
	v_mov_b32_e32 v27, v25
	v_mul_f32_e32 v22, v15, v15
	v_mul_f32_e32 v12, v23, v23
	v_pk_add_f32 v[22:23], v[26:27], v[22:23]
	v_pk_mul_f32 v[26:27], v[24:25], v[14:15] op_sel:[1,0] op_sel_hi:[0,1]
	v_pk_add_f32 v[14:15], v[24:25], v[14:15] op_sel:[1,0] op_sel_hi:[0,1]
	v_pk_mul_f32 v[38:39], v[8:9], v[8:9]
	v_mov_b32_e32 v27, v15
	v_pk_mul_f32 v[38:39], v[38:39], s[64:65] op_sel_hi:[1,0]
	v_pk_fma_f32 v[46:47], v[36:37], s[42:43], v[18:19] op_sel_hi:[1,0,0]
	v_mul_f32_e32 v40, v41, v41
	v_mul_f32_e32 v10, v11, v11
	v_pk_add_f32 v[12:13], v[26:27], v[12:13]
	v_exp_f32_e32 v38, v38
	v_pk_fma_f32 v[46:47], v[36:37], v[46:47], s[48:49] op_sel_hi:[1,1,0]
	v_pk_add_f32 v[10:11], v[40:41], v[10:11]
	v_pk_add_f32 v[12:13], v[22:23], v[12:13]
	v_exp_f32_e32 v39, v39
	v_pk_add_f32 v[22:23], v[10:11], v[12:13]
	v_pk_fma_f32 v[10:11], v[36:37], v[46:47], s[50:51] op_sel_hi:[1,1,0]
	v_pk_fma_f32 v[10:11], v[36:37], v[10:11], s[56:57] op_sel_hi:[1,1,0]
	s_nop 0
	v_pk_mul_f32 v[10:11], v[36:37], v[10:11]
	s_waitcnt vmcnt(0)
	v_lshlrev_b32_e32 v36, 16, v6
	v_pk_mul_f32 v[10:11], v[38:39], v[10:11]
	v_and_b32_e32 v37, 0xffff0000, v6
	v_max_f32_e32 v86, 0, v8
	v_fma_f32 v15, -|v8|, v10, v86
	v_max_f32_e32 v90, 0, v9
	v_fma_f32 v9, -|v9|, v11, v90
	v_and_b32_e32 v33, 0x7fffffff, v37
	v_lshlrev_b32_e32 v12, 16, v4
	v_and_b32_e32 v10, 0x7fffffff, v12
	v_and_b32_e32 v13, 0xffff0000, v4
	v_and_b32_e32 v11, 0x7fffffff, v13
	v_pk_fma_f32 v[10:11], v[10:11], s[40:41], 1.0 op_sel_hi:[1,0,0]
	v_mul_f32_e32 v14, v15, v15
	v_rcp_f32_e32 v10, v10
	v_rcp_f32_e32 v11, v11
	v_mul_f32_e32 v8, v9, v9
	v_pk_add_f32 v[24:25], v[14:15], v[8:9]
	v_pk_mul_f32 v[14:15], v[12:13], v[12:13]
	v_pk_fma_f32 v[8:9], v[10:11], s[42:43], v[18:19] op_sel_hi:[1,0,0]
	v_pk_mul_f32 v[14:15], v[14:15], s[64:65] op_sel_hi:[1,0]
	v_pk_fma_f32 v[8:9], v[10:11], v[8:9], s[48:49] op_sel_hi:[1,1,0]
	v_exp_f32_e32 v14, v14
	v_exp_f32_e32 v15, v15
	v_pk_fma_f32 v[8:9], v[10:11], v[8:9], s[50:51] op_sel_hi:[1,1,0]
	v_lshlrev_b32_e32 v4, 16, v5
	v_pk_fma_f32 v[8:9], v[10:11], v[8:9], s[56:57] op_sel_hi:[1,1,0]
	v_and_b32_e32 v5, 0xffff0000, v5
	v_pk_mul_f32 v[8:9], v[10:11], v[8:9]
	v_pk_mul_f32 v[14:15], v[14:15], v[8:9]
	global_load_dwordx4 v[8:11], v[20:21], off offset:512
	v_fma_f32 v30, |v4|, s40, 1.0
	v_fma_f32 v31, |v5|, s40, 1.0
	v_rcp_f32_e32 v30, v30
	v_rcp_f32_e32 v31, v31
	v_max_f32_e32 v91, 0, v12
	v_fma_f32 v27, -|v12|, v14, v91
	v_max_f32_e32 v92, 0, v13
	v_fma_f32 v29, -|v13|, v15, v92
	v_and_b32_e32 v32, 0x7fffffff, v36
	v_pk_fma_f32 v[32:33], v[32:33], s[40:41], 1.0 op_sel_hi:[1,0,0]
	v_pk_fma_f32 v[12:13], v[30:31], s[42:43], v[18:19] op_sel_hi:[1,0,0]
	v_rcp_f32_e32 v34, v32
	v_pk_mul_f32 v[14:15], v[4:5], v[4:5]
	v_pk_fma_f32 v[12:13], v[30:31], v[12:13], s[48:49] op_sel_hi:[1,1,0]
	v_pk_mul_f32 v[14:15], v[14:15], s[64:65] op_sel_hi:[1,0]
	v_pk_fma_f32 v[12:13], v[30:31], v[12:13], s[50:51] op_sel_hi:[1,1,0]
	v_exp_f32_e32 v14, v14
	v_exp_f32_e32 v15, v15
	v_pk_fma_f32 v[12:13], v[30:31], v[12:13], s[56:57] op_sel_hi:[1,1,0]
	v_rcp_f32_e32 v35, v33
	v_pk_mul_f32 v[12:13], v[30:31], v[12:13]
	v_pk_mul_f32 v[12:13], v[14:15], v[12:13]
	v_mul_f32_e32 v26, v27, v27
	v_max_f32_e32 v93, 0, v4
	v_fma_f32 v31, -|v4|, v12, v93
	v_max_f32_e32 v94, 0, v5
	v_fma_f32 v33, -|v5|, v13, v94
	v_mul_f32_e32 v28, v29, v29
	v_pk_fma_f32 v[4:5], v[34:35], s[42:43], v[18:19] op_sel_hi:[1,0,0]
	v_lshlrev_b32_e32 v14, 16, v7
	v_pk_mul_f32 v[12:13], v[36:37], v[36:37]
	v_pk_fma_f32 v[4:5], v[34:35], v[4:5], s[48:49] op_sel_hi:[1,1,0]
	v_pk_mul_f32 v[12:13], v[12:13], s[64:65] op_sel_hi:[1,0]
	v_pk_fma_f32 v[4:5], v[34:35], v[4:5], s[50:51] op_sel_hi:[1,1,0]
	v_exp_f32_e32 v12, v12
	v_exp_f32_e32 v13, v13
	v_and_b32_e32 v15, 0xffff0000, v7
	v_pk_fma_f32 v[4:5], v[34:35], v[4:5], s[56:57] op_sel_hi:[1,1,0]
	v_pk_mul_f32 v[4:5], v[34:35], v[4:5]
	v_fma_f32 v6, |v14|, s40, 1.0
	v_fma_f32 v7, |v15|, s40, 1.0
	v_pk_mul_f32 v[4:5], v[12:13], v[4:5]
	v_rcp_f32_e32 v6, v6
	v_rcp_f32_e32 v7, v7
	v_max_f32_e32 v95, 0, v36
	v_fma_f32 v35, -|v36|, v4, v95
	v_max_f32_e32 v96, 0, v37
	v_fma_f32 v37, -|v37|, v5, v96
	v_mul_f32_e32 v30, v31, v31
	v_mul_f32_e32 v32, v33, v33
	v_pk_add_f32 v[22:23], v[24:25], v[22:23]
	v_pk_add_f32 v[24:25], v[26:27], v[28:29]
	v_pk_mul_f32 v[12:13], v[14:15], v[14:15]
	v_pk_fma_f32 v[4:5], v[6:7], s[42:43], v[18:19] op_sel_hi:[1,0,0]
	v_pk_mul_f32 v[12:13], v[12:13], s[64:65] op_sel_hi:[1,0]
	v_pk_fma_f32 v[4:5], v[6:7], v[4:5], s[48:49] op_sel_hi:[1,1,0]
	v_exp_f32_e32 v12, v12
	v_exp_f32_e32 v13, v13
	v_pk_fma_f32 v[4:5], v[6:7], v[4:5], s[50:51] op_sel_hi:[1,1,0]
	v_cmp_gt_f32_e64 s[0:1], 0, v14
	v_pk_fma_f32 v[4:5], v[6:7], v[4:5], s[56:57] op_sel_hi:[1,1,0]
	v_mul_f32_e32 v34, v35, v35
	v_pk_mul_f32 v[4:5], v[6:7], v[4:5]
	v_mul_f32_e32 v36, v37, v37
	v_pk_mul_f32 v[4:5], v[12:13], v[4:5]
	v_pk_add_f32 v[22:23], v[24:25], v[22:23]
	v_pk_mul_f32 v[12:13], v[14:15], v[4:5]
	v_pk_fma_f32 v[40:41], v[14:15], v[4:5], v[14:15] neg_lo:[1,0,0] neg_hi:[1,0,0]
	global_load_dwordx4 v[4:7], v[20:21], off offset:768
	v_cndmask_b32_e64 v39, v40, v12, s[0:1]
	v_cmp_gt_f32_e64 s[0:1], 0, v15
	v_pk_add_f32 v[24:25], v[30:31], v[32:33]
	s_waitcnt vmcnt(1)
	v_lshlrev_b32_e32 v44, 16, v8
	v_and_b32_e32 v45, 0xffff0000, v8
	v_fma_f32 v42, |v44|, s40, 1.0
	v_fma_f32 v43, |v45|, s40, 1.0
	v_pk_mul_f32 v[14:15], v[44:45], v[44:45]
	v_rcp_f32_e32 v42, v42
	v_rcp_f32_e32 v43, v43
	v_cndmask_b32_e64 v41, v41, v13, s[0:1]
	v_pk_mul_f32 v[14:15], v[14:15], s[64:65] op_sel_hi:[1,0]
	v_lshlrev_b32_e32 v46, 16, v9
	v_pk_fma_f32 v[12:13], v[42:43], s[42:43], v[18:19] op_sel_hi:[1,0,0]
	v_exp_f32_e32 v14, v14
	v_pk_fma_f32 v[12:13], v[42:43], v[12:13], s[48:49] op_sel_hi:[1,1,0]
	v_exp_f32_e32 v15, v15
	v_and_b32_e32 v47, 0xffff0000, v9
	v_pk_fma_f32 v[12:13], v[42:43], v[12:13], s[50:51] op_sel_hi:[1,1,0]
	v_pk_fma_f32 v[12:13], v[42:43], v[12:13], s[56:57] op_sel_hi:[1,1,0]
	v_fma_f32 v8, |v46|, s40, 1.0
	v_fma_f32 v9, |v47|, s40, 1.0
	v_pk_mul_f32 v[12:13], v[42:43], v[12:13]
	v_rcp_f32_e32 v48, v8
	v_rcp_f32_e32 v49, v9
	v_pk_mul_f32 v[12:13], v[14:15], v[12:13]
	v_max_f32_e32 v99, 0, v44
	v_fma_f32 v43, -|v44|, v12, v99
	v_max_f32_e32 v100, 0, v45
	v_fma_f32 v9, -|v45|, v13, v100
	v_lshlrev_b32_e32 v50, 16, v10
	v_and_b32_e32 v51, 0xffff0000, v10
	v_lshlrev_b32_e32 v10, 16, v11
	v_pk_fma_f32 v[12:13], v[48:49], s[42:43], v[18:19] op_sel_hi:[1,0,0]
	v_pk_mul_f32 v[14:15], v[46:47], v[46:47]
	v_pk_fma_f32 v[12:13], v[48:49], v[12:13], s[48:49] op_sel_hi:[1,1,0]
	v_pk_mul_f32 v[14:15], v[14:15], s[64:65] op_sel_hi:[1,0]
	v_pk_fma_f32 v[12:13], v[48:49], v[12:13], s[50:51] op_sel_hi:[1,1,0]
	v_exp_f32_e32 v14, v14
	v_exp_f32_e32 v15, v15
	v_pk_fma_f32 v[12:13], v[48:49], v[12:13], s[56:57] op_sel_hi:[1,1,0]
	v_pk_mul_f32 v[12:13], v[48:49], v[12:13]
	v_fma_f32 v48, |v50|, s40, 1.0
	v_fma_f32 v49, |v51|, s40, 1.0
	v_pk_mul_f32 v[12:13], v[14:15], v[12:13]
	v_rcp_f32_e32 v48, v48
	v_rcp_f32_e32 v49, v49
	v_max_f32_e32 v104, 0, v46
	v_fma_f32 v45, -|v46|, v12, v104
	v_max_f32_e32 v105, 0, v47
	v_fma_f32 v47, -|v47|, v13, v105
	v_and_b32_e32 v11, 0xffff0000, v11
	v_pk_mul_f32 v[14:15], v[50:51], v[50:51]
	v_pk_fma_f32 v[12:13], v[48:49], s[42:43], v[18:19] op_sel_hi:[1,0,0]
	v_pk_mul_f32 v[14:15], v[14:15], s[64:65] op_sel_hi:[1,0]
	v_pk_fma_f32 v[12:13], v[48:49], v[12:13], s[48:49] op_sel_hi:[1,1,0]
	v_exp_f32_e32 v14, v14
	v_exp_f32_e32 v15, v15
	v_pk_fma_f32 v[12:13], v[48:49], v[12:13], s[50:51] op_sel_hi:[1,1,0]
	v_fma_f32 v52, |v10|, s40, 1.0
	v_fma_f32 v53, |v11|, s40, 1.0
	v_pk_fma_f32 v[12:13], v[48:49], v[12:13], s[56:57] op_sel_hi:[1,1,0]
	v_rcp_f32_e32 v52, v52
	v_pk_mul_f32 v[12:13], v[48:49], v[12:13]
	v_rcp_f32_e32 v53, v53
	v_pk_mul_f32 v[12:13], v[14:15], v[12:13]
	v_max_f32_e32 v106, 0, v50
	v_mul_f32_e32 v38, v39, v39
	v_fma_f32 v49, -|v50|, v12, v106
	v_max_f32_e32 v107, 0, v51
	s_waitcnt vmcnt(0)
	v_lshlrev_b32_e32 v60, 16, v4
	v_and_b32_e32 v61, 0xffff0000, v4
	v_fma_f32 v51, -|v51|, v13, v107
	v_pk_mul_f32 v[14:15], v[10:11], v[10:11]
	v_pk_fma_f32 v[12:13], v[52:53], s[42:43], v[18:19] op_sel_hi:[1,0,0]
	v_pk_mul_f32 v[14:15], v[14:15], s[64:65] op_sel_hi:[1,0]
	v_pk_fma_f32 v[12:13], v[52:53], v[12:13], s[48:49] op_sel_hi:[1,1,0]
	v_exp_f32_e32 v14, v14
	v_exp_f32_e32 v15, v15
	v_pk_fma_f32 v[12:13], v[52:53], v[12:13], s[50:51] op_sel_hi:[1,1,0]
	v_pk_fma_f32 v[12:13], v[52:53], v[12:13], s[56:57] op_sel_hi:[1,1,0]
	v_pk_mul_f32 v[12:13], v[52:53], v[12:13]
	v_fma_f32 v62, |v60|, s40, 1.0
	v_fma_f32 v63, |v61|, s40, 1.0
	v_pk_mul_f32 v[12:13], v[14:15], v[12:13]
	v_rcp_f32_e32 v62, v62
	v_rcp_f32_e32 v63, v63
	v_max_f32_e32 v108, 0, v10
	v_fma_f32 v53, -|v10|, v12, v108
	v_max_f32_e32 v109, 0, v11
	v_fma_f32 v11, -|v11|, v13, v109
	v_lshlrev_b32_e32 v4, 16, v5
	v_and_b32_e32 v5, 0xffff0000, v5
	v_pk_mul_f32 v[14:15], v[60:61], v[60:61]
	v_pk_fma_f32 v[12:13], v[62:63], s[42:43], v[18:19] op_sel_hi:[1,0,0]
	v_pk_mul_f32 v[14:15], v[14:15], s[64:65] op_sel_hi:[1,0]
	v_pk_fma_f32 v[12:13], v[62:63], v[12:13], s[48:49] op_sel_hi:[1,1,0]
	v_exp_f32_e32 v14, v14
	v_exp_f32_e32 v15, v15
	v_pk_fma_f32 v[12:13], v[62:63], v[12:13], s[50:51] op_sel_hi:[1,1,0]
	v_fma_f32 v64, |v4|, s40, 1.0
	v_fma_f32 v65, |v5|, s40, 1.0
	v_pk_fma_f32 v[12:13], v[62:63], v[12:13], s[56:57] op_sel_hi:[1,1,0]
	v_rcp_f32_e32 v64, v64
	v_pk_mul_f32 v[12:13], v[62:63], v[12:13]
	v_rcp_f32_e32 v65, v65
	v_pk_mul_f32 v[12:13], v[14:15], v[12:13]
	v_max_f32_e32 v110, 0, v60
	v_fma_f32 v63, -|v60|, v12, v110
	v_max_f32_e32 v111, 0, v61
	v_fma_f32 v61, -|v61|, v13, v111
	v_mul_f32_e32 v40, v41, v41
	v_pk_add_f32 v[22:23], v[24:25], v[22:23]
	v_pk_add_f32 v[24:25], v[34:35], v[36:37]
	v_pk_fma_f32 v[12:13], v[64:65], s[42:43], v[18:19] op_sel_hi:[1,0,0]
	v_pk_mul_f32 v[14:15], v[4:5], v[4:5]
	v_pk_fma_f32 v[12:13], v[64:65], v[12:13], s[48:49] op_sel_hi:[1,1,0]
	v_pk_mul_f32 v[14:15], v[14:15], s[64:65] op_sel_hi:[1,0]
	v_pk_fma_f32 v[12:13], v[64:65], v[12:13], s[50:51] op_sel_hi:[1,1,0]
	v_exp_f32_e32 v66, v14
	v_exp_f32_e32 v67, v15
	v_pk_fma_f32 v[68:69], v[64:65], v[12:13], s[56:57] op_sel_hi:[1,1,0]
	global_load_dwordx4 v[12:15], v[20:21], off offset:1024
	v_mul_f32_e32 v42, v43, v43
	v_mul_f32_e32 v8, v9, v9
	v_pk_add_f32 v[22:23], v[24:25], v[22:23]
	v_pk_add_f32 v[24:25], v[38:39], v[40:41]
	v_mul_f32_e32 v44, v45, v45
	v_mul_f32_e32 v46, v47, v47
	v_pk_add_f32 v[22:23], v[24:25], v[22:23]
	v_pk_add_f32 v[8:9], v[42:43], v[8:9]
	v_mul_f32_e32 v48, v49, v49
	v_mul_f32_e32 v50, v51, v51
	v_pk_mul_f32 v[64:65], v[64:65], v[68:69]
	v_pk_add_f32 v[8:9], v[8:9], v[22:23]
	v_pk_add_f32 v[22:23], v[44:45], v[46:47]
	v_pk_mul_f32 v[64:65], v[66:67], v[64:65]
	v_pk_add_f32 v[8:9], v[22:23], v[8:9]
	v_pk_add_f32 v[22:23], v[48:49], v[50:51]
	v_lshlrev_b32_e32 v24, 16, v6
	v_and_b32_e32 v25, 0xffff0000, v6
	v_max_f32_e32 v112, 0, v4
	v_fma_f32 v69, -|v4|, v64, v112
	v_max_f32_e32 v113, 0, v5
	v_fma_f32 v5, -|v5|, v65, v113
	v_pk_add_f32 v[8:9], v[22:23], v[8:9]
	v_mul_f32_e32 v52, v53, v53
	v_mul_f32_e32 v10, v11, v11
	v_fma_f32 v22, |v24|, s40, 1.0
	v_fma_f32 v23, |v25|, s40, 1.0
	v_mul_f32_e32 v62, v63, v63
	v_mul_f32_e32 v60, v61, v61
	v_pk_add_f32 v[10:11], v[52:53], v[10:11]
	v_rcp_f32_e32 v26, v22
	v_rcp_f32_e32 v27, v23
	v_mul_f32_e32 v68, v69, v69
	v_mul_f32_e32 v4, v5, v5
	v_pk_add_f32 v[8:9], v[10:11], v[8:9]
	v_pk_add_f32 v[10:11], v[62:63], v[60:61]
	v_pk_add_f32 v[4:5], v[68:69], v[4:5]
	v_pk_add_f32 v[8:9], v[10:11], v[8:9]
	v_pk_add_f32 v[22:23], v[4:5], v[8:9]
	v_pk_mul_f32 v[8:9], v[24:25], v[24:25]
	v_pk_fma_f32 v[4:5], v[26:27], s[42:43], v[18:19] op_sel_hi:[1,0,0]
	v_pk_mul_f32 v[8:9], v[8:9], s[64:65] op_sel_hi:[1,0]
	v_pk_fma_f32 v[4:5], v[26:27], v[4:5], s[48:49] op_sel_hi:[1,1,0]
	v_exp_f32_e32 v8, v8
	v_exp_f32_e32 v9, v9
	v_pk_fma_f32 v[4:5], v[26:27], v[4:5], s[50:51] op_sel_hi:[1,1,0]
	v_lshlrev_b32_e32 v6, 16, v7
	v_pk_fma_f32 v[4:5], v[26:27], v[4:5], s[56:57] op_sel_hi:[1,1,0]
	v_and_b32_e32 v7, 0xffff0000, v7
	v_pk_mul_f32 v[4:5], v[26:27], v[4:5]
	s_nop 0
	v_pk_mul_f32 v[4:5], v[8:9], v[4:5]
	s_nop 0
	v_max_f32_e32 v114, 0, v24
	v_fma_f32 v11, -|v24|, v4, v114
	v_max_f32_e32 v115, 0, v25
	v_fma_f32 v5, -|v25|, v5, v115
	s_nop 0
	v_mul_f32_e32 v10, v11, v11
	v_fma_f32 v8, |v6|, s40, 1.0
	v_fma_f32 v9, |v7|, s40, 1.0
	v_mul_f32_e32 v4, v5, v5
	v_rcp_f32_e32 v8, v8
	v_rcp_f32_e32 v9, v9
	v_pk_add_f32 v[24:25], v[10:11], v[4:5]
	v_pk_mul_f32 v[10:11], v[6:7], v[6:7]
	v_pk_fma_f32 v[4:5], v[8:9], s[42:43], v[18:19] op_sel_hi:[1,0,0]
	v_pk_mul_f32 v[10:11], v[10:11], s[64:65] op_sel_hi:[1,0]
	v_pk_fma_f32 v[4:5], v[8:9], v[4:5], s[48:49] op_sel_hi:[1,1,0]
	v_exp_f32_e32 v10, v10
	v_exp_f32_e32 v11, v11
	v_pk_fma_f32 v[4:5], v[8:9], v[4:5], s[50:51] op_sel_hi:[1,1,0]
	v_pk_add_f32 v[22:23], v[24:25], v[22:23]
	v_pk_fma_f32 v[4:5], v[8:9], v[4:5], s[56:57] op_sel_hi:[1,1,0]
	s_nop 0
	v_pk_mul_f32 v[4:5], v[8:9], v[4:5]
	s_nop 0
	v_pk_mul_f32 v[4:5], v[10:11], v[4:5]
	global_load_dwordx4 v[8:11], v[20:21], off offset:1280
	s_waitcnt vmcnt(1)
	v_lshlrev_b32_e32 v32, 16, v12
	v_and_b32_e32 v33, 0xffff0000, v12
	v_fma_f32 v30, |v32|, s40, 1.0
	v_fma_f32 v31, |v33|, s40, 1.0
	v_rcp_f32_e32 v30, v30
	v_rcp_f32_e32 v31, v31
	v_max_f32_e32 v116, 0, v6
	v_fma_f32 v27, -|v6|, v4, v116
	v_max_f32_e32 v117, 0, v7
	v_fma_f32 v29, -|v7|, v5, v117
	v_lshlrev_b32_e32 v34, 16, v13
	v_pk_mul_f32 v[6:7], v[32:33], v[32:33]
	v_and_b32_e32 v35, 0xffff0000, v13
	v_pk_fma_f32 v[4:5], v[30:31], s[42:43], v[18:19] op_sel_hi:[1,0,0]
	v_pk_mul_f32 v[6:7], v[6:7], s[64:65] op_sel_hi:[1,0]
	v_pk_fma_f32 v[4:5], v[30:31], v[4:5], s[48:49] op_sel_hi:[1,1,0]
	v_exp_f32_e32 v6, v6
	v_exp_f32_e32 v7, v7
	v_pk_fma_f32 v[4:5], v[30:31], v[4:5], s[50:51] op_sel_hi:[1,1,0]
	v_pk_fma_f32 v[4:5], v[30:31], v[4:5], s[56:57] op_sel_hi:[1,1,0]
	v_fma_f32 v12, |v34|, s40, 1.0
	v_fma_f32 v13, |v35|, s40, 1.0
	v_pk_mul_f32 v[4:5], v[30:31], v[4:5]
	v_rcp_f32_e32 v36, v12
	v_rcp_f32_e32 v37, v13
	v_pk_mul_f32 v[4:5], v[6:7], v[4:5]
	v_max_f32_e32 v80, 0, v32
	v_fma_f32 v31, -|v32|, v4, v80
	v_max_f32_e32 v81, 0, v33
	v_fma_f32 v13, -|v33|, v5, v81
	v_lshlrev_b32_e32 v38, 16, v14
	v_and_b32_e32 v39, 0xffff0000, v14
	v_lshlrev_b32_e32 v40, 16, v15
	v_pk_fma_f32 v[4:5], v[36:37], s[42:43], v[18:19] op_sel_hi:[1,0,0]
	v_pk_mul_f32 v[6:7], v[34:35], v[34:35]
	v_pk_fma_f32 v[4:5], v[36:37], v[4:5], s[48:49] op_sel_hi:[1,1,0]
	v_pk_mul_f32 v[6:7], v[6:7], s[64:65] op_sel_hi:[1,0]
	v_pk_fma_f32 v[4:5], v[36:37], v[4:5], s[50:51] op_sel_hi:[1,1,0]
	v_exp_f32_e32 v6, v6
	v_exp_f32_e32 v7, v7
	v_pk_fma_f32 v[4:5], v[36:37], v[4:5], s[56:57] op_sel_hi:[1,1,0]
	v_pk_mul_f32 v[4:5], v[36:37], v[4:5]
	v_fma_f32 v36, |v38|, s40, 1.0
	v_fma_f32 v37, |v39|, s40, 1.0
	v_pk_mul_f32 v[4:5], v[6:7], v[4:5]
	v_rcp_f32_e32 v36, v36
	v_rcp_f32_e32 v37, v37
	v_max_f32_e32 v82, 0, v34
	v_fma_f32 v33, -|v34|, v4, v82
	v_max_f32_e32 v83, 0, v35
	v_fma_f32 v35, -|v35|, v5, v83
	v_and_b32_e32 v41, 0xffff0000, v15
	v_pk_mul_f32 v[6:7], v[38:39], v[38:39]
	v_pk_fma_f32 v[4:5], v[36:37], s[42:43], v[18:19] op_sel_hi:[1,0,0]
	v_pk_mul_f32 v[6:7], v[6:7], s[64:65] op_sel_hi:[1,0]
	v_pk_fma_f32 v[4:5], v[36:37], v[4:5], s[48:49] op_sel_hi:[1,1,0]
	v_exp_f32_e32 v6, v6
	v_exp_f32_e32 v7, v7
	v_pk_fma_f32 v[4:5], v[36:37], v[4:5], s[50:51] op_sel_hi:[1,1,0]
	v_fma_f32 v14, |v40|, s40, 1.0
	v_fma_f32 v15, |v41|, s40, 1.0
	v_pk_fma_f32 v[4:5], v[36:37], v[4:5], s[56:57] op_sel_hi:[1,1,0]
	v_rcp_f32_e32 v42, v14
	v_pk_mul_f32 v[4:5], v[36:37], v[4:5]
	v_rcp_f32_e32 v43, v15
	v_pk_mul_f32 v[4:5], v[6:7], v[4:5]
	v_max_f32_e32 v84, 0, v38
	v_mul_f32_e32 v26, v27, v27
	v_fma_f32 v37, -|v38|, v4, v84
	v_max_f32_e32 v85, 0, v39
	s_waitcnt vmcnt(0)
	v_lshlrev_b32_e32 v44, 16, v8
	v_and_b32_e32 v45, 0xffff0000, v8
	v_fma_f32 v15, -|v39|, v5, v85
	v_pk_fma_f32 v[4:5], v[42:43], s[42:43], v[18:19] op_sel_hi:[1,0,0]
	v_pk_mul_f32 v[6:7], v[40:41], v[40:41]
	v_pk_fma_f32 v[4:5], v[42:43], v[4:5], s[48:49] op_sel_hi:[1,1,0]
	v_pk_mul_f32 v[6:7], v[6:7], s[64:65] op_sel_hi:[1,0]
	v_pk_fma_f32 v[4:5], v[42:43], v[4:5], s[50:51] op_sel_hi:[1,1,0]
	v_exp_f32_e32 v6, v6
	v_exp_f32_e32 v7, v7
	v_pk_fma_f32 v[4:5], v[42:43], v[4:5], s[56:57] op_sel_hi:[1,1,0]
	v_pk_mul_f32 v[4:5], v[42:43], v[4:5]
	v_fma_f32 v42, |v44|, s40, 1.0
	v_fma_f32 v43, |v45|, s40, 1.0
	v_pk_mul_f32 v[4:5], v[6:7], v[4:5]
	v_rcp_f32_e32 v42, v42
	v_rcp_f32_e32 v43, v43
	v_max_f32_e32 v86, 0, v40
	v_fma_f32 v39, -|v40|, v4, v86
	v_max_f32_e32 v90, 0, v41
	v_fma_f32 v41, -|v41|, v5, v90
	v_lshlrev_b32_e32 v50, 16, v9
	v_and_b32_e32 v51, 0xffff0000, v9
	v_pk_mul_f32 v[6:7], v[44:45], v[44:45]
	v_pk_fma_f32 v[4:5], v[42:43], s[42:43], v[18:19] op_sel_hi:[1,0,0]
	v_pk_mul_f32 v[6:7], v[6:7], s[64:65] op_sel_hi:[1,0]
	v_pk_fma_f32 v[4:5], v[42:43], v[4:5], s[48:49] op_sel_hi:[1,1,0]
	v_exp_f32_e32 v6, v6
	v_exp_f32_e32 v7, v7
	v_pk_fma_f32 v[4:5], v[42:43], v[4:5], s[50:51] op_sel_hi:[1,1,0]
	v_pk_fma_f32 v[4:5], v[42:43], v[4:5], s[56:57] op_sel_hi:[1,1,0]
	v_fma_f32 v8, |v50|, s40, 1.0
	v_fma_f32 v9, |v51|, s40, 1.0
	v_pk_mul_f32 v[4:5], v[42:43], v[4:5]
	v_rcp_f32_e32 v52, v8
	v_pk_mul_f32 v[42:43], v[6:7], v[4:5]
	global_load_dwordx4 v[4:7], v[20:21], off offset:1536
	v_rcp_f32_e32 v53, v9
	v_max_f32_e32 v92, 0, v45
	v_fma_f32 v9, -|v45|, v43, v92
	v_max_f32_e32 v91, 0, v44
	v_fma_f32 v43, -|v44|, v42, v91
	v_lshlrev_b32_e32 v62, 16, v11
	v_and_b32_e32 v63, 0xffff0000, v11
	v_pk_fma_f32 v[44:45], v[52:53], s[42:43], v[18:19] op_sel_hi:[1,0,0]
	v_and_b32_e32 v11, 0x7fffffff, v63
	v_pk_fma_f32 v[44:45], v[52:53], v[44:45], s[48:49] op_sel_hi:[1,1,0]
	v_pk_mul_f32 v[46:47], v[50:51], v[50:51]
	v_pk_fma_f32 v[44:45], v[52:53], v[44:45], s[50:51] op_sel_hi:[1,1,0]
	v_pk_mul_f32 v[46:47], v[46:47], s[64:65] op_sel_hi:[1,0]
	v_pk_fma_f32 v[44:45], v[52:53], v[44:45], s[56:57] op_sel_hi:[1,1,0]
	v_exp_f32_e32 v46, v46
	v_exp_f32_e32 v47, v47
	v_pk_mul_f32 v[44:45], v[52:53], v[44:45]
	v_lshlrev_b32_e32 v52, 16, v10
	v_and_b32_e32 v53, 0xffff0000, v10
	v_fma_f32 v60, |v52|, s40, 1.0
	v_fma_f32 v61, |v53|, s40, 1.0
	v_pk_mul_f32 v[44:45], v[46:47], v[44:45]
	v_rcp_f32_e32 v60, v60
	v_rcp_f32_e32 v61, v61
	v_max_f32_e32 v94, 0, v51
	v_fma_f32 v47, -|v51|, v45, v94
	v_max_f32_e32 v93, 0, v50
	v_fma_f32 v45, -|v50|, v44, v93
	v_and_b32_e32 v10, 0x7fffffff, v62
	v_pk_fma_f32 v[10:11], v[10:11], s[40:41], 1.0 op_sel_hi:[1,0,0]
	v_pk_mul_f32 v[50:51], v[52:53], v[52:53]
	v_rcp_f32_e32 v64, v10
	v_pk_fma_f32 v[48:49], v[60:61], s[42:43], v[18:19] op_sel_hi:[1,0,0]
	v_pk_mul_f32 v[50:51], v[50:51], s[64:65] op_sel_hi:[1,0]
	v_pk_fma_f32 v[48:49], v[60:61], v[48:49], s[48:49] op_sel_hi:[1,1,0]
	v_exp_f32_e32 v50, v50
	v_exp_f32_e32 v51, v51
	v_pk_fma_f32 v[48:49], v[60:61], v[48:49], s[50:51] op_sel_hi:[1,1,0]
	v_rcp_f32_e32 v65, v11
	v_pk_fma_f32 v[48:49], v[60:61], v[48:49], s[56:57] op_sel_hi:[1,1,0]
	v_pk_mul_f32 v[48:49], v[60:61], v[48:49]
	v_mul_f32_e32 v28, v29, v29
	v_pk_mul_f32 v[48:49], v[50:51], v[48:49]
	v_mul_f32_e32 v30, v31, v31
	v_max_f32_e32 v96, 0, v53
	v_fma_f32 v11, -|v53|, v49, v96
	v_max_f32_e32 v95, 0, v52
	v_fma_f32 v49, -|v52|, v48, v95
	v_mul_f32_e32 v12, v13, v13
	v_pk_mul_f32 v[52:53], v[62:63], v[62:63]
	v_pk_add_f32 v[24:25], v[26:27], v[28:29]
	v_pk_fma_f32 v[50:51], v[64:65], s[42:43], v[18:19] op_sel_hi:[1,0,0]
	v_pk_mul_f32 v[52:53], v[52:53], s[64:65] op_sel_hi:[1,0]
	v_pk_fma_f32 v[50:51], v[64:65], v[50:51], s[48:49] op_sel_hi:[1,1,0]
	v_exp_f32_e32 v52, v52
	v_exp_f32_e32 v53, v53
	v_pk_fma_f32 v[50:51], v[64:65], v[50:51], s[50:51] op_sel_hi:[1,1,0]
	v_pk_fma_f32 v[50:51], v[64:65], v[50:51], s[56:57] op_sel_hi:[1,1,0]
	v_mul_f32_e32 v32, v33, v33
	v_pk_mul_f32 v[50:51], v[64:65], v[50:51]
	v_mul_f32_e32 v34, v35, v35
	v_pk_mul_f32 v[50:51], v[52:53], v[50:51]
	v_pk_add_f32 v[22:23], v[24:25], v[22:23]
	v_max_f32_e32 v97, 0, v62
	v_fma_f32 v67, -|v62|, v50, v97
	v_max_f32_e32 v98, 0, v63
	v_fma_f32 v61, -|v63|, v51, v98
	global_load_dwordx4 v[50:53], v[20:21], off offset:1792
	v_pk_add_f32 v[12:13], v[30:31], v[12:13]
	v_mul_f32_e32 v36, v37, v37
	s_waitcnt vmcnt(1)
	v_lshlrev_b32_e32 v20, 16, v4
	v_and_b32_e32 v21, 0xffff0000, v4
	v_fma_f32 v68, |v20|, s40, 1.0
	v_fma_f32 v69, |v21|, s40, 1.0
	v_pk_mul_f32 v[64:65], v[20:21], v[20:21]
	v_rcp_f32_e32 v68, v68
	v_rcp_f32_e32 v69, v69
	v_mul_f32_e32 v14, v15, v15
	v_pk_mul_f32 v[64:65], v[64:65], s[64:65] op_sel_hi:[1,0]
	v_pk_add_f32 v[12:13], v[12:13], v[22:23]
	v_pk_fma_f32 v[62:63], v[68:69], s[42:43], v[18:19] op_sel_hi:[1,0,0]
	v_pk_add_f32 v[22:23], v[32:33], v[34:35]
	v_mul_f32_e32 v38, v39, v39
	v_mul_f32_e32 v40, v41, v41
	v_pk_fma_f32 v[62:63], v[68:69], v[62:63], s[48:49] op_sel_hi:[1,1,0]
	v_exp_f32_e32 v64, v64
	v_exp_f32_e32 v65, v65
	v_pk_add_f32 v[12:13], v[22:23], v[12:13]
	v_pk_add_f32 v[14:15], v[36:37], v[14:15]
	v_mul_f32_e32 v42, v43, v43
	v_mul_f32_e32 v8, v9, v9
	v_pk_fma_f32 v[62:63], v[68:69], v[62:63], s[50:51] op_sel_hi:[1,1,0]
	v_pk_add_f32 v[12:13], v[14:15], v[12:13]
	v_pk_add_f32 v[14:15], v[38:39], v[40:41]
	v_mul_f32_e32 v44, v45, v45
	v_mul_f32_e32 v46, v47, v47
	v_pk_fma_f32 v[62:63], v[68:69], v[62:63], s[56:57] op_sel_hi:[1,1,0]
	v_pk_add_f32 v[12:13], v[14:15], v[12:13]
	v_pk_add_f32 v[8:9], v[42:43], v[8:9]
	v_pk_mul_f32 v[62:63], v[68:69], v[62:63]
	v_pk_add_f32 v[8:9], v[8:9], v[12:13]
	v_pk_add_f32 v[12:13], v[44:45], v[46:47]
	v_lshlrev_b32_e32 v4, 16, v5
	v_and_b32_e32 v5, 0xffff0000, v5
	v_pk_mul_f32 v[62:63], v[64:65], v[62:63]
	v_pk_add_f32 v[8:9], v[12:13], v[8:9]
	v_max_f32_e32 v99, 0, v20
	v_fma_f32 v69, -|v20|, v62, v99
	v_max_f32_e32 v100, 0, v21
	v_fma_f32 v21, -|v21|, v63, v100
	v_fma_f32 v12, |v4|, s40, 1.0
	v_fma_f32 v13, |v5|, s40, 1.0
	v_mul_f32_e32 v48, v49, v49
	v_mul_f32_e32 v10, v11, v11
	v_rcp_f32_e32 v12, v12
	v_rcp_f32_e32 v13, v13
	v_mul_f32_e32 v66, v67, v67
	v_mul_f32_e32 v60, v61, v61
	v_pk_add_f32 v[10:11], v[48:49], v[10:11]
	v_mul_f32_e32 v68, v69, v69
	v_mul_f32_e32 v20, v21, v21
	v_pk_add_f32 v[8:9], v[10:11], v[8:9]
	v_pk_add_f32 v[10:11], v[66:67], v[60:61]
	v_pk_mul_f32 v[14:15], v[4:5], v[4:5]
	v_pk_add_f32 v[8:9], v[10:11], v[8:9]
	v_pk_add_f32 v[10:11], v[68:69], v[20:21]
	v_pk_mul_f32 v[14:15], v[14:15], s[64:65] op_sel_hi:[1,0]
	v_pk_add_f32 v[8:9], v[10:11], v[8:9]
	v_pk_fma_f32 v[10:11], v[12:13], s[42:43], v[18:19] op_sel_hi:[1,0,0]
	v_exp_f32_e32 v14, v14
	v_pk_fma_f32 v[10:11], v[12:13], v[10:11], s[48:49] op_sel_hi:[1,1,0]
	v_exp_f32_e32 v15, v15
	v_pk_fma_f32 v[10:11], v[12:13], v[10:11], s[50:51] op_sel_hi:[1,1,0]
	v_pk_fma_f32 v[10:11], v[12:13], v[10:11], s[56:57] op_sel_hi:[1,1,0]
	s_waitcnt vmcnt(0)
	v_lshlrev_b32_e32 v24, 16, v50
	v_pk_mul_f32 v[10:11], v[12:13], v[10:11]
	v_and_b32_e32 v25, 0xffff0000, v50
	v_pk_mul_f32 v[10:11], v[14:15], v[10:11]
	v_and_b32_e32 v27, 0x7fffffff, v25
	v_max_f32_e32 v104, 0, v4
	v_fma_f32 v15, -|v4|, v10, v104
	v_max_f32_e32 v105, 0, v5
	v_fma_f32 v5, -|v5|, v11, v105
	v_and_b32_e32 v26, 0x7fffffff, v24
	v_lshlrev_b32_e32 v10, 16, v6
	v_and_b32_e32 v12, 0x7fffffff, v10
	v_and_b32_e32 v11, 0xffff0000, v6
	v_and_b32_e32 v13, 0x7fffffff, v11
	v_pk_fma_f32 v[12:13], v[12:13], s[40:41], 1.0 op_sel_hi:[1,0,0]
	v_mul_f32_e32 v14, v15, v15
	v_rcp_f32_e32 v12, v12
	v_rcp_f32_e32 v13, v13
	v_mul_f32_e32 v4, v5, v5
	v_pk_mul_f32 v[20:21], v[10:11], v[10:11]
	v_pk_add_f32 v[4:5], v[14:15], v[4:5]
	v_pk_fma_f32 v[14:15], v[12:13], s[42:43], v[18:19] op_sel_hi:[1,0,0]
	v_pk_mul_f32 v[20:21], v[20:21], s[64:65] op_sel_hi:[1,0]
	v_pk_fma_f32 v[14:15], v[12:13], v[14:15], s[48:49] op_sel_hi:[1,1,0]
	v_exp_f32_e32 v20, v20
	v_exp_f32_e32 v21, v21
	v_pk_fma_f32 v[14:15], v[12:13], v[14:15], s[50:51] op_sel_hi:[1,1,0]
	v_lshlrev_b32_e32 v6, 16, v7
	v_and_b32_e32 v7, 0xffff0000, v7
	v_pk_fma_f32 v[14:15], v[12:13], v[14:15], s[56:57] op_sel_hi:[1,1,0]
	v_pk_mul_f32 v[12:13], v[12:13], v[14:15]
	v_fma_f32 v22, |v6|, s40, 1.0
	v_fma_f32 v23, |v7|, s40, 1.0
	v_pk_mul_f32 v[12:13], v[20:21], v[12:13]
	v_rcp_f32_e32 v22, v22
	v_rcp_f32_e32 v23, v23
	v_max_f32_e32 v106, 0, v10
	v_fma_f32 v21, -|v10|, v12, v106
	v_max_f32_e32 v107, 0, v11
	v_fma_f32 v11, -|v11|, v13, v107
	v_pk_fma_f32 v[26:27], v[26:27], s[40:41], 1.0 op_sel_hi:[1,0,0]
	v_lshlrev_b32_e32 v28, 16, v51
	v_rcp_f32_e32 v26, v26
	v_rcp_f32_e32 v27, v27
	v_pk_mul_f32 v[14:15], v[6:7], v[6:7]
	v_pk_fma_f32 v[12:13], v[22:23], s[42:43], v[18:19] op_sel_hi:[1,0,0]
	v_pk_mul_f32 v[14:15], v[14:15], s[64:65] op_sel_hi:[1,0]
	v_pk_fma_f32 v[12:13], v[22:23], v[12:13], s[48:49] op_sel_hi:[1,1,0]
	v_exp_f32_e32 v14, v14
	v_exp_f32_e32 v15, v15
	v_pk_fma_f32 v[12:13], v[22:23], v[12:13], s[50:51] op_sel_hi:[1,1,0]
	v_pk_fma_f32 v[12:13], v[22:23], v[12:13], s[56:57] op_sel_hi:[1,1,0]
	v_and_b32_e32 v29, 0xffff0000, v51
	v_pk_mul_f32 v[12:13], v[22:23], v[12:13]
	v_pk_mul_f32 v[12:13], v[14:15], v[12:13]
	v_max_f32_e32 v108, 0, v6
	v_fma_f32 v23, -|v6|, v12, v108
	v_max_f32_e32 v109, 0, v7
	v_fma_f32 v7, -|v7|, v13, v109
	v_fma_f32 v30, |v28|, s40, 1.0
	v_fma_f32 v31, |v29|, s40, 1.0
	v_rcp_f32_e32 v30, v30
	v_rcp_f32_e32 v31, v31
	v_pk_mul_f32 v[14:15], v[24:25], v[24:25]
	v_pk_fma_f32 v[12:13], v[26:27], s[42:43], v[18:19] op_sel_hi:[1,0,0]
	v_pk_mul_f32 v[14:15], v[14:15], s[64:65] op_sel_hi:[1,0]
	v_pk_fma_f32 v[12:13], v[26:27], v[12:13], s[48:49] op_sel_hi:[1,1,0]
	v_exp_f32_e32 v14, v14
	v_exp_f32_e32 v15, v15
	v_pk_fma_f32 v[12:13], v[26:27], v[12:13], s[50:51] op_sel_hi:[1,1,0]
	v_pk_fma_f32 v[12:13], v[26:27], v[12:13], s[56:57] op_sel_hi:[1,1,0]
	v_lshlrev_b32_e32 v32, 16, v52
	v_pk_mul_f32 v[12:13], v[26:27], v[12:13]
	v_and_b32_e32 v33, 0xffff0000, v52
	v_pk_mul_f32 v[12:13], v[14:15], v[12:13]
	v_max_f32_e32 v110, 0, v24
	v_fma_f32 v27, -|v24|, v12, v110
	v_max_f32_e32 v111, 0, v25
	v_fma_f32 v13, -|v25|, v13, v111
	v_pk_mul_f32 v[24:25], v[28:29], v[28:29]
	v_fma_f32 v34, |v32|, s40, 1.0
	v_fma_f32 v35, |v33|, s40, 1.0
	v_pk_fma_f32 v[14:15], v[30:31], s[42:43], v[18:19] op_sel_hi:[1,0,0]
	v_pk_mul_f32 v[24:25], v[24:25], s[64:65] op_sel_hi:[1,0]
	v_pk_fma_f32 v[14:15], v[30:31], v[14:15], s[48:49] op_sel_hi:[1,1,0]
	v_exp_f32_e32 v24, v24
	v_exp_f32_e32 v25, v25
	v_pk_fma_f32 v[14:15], v[30:31], v[14:15], s[50:51] op_sel_hi:[1,1,0]
	v_rcp_f32_e32 v34, v34
	v_pk_fma_f32 v[14:15], v[30:31], v[14:15], s[56:57] op_sel_hi:[1,1,0]
	v_rcp_f32_e32 v35, v35
	v_pk_mul_f32 v[14:15], v[30:31], v[14:15]
	v_pk_mul_f32 v[14:15], v[24:25], v[14:15]
	v_lshlrev_b32_e32 v36, 16, v53
	v_max_f32_e32 v112, 0, v28
	v_fma_f32 v31, -|v28|, v14, v112
	v_max_f32_e32 v113, 0, v29
	v_fma_f32 v15, -|v29|, v15, v113
	v_and_b32_e32 v37, 0xffff0000, v53
	v_pk_mul_f32 v[28:29], v[32:33], v[32:33]
	v_pk_fma_f32 v[24:25], v[34:35], s[42:43], v[18:19] op_sel_hi:[1,0,0]
	v_pk_mul_f32 v[28:29], v[28:29], s[64:65] op_sel_hi:[1,0]
	v_pk_fma_f32 v[24:25], v[34:35], v[24:25], s[48:49] op_sel_hi:[1,1,0]
	v_exp_f32_e32 v28, v28
	v_exp_f32_e32 v29, v29
	v_pk_fma_f32 v[24:25], v[34:35], v[24:25], s[50:51] op_sel_hi:[1,1,0]
	v_pk_fma_f32 v[24:25], v[34:35], v[24:25], s[56:57] op_sel_hi:[1,1,0]
	v_fma_f32 v38, |v36|, s40, 1.0
	v_fma_f32 v39, |v37|, s40, 1.0
	v_pk_mul_f32 v[24:25], v[34:35], v[24:25]
	v_rcp_f32_e32 v38, v38
	v_pk_mul_f32 v[24:25], v[28:29], v[24:25]
	v_rcp_f32_e32 v39, v39
	v_max_f32_e32 v114, 0, v32
	v_fma_f32 v35, -|v32|, v24, v114
	v_max_f32_e32 v115, 0, v33
	v_fma_f32 v25, -|v33|, v25, v115
	v_pk_fma_f32 v[18:19], v[38:39], s[42:43], v[18:19] op_sel_hi:[1,0,0]
	v_mul_f32_e32 v20, v21, v21
	v_pk_fma_f32 v[18:19], v[38:39], v[18:19], s[48:49] op_sel_hi:[1,1,0]
	v_mul_f32_e32 v10, v11, v11
	v_pk_mul_f32 v[28:29], v[36:37], v[36:37]
	v_pk_fma_f32 v[18:19], v[38:39], v[18:19], s[50:51] op_sel_hi:[1,1,0]
	v_pk_mul_f32 v[28:29], v[28:29], s[64:65] op_sel_hi:[1,0]
	v_pk_fma_f32 v[18:19], v[38:39], v[18:19], s[56:57] op_sel_hi:[1,1,0]
	v_exp_f32_e32 v28, v28
	v_exp_f32_e32 v29, v29
	v_pk_mul_f32 v[18:19], v[38:39], v[18:19]
	v_mul_f32_e32 v22, v23, v23
	v_mul_f32_e32 v6, v7, v7
	v_pk_mul_f32 v[18:19], v[28:29], v[18:19]
	v_pk_add_f32 v[4:5], v[4:5], v[8:9]
	v_pk_add_f32 v[8:9], v[20:21], v[10:11]
	v_mul_f32_e32 v26, v27, v27
	v_mul_f32_e32 v12, v13, v13
	v_max_f32_e32 v116, 0, v36
	v_fma_f32 v33, -|v36|, v18, v116
	v_max_f32_e32 v117, 0, v37
	v_fma_f32 v19, -|v37|, v19, v117
	v_pk_add_f32 v[4:5], v[8:9], v[4:5]
	v_pk_add_f32 v[6:7], v[22:23], v[6:7]
	v_mul_f32_e32 v30, v31, v31
	v_mul_f32_e32 v14, v15, v15
	v_pk_add_f32 v[4:5], v[6:7], v[4:5]
	v_pk_add_f32 v[6:7], v[26:27], v[12:13]
	v_mul_f32_e32 v34, v35, v35
	v_mul_f32_e32 v24, v25, v25
	v_pk_add_f32 v[4:5], v[6:7], v[4:5]
	v_pk_add_f32 v[6:7], v[30:31], v[14:15]
	v_mul_f32_e32 v32, v33, v33
	v_mul_f32_e32 v18, v19, v19
	v_pk_add_f32 v[4:5], v[6:7], v[4:5]
	v_pk_add_f32 v[6:7], v[34:35], v[24:25]
	s_nop 0
	v_pk_add_f32 v[4:5], v[6:7], v[4:5]
	v_pk_add_f32 v[6:7], v[32:33], v[18:19]
	s_nop 0
	v_pk_add_f32 v[4:5], v[6:7], v[4:5]
	ds_bpermute_b32 v7, v56, v5
	ds_bpermute_b32 v6, v56, v4
	s_waitcnt lgkmcnt(0)
	v_pk_add_f32 v[4:5], v[4:5], v[6:7]
	ds_bpermute_b32 v7, v57, v5
	ds_bpermute_b32 v6, v57, v4
	s_waitcnt lgkmcnt(0)
	v_pk_add_f32 v[4:5], v[4:5], v[6:7]
	ds_bpermute_b32 v7, v58, v5
	ds_bpermute_b32 v6, v58, v4
	s_waitcnt lgkmcnt(0)
	v_pk_add_f32 v[4:5], v[4:5], v[6:7]
	ds_bpermute_b32 v7, v59, v5
	ds_bpermute_b32 v6, v59, v4
	s_and_saveexec_b64 s[0:1], vcc
	s_cbranch_execz .LBB0_451
	s_waitcnt lgkmcnt(0)
	v_pk_add_f32 v[4:5], v[4:5], v[6:7]
	s_nop 0
	v_pk_mul_f32 v[4:5], v[4:5], s[66:67] op_sel_hi:[1,0]
	s_nop 0
	v_fma_f32 v4, -v5, v5, v4
	v_max_f32_e32 v4, 0, v4
	v_add_f32_e32 v4, 0x358637bd, v4
	v_mul_f32_e32 v6, 0x4b800000, v4
	v_cmp_gt_f32_e32 vcc, s36, v4
	s_nop 1
	v_cndmask_b32_e32 v4, v4, v6, vcc
	v_rsq_f32_e32 v4, v4
	v_lshl_add_u32 v6, v16, 2, 0
	v_add_u32_e32 v7, 0x11000, v6
	ds_write_b32 v7, v5
	v_mul_f32_e32 v5, 0x45800000, v4
	v_cndmask_b32_e32 v4, v4, v5, vcc
	v_add_u32_e32 v5, 0x11200, v6
	ds_write_b32 v5, v4

.LBB0_452:
	s_waitcnt vmcnt(15)
	v_lshlrev_b32_e32 v8, 16, v36
	v_and_b32_e32 v9, 0xffff0000, v36
	v_fma_f32 v10, |v8|, s40, 1.0
	v_fma_f32 v11, |v9|, s40, 1.0
	v_mov_b64_e32 v[12:13], s[44:45]
	v_rcp_f32_e32 v10, v10
	v_rcp_f32_e32 v11, v11
	v_pk_mul_f32 v[16:17], v[8:9], v[8:9]
	v_pk_mul_f32 v[16:17], v[16:17], s[64:65] op_sel_hi:[1,0]
	v_pk_fma_f32 v[14:15], v[10:11], s[42:43], v[12:13] op_sel_hi:[1,0,0]
	v_exp_f32_e32 v16, v16
	v_pk_fma_f32 v[14:15], v[10:11], v[14:15], s[48:49] op_sel_hi:[1,1,0]
	v_exp_f32_e32 v17, v17
	v_pk_fma_f32 v[14:15], v[10:11], v[14:15], s[50:51] op_sel_hi:[1,1,0]
	v_add_f32_e32 v4, v72, v4
	v_pk_fma_f32 v[14:15], v[10:11], v[14:15], s[56:57] op_sel_hi:[1,1,0]
	s_mov_b32 s0, 0x1506e000
	v_pk_mul_f32 v[10:11], v[10:11], v[14:15]
	s_add_u32 s70, s70, 0x400
	v_pk_mul_f32 v[10:11], v[16:17], v[10:11]
	v_lshlrev_b32_e32 v16, 16, v37
	v_and_b32_e32 v17, 0xffff0000, v37
	v_fma_f32 v18, |v16|, s40, 1.0
	v_fma_f32 v19, |v17|, s40, 1.0
	v_rcp_f32_e32 v18, v18
	v_rcp_f32_e32 v19, v19
	v_max_f32_e32 v80, 0, v8
	v_fma_f32 v3, -|v8|, v10, v80
	v_max_f32_e32 v81, 0, v9
	v_fma_f32 v14, -|v9|, v11, v81
	s_addc_u32 s71, s71, 0
	v_pk_fma_f32 v[8:9], v[18:19], s[42:43], v[12:13] op_sel_hi:[1,0,0]
	v_mul_f32_e32 v3, v3, v4
	v_pk_mul_f32 v[10:11], v[16:17], v[16:17]
	v_pk_fma_f32 v[8:9], v[18:19], v[8:9], s[48:49] op_sel_hi:[1,1,0]
	v_pk_mul_f32 v[10:11], v[10:11], s[64:65] op_sel_hi:[1,0]
	v_pk_fma_f32 v[8:9], v[18:19], v[8:9], s[50:51] op_sel_hi:[1,1,0]
	v_exp_f32_e32 v10, v10
	v_exp_f32_e32 v11, v11
	v_pk_fma_f32 v[8:9], v[18:19], v[8:9], s[56:57] op_sel_hi:[1,1,0]
	v_cmp_gt_f32_e32 vcc, 0, v16
	v_pk_mul_f32 v[8:9], v[18:19], v[8:9]
	v_add_f32_e32 v4, v72, v5
	v_pk_mul_f32 v[8:9], v[10:11], v[8:9]
	v_mul_f32_e32 v4, v14, v4
	v_pk_mul_f32 v[10:11], v[16:17], v[8:9]
	v_pk_fma_f32 v[8:9], v[16:17], v[8:9], v[16:17] neg_lo:[1,0,0] neg_hi:[1,0,0]
	v_cvt_pk_bf16_f32 v4, v3, v4
	v_add_f32_e32 v3, v72, v6
	v_cndmask_b32_e32 v8, v8, v10, vcc
	v_cmp_gt_f32_e32 vcc, 0, v17
	v_add_f32_e32 v5, v72, v7
	v_lshl_add_u64 v[26:27], v[26:27], 0, s[68:69]
	v_cndmask_b32_e32 v9, v9, v11, vcc
	v_add_co_u32_e32 v6, vcc, s0, v34
	s_mov_b64 s[0:1], 0x8000
	v_mul_f32_e32 v5, v9, v5
	v_addc_co_u32_e32 v7, vcc, 0, v35, vcc
	v_lshl_add_u64 v[28:29], v[28:29], 0, s[0:1]
	v_lshl_add_u64 v[30:31], v[30:31], 0, s[68:69]
	s_cmpk_eq_i32 s70, 0x1000
	v_lshl_add_u64 v[32:33], v[32:33], 0, s[68:69]
	v_mul_f32_e32 v3, v8, v3
	v_cvt_pk_bf16_f32 v5, v3, v5
	global_store_dwordx2 v[6:7], v[4:5], off offset:480
	s_barrier
	s_cbranch_scc1 .LBB0_410
.LBB0_453:
	v_lshl_add_u64 v[4:5], s[12:13], 0, v[32:33]
	v_add_co_u32_e32 v18, vcc, 0x696e000, v4
	s_add_u32 s0, s16, s70
	s_nop 0
	v_addc_co_u32_e32 v19, vcc, 0, v5, vcc
	global_load_dwordx4 v[8:11], v[18:19], off
	global_load_dwordx4 v[4:7], v[18:19], off offset:2048
	s_addc_u32 s1, s38, s71
	s_add_u32 s4, s88, s70
	s_addc_u32 s5, s89, s71
	global_load_dwordx2 v[20:21], v2, s[0:1]
	global_load_dwordx2 v[22:23], v2, s[4:5]
	v_mov_b64_e32 v[16:17], s[44:45]
	ds_read_b64 v[14:15], v68
	ds_read_b64 v[12:13], v69
	s_waitcnt vmcnt(3)
	v_lshlrev_b32_e32 v24, 16, v8
	v_and_b32_e32 v25, 0xffff0000, v8
	s_waitcnt vmcnt(2)
	v_lshlrev_b32_e32 v34, 16, v4
	v_and_b32_e32 v35, 0xffff0000, v4
	v_fma_f32 v36, |v24|, s40, 1.0
	v_fma_f32 v37, |v25|, s40, 1.0
	v_fma_f32 v40, |v34|, s40, 1.0
	v_fma_f32 v41, |v35|, s40, 1.0
	v_rcp_f32_e32 v36, v36
	v_rcp_f32_e32 v37, v37
	v_rcp_f32_e32 v40, v40
	v_rcp_f32_e32 v41, v41
	v_pk_mul_f32 v[38:39], v[24:25], v[24:25]
	v_pk_mul_f32 v[42:43], v[34:35], v[34:35]
	v_pk_mul_f32 v[38:39], v[38:39], s[64:65] op_sel_hi:[1,0]
	v_pk_fma_f32 v[44:45], v[36:37], s[42:43], v[16:17] op_sel_hi:[1,0,0]
	v_pk_mul_f32 v[42:43], v[42:43], s[64:65] op_sel_hi:[1,0]
	v_exp_f32_e32 v38, v38
	v_exp_f32_e32 v39, v39
	v_pk_fma_f32 v[46:47], v[40:41], s[42:43], v[16:17] op_sel_hi:[1,0,0]
	v_pk_fma_f32 v[44:45], v[36:37], v[44:45], s[48:49] op_sel_hi:[1,1,0]
	v_exp_f32_e32 v42, v42
	v_exp_f32_e32 v43, v43
	v_pk_fma_f32 v[46:47], v[40:41], v[46:47], s[48:49] op_sel_hi:[1,1,0]
	v_pk_fma_f32 v[44:45], v[36:37], v[44:45], s[50:51] op_sel_hi:[1,1,0]
	v_pk_fma_f32 v[46:47], v[40:41], v[46:47], s[50:51] op_sel_hi:[1,1,0]
	v_pk_fma_f32 v[44:45], v[36:37], v[44:45], s[56:57] op_sel_hi:[1,1,0]
	v_pk_fma_f32 v[46:47], v[40:41], v[46:47], s[56:57] op_sel_hi:[1,1,0]
	v_pk_mul_f32 v[36:37], v[36:37], v[44:45]
	v_pk_mul_f32 v[40:41], v[40:41], v[46:47]
	v_pk_mul_f32 v[36:37], v[38:39], v[36:37]
	v_pk_mul_f32 v[38:39], v[42:43], v[40:41]
	v_max_f32_e32 v82, 0, v24
	v_fma_f32 v3, -|v24|, v36, v82
	v_max_f32_e32 v83, 0, v25
	s_waitcnt lgkmcnt(1)
	v_sub_f32_e32 v3, v3, v14
	s_waitcnt lgkmcnt(0)
	v_mul_f32_e32 v3, v12, v3
	v_fma_f32 v4, -|v25|, v37, v83
	v_max_f32_e32 v84, 0, v34
	v_sub_f32_e32 v4, v4, v14
	v_mul_f32_e32 v4, v12, v4
	v_fma_f32 v8, -|v34|, v38, v84
	v_max_f32_e32 v85, 0, v35
	v_sub_f32_e32 v8, v8, v15
	v_mul_f32_e32 v8, v13, v8
	v_fma_f32 v24, -|v35|, v39, v85
	v_sub_f32_e32 v24, v24, v15
	v_mul_f32_e32 v24, v13, v24
	s_waitcnt vmcnt(0)
	v_fma_f32 v3, v20, v3, v22
	v_fma_f32 v4, v21, v4, v23
	v_fma_f32 v8, v20, v8, v22
	v_fmac_f32_e32 v23, v21, v24
	v_cvt_pk_bf16_f32 v3, v3, v8
	ds_write_b32 v70, v3
	v_cvt_pk_bf16_f32 v3, v4, v23
	global_load_dwordx2 v[22:23], v2, s[0:1] offset:8
	global_load_dwordx2 v[20:21], v2, s[4:5] offset:8
	v_lshlrev_b32_e32 v8, 16, v9
	v_and_b32_e32 v9, 0xffff0000, v9
	v_lshlrev_b32_e32 v4, 16, v5
	v_and_b32_e32 v5, 0xffff0000, v5
	v_fma_f32 v24, |v8|, s40, 1.0
	v_fma_f32 v25, |v9|, s40, 1.0
	v_fma_f32 v36, |v4|, s40, 1.0
	v_fma_f32 v37, |v5|, s40, 1.0
	v_rcp_f32_e32 v24, v24
	v_rcp_f32_e32 v25, v25
	v_rcp_f32_e32 v36, v36
	v_rcp_f32_e32 v37, v37
	v_pk_mul_f32 v[34:35], v[8:9], v[8:9]
	v_pk_mul_f32 v[38:39], v[4:5], v[4:5]
	v_pk_mul_f32 v[34:35], v[34:35], s[64:65] op_sel_hi:[1,0]
	v_pk_fma_f32 v[40:41], v[24:25], s[42:43], v[16:17] op_sel_hi:[1,0,0]
	v_pk_mul_f32 v[38:39], v[38:39], s[64:65] op_sel_hi:[1,0]
	v_exp_f32_e32 v34, v34
	v_exp_f32_e32 v35, v35
	v_pk_fma_f32 v[42:43], v[36:37], s[42:43], v[16:17] op_sel_hi:[1,0,0]
	v_pk_fma_f32 v[40:41], v[24:25], v[40:41], s[48:49] op_sel_hi:[1,1,0]
	v_exp_f32_e32 v38, v38
	v_exp_f32_e32 v39, v39
	v_pk_fma_f32 v[42:43], v[36:37], v[42:43], s[48:49] op_sel_hi:[1,1,0]
	v_pk_fma_f32 v[40:41], v[24:25], v[40:41], s[50:51] op_sel_hi:[1,1,0]
	v_pk_fma_f32 v[42:43], v[36:37], v[42:43], s[50:51] op_sel_hi:[1,1,0]
	v_pk_fma_f32 v[40:41], v[24:25], v[40:41], s[56:57] op_sel_hi:[1,1,0]
	v_pk_fma_f32 v[42:43], v[36:37], v[42:43], s[56:57] op_sel_hi:[1,1,0]
	v_pk_mul_f32 v[24:25], v[24:25], v[40:41]
	v_pk_mul_f32 v[36:37], v[36:37], v[42:43]
	v_pk_mul_f32 v[24:25], v[34:35], v[24:25]
	v_pk_mul_f32 v[34:35], v[38:39], v[36:37]
	v_max_f32_e32 v86, 0, v8
	v_fma_f32 v8, -|v8|, v24, v86
	v_max_f32_e32 v90, 0, v9
	v_fma_f32 v9, -|v9|, v25, v90
	v_max_f32_e32 v91, 0, v4
	v_fma_f32 v4, -|v4|, v34, v91
	v_max_f32_e32 v92, 0, v5
	v_fma_f32 v5, -|v5|, v35, v92
	v_sub_f32_e32 v8, v8, v14
	v_mul_f32_e32 v8, v12, v8
	v_sub_f32_e32 v9, v9, v14
	v_mul_f32_e32 v9, v12, v9
	v_sub_f32_e32 v4, v4, v15
	v_mul_f32_e32 v4, v13, v4
	v_sub_f32_e32 v5, v5, v15
	ds_write_b32 v70, v3 offset:272
	v_mul_f32_e32 v5, v13, v5
	s_waitcnt vmcnt(0)
	v_fma_f32 v3, v22, v8, v20
	v_fma_f32 v8, v23, v9, v21
	v_fma_f32 v4, v22, v4, v20
	v_cvt_pk_bf16_f32 v3, v3, v4
	v_fmac_f32_e32 v21, v23, v5
	ds_write_b32 v70, v3 offset:544
	v_cvt_pk_bf16_f32 v3, v8, v21
	global_load_dwordx2 v[8:9], v2, s[0:1] offset:16
	global_load_dwordx2 v[4:5], v2, s[4:5] offset:16
	v_lshlrev_b32_e32 v20, 16, v10
	v_and_b32_e32 v21, 0xffff0000, v10
	v_lshlrev_b32_e32 v22, 16, v6
	v_and_b32_e32 v23, 0xffff0000, v6
	v_fma_f32 v24, |v20|, s40, 1.0
	v_fma_f32 v25, |v21|, s40, 1.0
	v_fma_f32 v36, |v22|, s40, 1.0
	v_fma_f32 v37, |v23|, s40, 1.0
	v_rcp_f32_e32 v24, v24
	v_rcp_f32_e32 v25, v25
	v_rcp_f32_e32 v36, v36
	v_rcp_f32_e32 v37, v37
	v_pk_mul_f32 v[34:35], v[20:21], v[20:21]
	v_pk_mul_f32 v[38:39], v[22:23], v[22:23]
	v_pk_mul_f32 v[34:35], v[34:35], s[64:65] op_sel_hi:[1,0]
	v_pk_fma_f32 v[40:41], v[24:25], s[42:43], v[16:17] op_sel_hi:[1,0,0]
	v_pk_mul_f32 v[38:39], v[38:39], s[64:65] op_sel_hi:[1,0]
	v_exp_f32_e32 v34, v34
	v_exp_f32_e32 v35, v35
	v_pk_fma_f32 v[42:43], v[36:37], s[42:43], v[16:17] op_sel_hi:[1,0,0]
	v_pk_fma_f32 v[40:41], v[24:25], v[40:41], s[48:49] op_sel_hi:[1,1,0]
	v_exp_f32_e32 v38, v38
	v_exp_f32_e32 v39, v39
	v_pk_fma_f32 v[42:43], v[36:37], v[42:43], s[48:49] op_sel_hi:[1,1,0]
	v_pk_fma_f32 v[40:41], v[24:25], v[40:41], s[50:51] op_sel_hi:[1,1,0]
	v_pk_fma_f32 v[42:43], v[36:37], v[42:43], s[50:51] op_sel_hi:[1,1,0]
	v_pk_fma_f32 v[40:41], v[24:25], v[40:41], s[56:57] op_sel_hi:[1,1,0]
	v_pk_fma_f32 v[42:43], v[36:37], v[42:43], s[56:57] op_sel_hi:[1,1,0]
	v_pk_mul_f32 v[24:25], v[24:25], v[40:41]
	v_pk_mul_f32 v[36:37], v[36:37], v[42:43]
	v_pk_mul_f32 v[24:25], v[34:35], v[24:25]
	v_pk_mul_f32 v[34:35], v[38:39], v[36:37]
	v_max_f32_e32 v93, 0, v20
	v_fma_f32 v6, -|v20|, v24, v93
	v_max_f32_e32 v94, 0, v21
	v_fma_f32 v10, -|v21|, v25, v94
	v_max_f32_e32 v95, 0, v22
	v_fma_f32 v20, -|v22|, v34, v95
	v_max_f32_e32 v96, 0, v23
	v_fma_f32 v21, -|v23|, v35, v96
	v_sub_f32_e32 v6, v6, v14
	v_mul_f32_e32 v6, v12, v6
	v_sub_f32_e32 v10, v10, v14
	v_mul_f32_e32 v10, v12, v10
	v_sub_f32_e32 v20, v20, v15
	v_mul_f32_e32 v20, v13, v20
	v_sub_f32_e32 v21, v21, v15
	v_mul_f32_e32 v21, v13, v21
	ds_write_b32 v70, v3 offset:816
	s_waitcnt vmcnt(0)
	v_fma_f32 v3, v8, v6, v4
	v_fma_f32 v6, v9, v10, v5
	v_fma_f32 v4, v8, v20, v4
	v_fmac_f32_e32 v5, v9, v21
	v_cvt_pk_bf16_f32 v3, v3, v4
	ds_write_b32 v70, v3 offset:1088
	v_cvt_pk_bf16_f32 v3, v6, v5
	global_load_dwordx2 v[8:9], v2, s[0:1] offset:24
	global_load_dwordx2 v[4:5], v2, s[4:5] offset:24
	v_lshlrev_b32_e32 v10, 16, v11
	v_and_b32_e32 v11, 0xffff0000, v11
	v_lshlrev_b32_e32 v6, 16, v7
	v_and_b32_e32 v7, 0xffff0000, v7
	v_fma_f32 v20, |v10|, s40, 1.0
	v_fma_f32 v21, |v11|, s40, 1.0
	v_fma_f32 v24, |v6|, s40, 1.0
	v_fma_f32 v25, |v7|, s40, 1.0
	v_rcp_f32_e32 v20, v20
	v_rcp_f32_e32 v21, v21
	v_rcp_f32_e32 v24, v24
	v_rcp_f32_e32 v25, v25
	v_pk_mul_f32 v[22:23], v[10:11], v[10:11]
	v_pk_mul_f32 v[34:35], v[6:7], v[6:7]
	v_pk_mul_f32 v[22:23], v[22:23], s[64:65] op_sel_hi:[1,0]
	v_pk_fma_f32 v[36:37], v[20:21], s[42:43], v[16:17] op_sel_hi:[1,0,0]
	v_pk_mul_f32 v[34:35], v[34:35], s[64:65] op_sel_hi:[1,0]
	v_exp_f32_e32 v22, v22
	v_exp_f32_e32 v23, v23
	v_pk_fma_f32 v[38:39], v[24:25], s[42:43], v[16:17] op_sel_hi:[1,0,0]
	v_pk_fma_f32 v[36:37], v[20:21], v[36:37], s[48:49] op_sel_hi:[1,1,0]
	v_exp_f32_e32 v34, v34
	v_exp_f32_e32 v35, v35
	v_pk_fma_f32 v[38:39], v[24:25], v[38:39], s[48:49] op_sel_hi:[1,1,0]
	v_pk_fma_f32 v[36:37], v[20:21], v[36:37], s[50:51] op_sel_hi:[1,1,0]
	v_pk_fma_f32 v[38:39], v[24:25], v[38:39], s[50:51] op_sel_hi:[1,1,0]
	v_pk_fma_f32 v[36:37], v[20:21], v[36:37], s[56:57] op_sel_hi:[1,1,0]
	v_pk_fma_f32 v[38:39], v[24:25], v[38:39], s[56:57] op_sel_hi:[1,1,0]
	v_pk_mul_f32 v[20:21], v[20:21], v[36:37]
	v_pk_mul_f32 v[24:25], v[24:25], v[38:39]
	v_pk_mul_f32 v[20:21], v[22:23], v[20:21]
	v_pk_mul_f32 v[22:23], v[34:35], v[24:25]
	v_max_f32_e32 v97, 0, v10
	v_fma_f32 v10, -|v10|, v20, v97
	v_max_f32_e32 v98, 0, v11
	v_fma_f32 v11, -|v11|, v21, v98
	v_max_f32_e32 v99, 0, v6
	v_fma_f32 v6, -|v6|, v22, v99
	v_max_f32_e32 v100, 0, v7
	v_fma_f32 v7, -|v7|, v23, v100
	v_sub_f32_e32 v10, v10, v14
	v_mul_f32_e32 v10, v12, v10
	v_sub_f32_e32 v11, v11, v14
	v_mul_f32_e32 v11, v12, v11
	v_sub_f32_e32 v6, v6, v15
	v_mul_f32_e32 v6, v13, v6
	v_sub_f32_e32 v7, v7, v15
	v_mul_f32_e32 v7, v13, v7
	ds_write_b32 v70, v3 offset:1360
	s_waitcnt vmcnt(0)
	v_fma_f32 v3, v8, v10, v4
	v_fma_f32 v10, v9, v11, v5
	v_fma_f32 v4, v8, v6, v4
	v_fmac_f32_e32 v5, v9, v7
	v_cvt_pk_bf16_f32 v3, v3, v4
	ds_write_b32 v70, v3 offset:1632
	v_cvt_pk_bf16_f32 v3, v10, v5
	global_load_dwordx4 v[8:11], v[18:19], off offset:16
	global_load_dwordx4 v[4:7], v[18:19], off offset:2064
	global_load_dwordx2 v[22:23], v2, s[0:1] offset:32
	global_load_dwordx2 v[20:21], v2, s[4:5] offset:32
	ds_write_b32 v70, v3 offset:1904
	s_waitcnt vmcnt(3)
	v_lshlrev_b32_e32 v24, 16, v8
	v_and_b32_e32 v25, 0xffff0000, v8
	s_waitcnt vmcnt(2)
	v_lshlrev_b32_e32 v34, 16, v4
	v_and_b32_e32 v35, 0xffff0000, v4
	v_fma_f32 v36, |v24|, s40, 1.0
	v_fma_f32 v37, |v25|, s40, 1.0
	v_fma_f32 v40, |v34|, s40, 1.0
	v_fma_f32 v41, |v35|, s40, 1.0
	v_rcp_f32_e32 v36, v36
	v_rcp_f32_e32 v37, v37
	v_rcp_f32_e32 v40, v40
	v_rcp_f32_e32 v41, v41
	v_pk_mul_f32 v[38:39], v[24:25], v[24:25]
	v_pk_mul_f32 v[42:43], v[34:35], v[34:35]
	v_pk_mul_f32 v[38:39], v[38:39], s[64:65] op_sel_hi:[1,0]
	v_pk_fma_f32 v[44:45], v[36:37], s[42:43], v[16:17] op_sel_hi:[1,0,0]
	v_pk_mul_f32 v[42:43], v[42:43], s[64:65] op_sel_hi:[1,0]
	v_exp_f32_e32 v38, v38
	v_exp_f32_e32 v39, v39
	v_pk_fma_f32 v[46:47], v[40:41], s[42:43], v[16:17] op_sel_hi:[1,0,0]
	v_pk_fma_f32 v[44:45], v[36:37], v[44:45], s[48:49] op_sel_hi:[1,1,0]
	v_exp_f32_e32 v42, v42
	v_exp_f32_e32 v43, v43
	v_pk_fma_f32 v[46:47], v[40:41], v[46:47], s[48:49] op_sel_hi:[1,1,0]
	v_pk_fma_f32 v[44:45], v[36:37], v[44:45], s[50:51] op_sel_hi:[1,1,0]
	v_pk_fma_f32 v[46:47], v[40:41], v[46:47], s[50:51] op_sel_hi:[1,1,0]
	v_pk_fma_f32 v[44:45], v[36:37], v[44:45], s[56:57] op_sel_hi:[1,1,0]
	v_pk_fma_f32 v[46:47], v[40:41], v[46:47], s[56:57] op_sel_hi:[1,1,0]
	v_pk_mul_f32 v[36:37], v[36:37], v[44:45]
	v_pk_mul_f32 v[40:41], v[40:41], v[46:47]
	v_pk_mul_f32 v[36:37], v[38:39], v[36:37]
	v_pk_mul_f32 v[38:39], v[42:43], v[40:41]
	v_max_f32_e32 v104, 0, v24
	v_fma_f32 v3, -|v24|, v36, v104
	v_max_f32_e32 v105, 0, v25
	v_fma_f32 v4, -|v25|, v37, v105
	v_max_f32_e32 v106, 0, v34
	v_fma_f32 v8, -|v34|, v38, v106
	v_max_f32_e32 v107, 0, v35
	v_fma_f32 v24, -|v35|, v39, v107
	v_sub_f32_e32 v3, v3, v14
	v_mul_f32_e32 v3, v12, v3
	v_sub_f32_e32 v4, v4, v14
	v_mul_f32_e32 v4, v12, v4
	v_sub_f32_e32 v8, v8, v15
	v_mul_f32_e32 v8, v13, v8
	v_sub_f32_e32 v24, v24, v15
	v_mul_f32_e32 v24, v13, v24
	s_waitcnt vmcnt(0)
	v_fma_f32 v3, v22, v3, v20
	v_fma_f32 v4, v23, v4, v21
	v_fma_f32 v8, v22, v8, v20
	v_fmac_f32_e32 v21, v23, v24
	v_cvt_pk_bf16_f32 v3, v3, v8
	ds_write_b32 v70, v3 offset:2176
	v_cvt_pk_bf16_f32 v3, v4, v21
	global_load_dwordx2 v[22:23], v2, s[0:1] offset:40
	global_load_dwordx2 v[20:21], v2, s[4:5] offset:40
	v_lshlrev_b32_e32 v8, 16, v9
	v_and_b32_e32 v9, 0xffff0000, v9
	v_lshlrev_b32_e32 v4, 16, v5
	v_and_b32_e32 v5, 0xffff0000, v5
	v_fma_f32 v24, |v8|, s40, 1.0
	v_fma_f32 v25, |v9|, s40, 1.0
	v_fma_f32 v36, |v4|, s40, 1.0
	v_fma_f32 v37, |v5|, s40, 1.0
	v_rcp_f32_e32 v24, v24
	v_rcp_f32_e32 v25, v25
	v_rcp_f32_e32 v36, v36
	v_rcp_f32_e32 v37, v37
	v_pk_mul_f32 v[34:35], v[8:9], v[8:9]
	v_pk_mul_f32 v[38:39], v[4:5], v[4:5]
	v_pk_mul_f32 v[34:35], v[34:35], s[64:65] op_sel_hi:[1,0]
	v_pk_fma_f32 v[40:41], v[24:25], s[42:43], v[16:17] op_sel_hi:[1,0,0]
	v_pk_mul_f32 v[38:39], v[38:39], s[64:65] op_sel_hi:[1,0]
	v_exp_f32_e32 v34, v34
	v_exp_f32_e32 v35, v35
	v_pk_fma_f32 v[42:43], v[36:37], s[42:43], v[16:17] op_sel_hi:[1,0,0]
	v_pk_fma_f32 v[40:41], v[24:25], v[40:41], s[48:49] op_sel_hi:[1,1,0]
	v_exp_f32_e32 v38, v38
	v_exp_f32_e32 v39, v39
	v_pk_fma_f32 v[42:43], v[36:37], v[42:43], s[48:49] op_sel_hi:[1,1,0]
	v_pk_fma_f32 v[40:41], v[24:25], v[40:41], s[50:51] op_sel_hi:[1,1,0]
	v_pk_fma_f32 v[42:43], v[36:37], v[42:43], s[50:51] op_sel_hi:[1,1,0]
	v_pk_fma_f32 v[40:41], v[24:25], v[40:41], s[56:57] op_sel_hi:[1,1,0]
	v_pk_fma_f32 v[42:43], v[36:37], v[42:43], s[56:57] op_sel_hi:[1,1,0]
	v_pk_mul_f32 v[24:25], v[24:25], v[40:41]
	v_pk_mul_f32 v[36:37], v[36:37], v[42:43]
	v_pk_mul_f32 v[24:25], v[34:35], v[24:25]
	v_pk_mul_f32 v[34:35], v[38:39], v[36:37]
	v_max_f32_e32 v108, 0, v8
	v_fma_f32 v8, -|v8|, v24, v108
	v_max_f32_e32 v109, 0, v9
	v_fma_f32 v9, -|v9|, v25, v109
	v_max_f32_e32 v110, 0, v4
	v_fma_f32 v4, -|v4|, v34, v110
	v_max_f32_e32 v111, 0, v5
	v_fma_f32 v5, -|v5|, v35, v111
	v_sub_f32_e32 v8, v8, v14
	v_mul_f32_e32 v8, v12, v8
	v_sub_f32_e32 v9, v9, v14
	v_mul_f32_e32 v9, v12, v9
	v_sub_f32_e32 v4, v4, v15
	v_mul_f32_e32 v4, v13, v4
	v_sub_f32_e32 v5, v5, v15
	ds_write_b32 v70, v3 offset:2448
	v_mul_f32_e32 v5, v13, v5
	s_waitcnt vmcnt(0)
	v_fma_f32 v3, v22, v8, v20
	v_fma_f32 v8, v23, v9, v21
	v_fma_f32 v4, v22, v4, v20
	v_cvt_pk_bf16_f32 v3, v3, v4
	v_fmac_f32_e32 v21, v23, v5
	ds_write_b32 v70, v3 offset:2720
	v_cvt_pk_bf16_f32 v3, v8, v21
	global_load_dwordx2 v[8:9], v2, s[0:1] offset:48
	global_load_dwordx2 v[4:5], v2, s[4:5] offset:48
	v_lshlrev_b32_e32 v20, 16, v10
	v_and_b32_e32 v21, 0xffff0000, v10
	v_lshlrev_b32_e32 v22, 16, v6
	v_and_b32_e32 v23, 0xffff0000, v6
	v_fma_f32 v24, |v20|, s40, 1.0
	v_fma_f32 v25, |v21|, s40, 1.0
	v_fma_f32 v36, |v22|, s40, 1.0
	v_fma_f32 v37, |v23|, s40, 1.0
	v_rcp_f32_e32 v24, v24
	v_rcp_f32_e32 v25, v25
	v_rcp_f32_e32 v36, v36
	v_rcp_f32_e32 v37, v37
	v_pk_mul_f32 v[34:35], v[20:21], v[20:21]
	v_pk_mul_f32 v[38:39], v[22:23], v[22:23]
	v_pk_mul_f32 v[34:35], v[34:35], s[64:65] op_sel_hi:[1,0]
	v_pk_fma_f32 v[40:41], v[24:25], s[42:43], v[16:17] op_sel_hi:[1,0,0]
	v_pk_mul_f32 v[38:39], v[38:39], s[64:65] op_sel_hi:[1,0]
	v_exp_f32_e32 v34, v34
	v_exp_f32_e32 v35, v35
	v_pk_fma_f32 v[42:43], v[36:37], s[42:43], v[16:17] op_sel_hi:[1,0,0]
	v_pk_fma_f32 v[40:41], v[24:25], v[40:41], s[48:49] op_sel_hi:[1,1,0]
	v_exp_f32_e32 v38, v38
	v_exp_f32_e32 v39, v39
	v_pk_fma_f32 v[42:43], v[36:37], v[42:43], s[48:49] op_sel_hi:[1,1,0]
	v_pk_fma_f32 v[40:41], v[24:25], v[40:41], s[50:51] op_sel_hi:[1,1,0]
	v_pk_fma_f32 v[42:43], v[36:37], v[42:43], s[50:51] op_sel_hi:[1,1,0]
	v_pk_fma_f32 v[40:41], v[24:25], v[40:41], s[56:57] op_sel_hi:[1,1,0]
	v_pk_fma_f32 v[42:43], v[36:37], v[42:43], s[56:57] op_sel_hi:[1,1,0]
	v_pk_mul_f32 v[24:25], v[24:25], v[40:41]
	v_pk_mul_f32 v[36:37], v[36:37], v[42:43]
	v_pk_mul_f32 v[24:25], v[34:35], v[24:25]
	v_pk_mul_f32 v[34:35], v[38:39], v[36:37]
	v_max_f32_e32 v112, 0, v20
	v_fma_f32 v6, -|v20|, v24, v112
	v_max_f32_e32 v113, 0, v21
	v_fma_f32 v10, -|v21|, v25, v113
	v_max_f32_e32 v114, 0, v22
	v_fma_f32 v20, -|v22|, v34, v114
	v_max_f32_e32 v115, 0, v23
	v_fma_f32 v21, -|v23|, v35, v115
	v_sub_f32_e32 v6, v6, v14
	v_mul_f32_e32 v6, v12, v6
	v_sub_f32_e32 v10, v10, v14
	v_mul_f32_e32 v10, v12, v10
	v_sub_f32_e32 v20, v20, v15
	v_mul_f32_e32 v20, v13, v20
	v_sub_f32_e32 v21, v21, v15
	v_mul_f32_e32 v21, v13, v21
	ds_write_b32 v70, v3 offset:2992
	s_waitcnt vmcnt(0)
	v_fma_f32 v3, v8, v6, v4
	v_fma_f32 v6, v9, v10, v5
	v_fma_f32 v4, v8, v20, v4
	v_fmac_f32_e32 v5, v9, v21
	v_cvt_pk_bf16_f32 v3, v3, v4
	ds_write_b32 v70, v3 offset:3264
	v_cvt_pk_bf16_f32 v3, v6, v5
	global_load_dwordx2 v[8:9], v2, s[0:1] offset:56
	global_load_dwordx2 v[4:5], v2, s[4:5] offset:56
	v_lshlrev_b32_e32 v10, 16, v11
	v_and_b32_e32 v11, 0xffff0000, v11
	v_lshlrev_b32_e32 v6, 16, v7
	v_and_b32_e32 v7, 0xffff0000, v7
	v_fma_f32 v20, |v10|, s40, 1.0
	v_fma_f32 v21, |v11|, s40, 1.0
	v_fma_f32 v24, |v6|, s40, 1.0
	v_fma_f32 v25, |v7|, s40, 1.0
	v_rcp_f32_e32 v20, v20
	v_rcp_f32_e32 v21, v21
	v_rcp_f32_e32 v24, v24
	v_rcp_f32_e32 v25, v25
	v_pk_mul_f32 v[22:23], v[10:11], v[10:11]
	v_pk_mul_f32 v[34:35], v[6:7], v[6:7]
	v_pk_mul_f32 v[22:23], v[22:23], s[64:65] op_sel_hi:[1,0]
	v_pk_fma_f32 v[36:37], v[20:21], s[42:43], v[16:17] op_sel_hi:[1,0,0]
	v_pk_mul_f32 v[34:35], v[34:35], s[64:65] op_sel_hi:[1,0]
	v_exp_f32_e32 v22, v22
	v_exp_f32_e32 v23, v23
	v_pk_fma_f32 v[38:39], v[24:25], s[42:43], v[16:17] op_sel_hi:[1,0,0]
	v_pk_fma_f32 v[36:37], v[20:21], v[36:37], s[48:49] op_sel_hi:[1,1,0]
	v_exp_f32_e32 v34, v34
	v_exp_f32_e32 v35, v35
	v_pk_fma_f32 v[38:39], v[24:25], v[38:39], s[48:49] op_sel_hi:[1,1,0]
	v_pk_fma_f32 v[36:37], v[20:21], v[36:37], s[50:51] op_sel_hi:[1,1,0]
	v_pk_fma_f32 v[38:39], v[24:25], v[38:39], s[50:51] op_sel_hi:[1,1,0]
	v_pk_fma_f32 v[36:37], v[20:21], v[36:37], s[56:57] op_sel_hi:[1,1,0]
	v_pk_fma_f32 v[38:39], v[24:25], v[38:39], s[56:57] op_sel_hi:[1,1,0]
	v_pk_mul_f32 v[20:21], v[20:21], v[36:37]
	v_pk_mul_f32 v[24:25], v[24:25], v[38:39]
	v_pk_mul_f32 v[20:21], v[22:23], v[20:21]
	v_pk_mul_f32 v[22:23], v[34:35], v[24:25]
	v_max_f32_e32 v116, 0, v10
	v_fma_f32 v10, -|v10|, v20, v116
	v_max_f32_e32 v117, 0, v11
	v_fma_f32 v11, -|v11|, v21, v117
	v_max_f32_e32 v80, 0, v6
	v_fma_f32 v6, -|v6|, v22, v80
	v_max_f32_e32 v81, 0, v7
	v_fma_f32 v7, -|v7|, v23, v81
	v_sub_f32_e32 v10, v10, v14
	v_mul_f32_e32 v10, v12, v10
	v_sub_f32_e32 v11, v11, v14
	v_mul_f32_e32 v11, v12, v11
	v_sub_f32_e32 v6, v6, v15
	v_mul_f32_e32 v6, v13, v6
	v_sub_f32_e32 v7, v7, v15
	v_mul_f32_e32 v7, v13, v7
	ds_write_b32 v70, v3 offset:3536
	s_waitcnt vmcnt(0)
	v_fma_f32 v3, v8, v10, v4
	v_fma_f32 v10, v9, v11, v5
	v_fma_f32 v4, v8, v6, v4
	v_fmac_f32_e32 v5, v9, v7
	v_cvt_pk_bf16_f32 v3, v3, v4
	ds_write_b32 v70, v3 offset:3808
	v_cvt_pk_bf16_f32 v3, v10, v5
	global_load_dwordx4 v[8:11], v[18:19], off offset:32
	global_load_dwordx4 v[4:7], v[18:19], off offset:2080
	global_load_dwordx2 v[22:23], v2, s[0:1] offset:64
	global_load_dwordx2 v[20:21], v2, s[4:5] offset:64
	ds_write_b32 v70, v3 offset:4080
	s_waitcnt vmcnt(3)
	v_lshlrev_b32_e32 v24, 16, v8
	v_and_b32_e32 v25, 0xffff0000, v8
	s_waitcnt vmcnt(2)
	v_lshlrev_b32_e32 v34, 16, v4
	v_and_b32_e32 v35, 0xffff0000, v4
	v_fma_f32 v36, |v24|, s40, 1.0
	v_fma_f32 v37, |v25|, s40, 1.0
	v_fma_f32 v40, |v34|, s40, 1.0
	v_fma_f32 v41, |v35|, s40, 1.0
	v_rcp_f32_e32 v36, v36
	v_rcp_f32_e32 v37, v37
	v_rcp_f32_e32 v40, v40
	v_rcp_f32_e32 v41, v41
	v_pk_mul_f32 v[38:39], v[24:25], v[24:25]
	v_pk_mul_f32 v[42:43], v[34:35], v[34:35]
	v_pk_mul_f32 v[38:39], v[38:39], s[64:65] op_sel_hi:[1,0]
	v_pk_fma_f32 v[44:45], v[36:37], s[42:43], v[16:17] op_sel_hi:[1,0,0]
	v_pk_mul_f32 v[42:43], v[42:43], s[64:65] op_sel_hi:[1,0]
	v_exp_f32_e32 v38, v38
	v_exp_f32_e32 v39, v39
	v_pk_fma_f32 v[46:47], v[40:41], s[42:43], v[16:17] op_sel_hi:[1,0,0]
	v_pk_fma_f32 v[44:45], v[36:37], v[44:45], s[48:49] op_sel_hi:[1,1,0]
	v_exp_f32_e32 v42, v42
	v_exp_f32_e32 v43, v43
	v_pk_fma_f32 v[46:47], v[40:41], v[46:47], s[48:49] op_sel_hi:[1,1,0]
	v_pk_fma_f32 v[44:45], v[36:37], v[44:45], s[50:51] op_sel_hi:[1,1,0]
	v_pk_fma_f32 v[46:47], v[40:41], v[46:47], s[50:51] op_sel_hi:[1,1,0]
	v_pk_fma_f32 v[44:45], v[36:37], v[44:45], s[56:57] op_sel_hi:[1,1,0]
	v_pk_fma_f32 v[46:47], v[40:41], v[46:47], s[56:57] op_sel_hi:[1,1,0]
	v_pk_mul_f32 v[36:37], v[36:37], v[44:45]
	v_pk_mul_f32 v[40:41], v[40:41], v[46:47]
	v_pk_mul_f32 v[36:37], v[38:39], v[36:37]
	v_pk_mul_f32 v[38:39], v[42:43], v[40:41]
	v_max_f32_e32 v82, 0, v24
	v_fma_f32 v3, -|v24|, v36, v82
	v_max_f32_e32 v83, 0, v25
	v_fma_f32 v4, -|v25|, v37, v83
	v_max_f32_e32 v84, 0, v34
	v_fma_f32 v8, -|v34|, v38, v84
	v_max_f32_e32 v85, 0, v35
	v_fma_f32 v24, -|v35|, v39, v85
	v_sub_f32_e32 v3, v3, v14
	v_mul_f32_e32 v3, v12, v3
	v_sub_f32_e32 v4, v4, v14
	v_mul_f32_e32 v4, v12, v4
	v_sub_f32_e32 v8, v8, v15
	v_mul_f32_e32 v8, v13, v8
	v_sub_f32_e32 v24, v24, v15
	v_mul_f32_e32 v24, v13, v24
	s_waitcnt vmcnt(0)
	v_fma_f32 v3, v22, v3, v20
	v_fma_f32 v4, v23, v4, v21
	v_fma_f32 v8, v22, v8, v20
	v_fmac_f32_e32 v21, v23, v24
	v_cvt_pk_bf16_f32 v3, v3, v8
	ds_write_b32 v70, v3 offset:4352
	v_cvt_pk_bf16_f32 v3, v4, v21
	global_load_dwordx2 v[22:23], v2, s[0:1] offset:72
	global_load_dwordx2 v[20:21], v2, s[4:5] offset:72
	v_lshlrev_b32_e32 v8, 16, v9
	v_and_b32_e32 v9, 0xffff0000, v9
	v_lshlrev_b32_e32 v4, 16, v5
	v_and_b32_e32 v5, 0xffff0000, v5
	v_fma_f32 v24, |v8|, s40, 1.0
	v_fma_f32 v25, |v9|, s40, 1.0
	v_fma_f32 v36, |v4|, s40, 1.0
	v_fma_f32 v37, |v5|, s40, 1.0
	v_rcp_f32_e32 v24, v24
	v_rcp_f32_e32 v25, v25
	v_rcp_f32_e32 v36, v36
	v_rcp_f32_e32 v37, v37
	v_pk_mul_f32 v[34:35], v[8:9], v[8:9]
	v_pk_mul_f32 v[38:39], v[4:5], v[4:5]
	v_pk_mul_f32 v[34:35], v[34:35], s[64:65] op_sel_hi:[1,0]
	v_pk_fma_f32 v[40:41], v[24:25], s[42:43], v[16:17] op_sel_hi:[1,0,0]
	v_pk_mul_f32 v[38:39], v[38:39], s[64:65] op_sel_hi:[1,0]
	v_exp_f32_e32 v34, v34
	v_exp_f32_e32 v35, v35
	v_pk_fma_f32 v[42:43], v[36:37], s[42:43], v[16:17] op_sel_hi:[1,0,0]
	v_pk_fma_f32 v[40:41], v[24:25], v[40:41], s[48:49] op_sel_hi:[1,1,0]
	v_exp_f32_e32 v38, v38
	v_exp_f32_e32 v39, v39
	v_pk_fma_f32 v[42:43], v[36:37], v[42:43], s[48:49] op_sel_hi:[1,1,0]
	v_pk_fma_f32 v[40:41], v[24:25], v[40:41], s[50:51] op_sel_hi:[1,1,0]
	v_pk_fma_f32 v[42:43], v[36:37], v[42:43], s[50:51] op_sel_hi:[1,1,0]
	v_pk_fma_f32 v[40:41], v[24:25], v[40:41], s[56:57] op_sel_hi:[1,1,0]
	v_pk_fma_f32 v[42:43], v[36:37], v[42:43], s[56:57] op_sel_hi:[1,1,0]
	v_pk_mul_f32 v[24:25], v[24:25], v[40:41]
	v_pk_mul_f32 v[36:37], v[36:37], v[42:43]
	v_pk_mul_f32 v[24:25], v[34:35], v[24:25]
	v_pk_mul_f32 v[34:35], v[38:39], v[36:37]
	v_max_f32_e32 v86, 0, v8
	v_fma_f32 v8, -|v8|, v24, v86
	v_max_f32_e32 v90, 0, v9
	v_fma_f32 v9, -|v9|, v25, v90
	v_max_f32_e32 v91, 0, v4
	v_fma_f32 v4, -|v4|, v34, v91
	v_max_f32_e32 v92, 0, v5
	v_fma_f32 v5, -|v5|, v35, v92
	v_sub_f32_e32 v8, v8, v14
	v_mul_f32_e32 v8, v12, v8
	v_sub_f32_e32 v9, v9, v14
	v_mul_f32_e32 v9, v12, v9
	v_sub_f32_e32 v4, v4, v15
	v_mul_f32_e32 v4, v13, v4
	v_sub_f32_e32 v5, v5, v15
	ds_write_b32 v70, v3 offset:4624
	v_mul_f32_e32 v5, v13, v5
	s_waitcnt vmcnt(0)
	v_fma_f32 v3, v22, v8, v20
	v_fma_f32 v8, v23, v9, v21
	v_fma_f32 v4, v22, v4, v20
	v_cvt_pk_bf16_f32 v3, v3, v4
	v_fmac_f32_e32 v21, v23, v5
	ds_write_b32 v70, v3 offset:4896
	v_cvt_pk_bf16_f32 v3, v8, v21
	global_load_dwordx2 v[8:9], v2, s[0:1] offset:80
	global_load_dwordx2 v[4:5], v2, s[4:5] offset:80
	v_lshlrev_b32_e32 v20, 16, v10
	v_and_b32_e32 v21, 0xffff0000, v10
	v_lshlrev_b32_e32 v22, 16, v6
	v_and_b32_e32 v23, 0xffff0000, v6
	v_fma_f32 v24, |v20|, s40, 1.0
	v_fma_f32 v25, |v21|, s40, 1.0
	v_fma_f32 v36, |v22|, s40, 1.0
	v_fma_f32 v37, |v23|, s40, 1.0
	v_rcp_f32_e32 v24, v24
	v_rcp_f32_e32 v25, v25
	v_rcp_f32_e32 v36, v36
	v_rcp_f32_e32 v37, v37
	v_pk_mul_f32 v[34:35], v[20:21], v[20:21]
	v_pk_mul_f32 v[38:39], v[22:23], v[22:23]
	v_pk_mul_f32 v[34:35], v[34:35], s[64:65] op_sel_hi:[1,0]
	v_pk_fma_f32 v[40:41], v[24:25], s[42:43], v[16:17] op_sel_hi:[1,0,0]
	v_pk_mul_f32 v[38:39], v[38:39], s[64:65] op_sel_hi:[1,0]
	v_exp_f32_e32 v34, v34
	v_exp_f32_e32 v35, v35
	v_pk_fma_f32 v[42:43], v[36:37], s[42:43], v[16:17] op_sel_hi:[1,0,0]
	v_pk_fma_f32 v[40:41], v[24:25], v[40:41], s[48:49] op_sel_hi:[1,1,0]
	v_exp_f32_e32 v38, v38
	v_exp_f32_e32 v39, v39
	v_pk_fma_f32 v[42:43], v[36:37], v[42:43], s[48:49] op_sel_hi:[1,1,0]
	v_pk_fma_f32 v[40:41], v[24:25], v[40:41], s[50:51] op_sel_hi:[1,1,0]
	v_pk_fma_f32 v[42:43], v[36:37], v[42:43], s[50:51] op_sel_hi:[1,1,0]
	v_pk_fma_f32 v[40:41], v[24:25], v[40:41], s[56:57] op_sel_hi:[1,1,0]
	v_pk_fma_f32 v[42:43], v[36:37], v[42:43], s[56:57] op_sel_hi:[1,1,0]
	v_pk_mul_f32 v[24:25], v[24:25], v[40:41]
	v_pk_mul_f32 v[36:37], v[36:37], v[42:43]
	v_pk_mul_f32 v[24:25], v[34:35], v[24:25]
	v_pk_mul_f32 v[34:35], v[38:39], v[36:37]
	v_max_f32_e32 v93, 0, v20
	v_fma_f32 v6, -|v20|, v24, v93
	v_max_f32_e32 v94, 0, v21
	v_fma_f32 v10, -|v21|, v25, v94
	v_max_f32_e32 v95, 0, v22
	v_fma_f32 v20, -|v22|, v34, v95
	v_max_f32_e32 v96, 0, v23
	v_fma_f32 v21, -|v23|, v35, v96
	v_sub_f32_e32 v6, v6, v14
	v_mul_f32_e32 v6, v12, v6
	v_sub_f32_e32 v10, v10, v14
	v_mul_f32_e32 v10, v12, v10
	v_sub_f32_e32 v20, v20, v15
	v_mul_f32_e32 v20, v13, v20
	v_sub_f32_e32 v21, v21, v15
	v_mul_f32_e32 v21, v13, v21
	ds_write_b32 v70, v3 offset:5168
	s_waitcnt vmcnt(0)
	v_fma_f32 v3, v8, v6, v4
	v_fma_f32 v6, v9, v10, v5
	v_fma_f32 v4, v8, v20, v4
	v_fmac_f32_e32 v5, v9, v21
	v_cvt_pk_bf16_f32 v3, v3, v4
	ds_write_b32 v70, v3 offset:5440
	v_cvt_pk_bf16_f32 v3, v6, v5
	global_load_dwordx2 v[8:9], v2, s[0:1] offset:88
	global_load_dwordx2 v[4:5], v2, s[4:5] offset:88
	v_lshlrev_b32_e32 v10, 16, v11
	v_and_b32_e32 v11, 0xffff0000, v11
	v_lshlrev_b32_e32 v6, 16, v7
	v_and_b32_e32 v7, 0xffff0000, v7
	v_fma_f32 v20, |v10|, s40, 1.0
	v_fma_f32 v21, |v11|, s40, 1.0
	v_fma_f32 v24, |v6|, s40, 1.0
	v_fma_f32 v25, |v7|, s40, 1.0
	v_rcp_f32_e32 v20, v20
	v_rcp_f32_e32 v21, v21
	v_rcp_f32_e32 v24, v24
	v_rcp_f32_e32 v25, v25
	v_pk_mul_f32 v[22:23], v[10:11], v[10:11]
	v_pk_mul_f32 v[34:35], v[6:7], v[6:7]
	v_pk_mul_f32 v[22:23], v[22:23], s[64:65] op_sel_hi:[1,0]
	v_pk_fma_f32 v[36:37], v[20:21], s[42:43], v[16:17] op_sel_hi:[1,0,0]
	v_pk_mul_f32 v[34:35], v[34:35], s[64:65] op_sel_hi:[1,0]
	v_exp_f32_e32 v22, v22
	v_exp_f32_e32 v23, v23
	v_pk_fma_f32 v[38:39], v[24:25], s[42:43], v[16:17] op_sel_hi:[1,0,0]
	v_pk_fma_f32 v[36:37], v[20:21], v[36:37], s[48:49] op_sel_hi:[1,1,0]
	v_exp_f32_e32 v34, v34
	v_exp_f32_e32 v35, v35
	v_pk_fma_f32 v[38:39], v[24:25], v[38:39], s[48:49] op_sel_hi:[1,1,0]
	v_pk_fma_f32 v[36:37], v[20:21], v[36:37], s[50:51] op_sel_hi:[1,1,0]
	v_pk_fma_f32 v[38:39], v[24:25], v[38:39], s[50:51] op_sel_hi:[1,1,0]
	v_pk_fma_f32 v[36:37], v[20:21], v[36:37], s[56:57] op_sel_hi:[1,1,0]
	v_pk_fma_f32 v[38:39], v[24:25], v[38:39], s[56:57] op_sel_hi:[1,1,0]
	v_pk_mul_f32 v[20:21], v[20:21], v[36:37]
	v_pk_mul_f32 v[24:25], v[24:25], v[38:39]
	v_pk_mul_f32 v[20:21], v[22:23], v[20:21]
	v_pk_mul_f32 v[22:23], v[34:35], v[24:25]
	v_max_f32_e32 v97, 0, v10
	v_fma_f32 v10, -|v10|, v20, v97
	v_max_f32_e32 v98, 0, v11
	v_fma_f32 v11, -|v11|, v21, v98
	v_max_f32_e32 v99, 0, v6
	v_fma_f32 v6, -|v6|, v22, v99
	v_max_f32_e32 v100, 0, v7
	v_fma_f32 v7, -|v7|, v23, v100
	v_sub_f32_e32 v10, v10, v14
	v_mul_f32_e32 v10, v12, v10
	v_sub_f32_e32 v11, v11, v14
	v_mul_f32_e32 v11, v12, v11
	v_sub_f32_e32 v6, v6, v15
	v_mul_f32_e32 v6, v13, v6
	v_sub_f32_e32 v7, v7, v15
	v_mul_f32_e32 v7, v13, v7
	ds_write_b32 v70, v3 offset:5712
	s_waitcnt vmcnt(0)
	v_fma_f32 v3, v8, v10, v4
	v_fma_f32 v10, v9, v11, v5
	v_fma_f32 v4, v8, v6, v4
	v_fmac_f32_e32 v5, v9, v7
	v_cvt_pk_bf16_f32 v3, v3, v4
	ds_write_b32 v70, v3 offset:5984
	v_cvt_pk_bf16_f32 v3, v10, v5
	global_load_dwordx4 v[8:11], v[18:19], off offset:48
	global_load_dwordx4 v[4:7], v[18:19], off offset:2096
	global_load_dwordx2 v[20:21], v2, s[0:1] offset:96
	s_nop 0
	global_load_dwordx2 v[18:19], v2, s[4:5] offset:96
	ds_write_b32 v70, v3 offset:6256
	s_waitcnt vmcnt(3)
	v_lshlrev_b32_e32 v22, 16, v8
	v_and_b32_e32 v23, 0xffff0000, v8
	s_waitcnt vmcnt(2)
	v_lshlrev_b32_e32 v24, 16, v4
	v_and_b32_e32 v25, 0xffff0000, v4
	v_fma_f32 v34, |v22|, s40, 1.0
	v_fma_f32 v35, |v23|, s40, 1.0
	v_fma_f32 v38, |v24|, s40, 1.0
	v_fma_f32 v39, |v25|, s40, 1.0
	v_rcp_f32_e32 v34, v34
	v_rcp_f32_e32 v35, v35
	v_rcp_f32_e32 v38, v38
	v_rcp_f32_e32 v39, v39
	v_pk_mul_f32 v[36:37], v[22:23], v[22:23]
	v_pk_mul_f32 v[40:41], v[24:25], v[24:25]
	v_pk_mul_f32 v[36:37], v[36:37], s[64:65] op_sel_hi:[1,0]
	v_pk_fma_f32 v[42:43], v[34:35], s[42:43], v[16:17] op_sel_hi:[1,0,0]
	v_pk_mul_f32 v[40:41], v[40:41], s[64:65] op_sel_hi:[1,0]
	v_exp_f32_e32 v36, v36
	v_exp_f32_e32 v37, v37
	v_pk_fma_f32 v[44:45], v[38:39], s[42:43], v[16:17] op_sel_hi:[1,0,0]
	v_pk_fma_f32 v[42:43], v[34:35], v[42:43], s[48:49] op_sel_hi:[1,1,0]
	v_exp_f32_e32 v40, v40
	v_exp_f32_e32 v41, v41
	v_pk_fma_f32 v[44:45], v[38:39], v[44:45], s[48:49] op_sel_hi:[1,1,0]
	v_pk_fma_f32 v[42:43], v[34:35], v[42:43], s[50:51] op_sel_hi:[1,1,0]
	v_pk_fma_f32 v[44:45], v[38:39], v[44:45], s[50:51] op_sel_hi:[1,1,0]
	v_pk_fma_f32 v[42:43], v[34:35], v[42:43], s[56:57] op_sel_hi:[1,1,0]
	v_pk_fma_f32 v[44:45], v[38:39], v[44:45], s[56:57] op_sel_hi:[1,1,0]
	v_pk_mul_f32 v[34:35], v[34:35], v[42:43]
	v_pk_mul_f32 v[38:39], v[38:39], v[44:45]
	v_pk_mul_f32 v[34:35], v[36:37], v[34:35]
	v_pk_mul_f32 v[36:37], v[40:41], v[38:39]
	v_max_f32_e32 v104, 0, v22
	v_fma_f32 v3, -|v22|, v34, v104
	v_max_f32_e32 v105, 0, v23
	v_fma_f32 v4, -|v23|, v35, v105
	v_max_f32_e32 v106, 0, v24
	v_fma_f32 v8, -|v24|, v36, v106
	v_max_f32_e32 v107, 0, v25
	v_fma_f32 v22, -|v25|, v37, v107
	v_sub_f32_e32 v3, v3, v14
	v_mul_f32_e32 v3, v12, v3
	v_sub_f32_e32 v4, v4, v14
	v_mul_f32_e32 v4, v12, v4
	v_sub_f32_e32 v8, v8, v15
	v_mul_f32_e32 v8, v13, v8
	v_sub_f32_e32 v22, v22, v15
	v_mul_f32_e32 v22, v13, v22
	s_waitcnt vmcnt(0)
	v_fma_f32 v3, v20, v3, v18
	v_fma_f32 v4, v21, v4, v19
	v_fma_f32 v8, v20, v8, v18
	v_fmac_f32_e32 v19, v21, v22
	v_cvt_pk_bf16_f32 v3, v3, v8
	ds_write_b32 v70, v3 offset:6528
	v_cvt_pk_bf16_f32 v3, v4, v19
	global_load_dwordx2 v[20:21], v2, s[0:1] offset:104
	global_load_dwordx2 v[18:19], v2, s[4:5] offset:104
	v_lshlrev_b32_e32 v8, 16, v9
	v_and_b32_e32 v9, 0xffff0000, v9
	v_lshlrev_b32_e32 v4, 16, v5
	v_and_b32_e32 v5, 0xffff0000, v5
	v_fma_f32 v22, |v8|, s40, 1.0
	v_fma_f32 v23, |v9|, s40, 1.0
	v_fma_f32 v34, |v4|, s40, 1.0
	v_fma_f32 v35, |v5|, s40, 1.0
	v_rcp_f32_e32 v22, v22
	v_rcp_f32_e32 v23, v23
	v_rcp_f32_e32 v34, v34
	v_rcp_f32_e32 v35, v35
	v_pk_mul_f32 v[24:25], v[8:9], v[8:9]
	v_pk_mul_f32 v[36:37], v[4:5], v[4:5]
	v_pk_mul_f32 v[24:25], v[24:25], s[64:65] op_sel_hi:[1,0]
	v_pk_fma_f32 v[38:39], v[22:23], s[42:43], v[16:17] op_sel_hi:[1,0,0]
	v_pk_mul_f32 v[36:37], v[36:37], s[64:65] op_sel_hi:[1,0]
	v_exp_f32_e32 v24, v24
	v_exp_f32_e32 v25, v25
	v_pk_fma_f32 v[40:41], v[34:35], s[42:43], v[16:17] op_sel_hi:[1,0,0]
	v_pk_fma_f32 v[38:39], v[22:23], v[38:39], s[48:49] op_sel_hi:[1,1,0]
	v_exp_f32_e32 v36, v36
	v_exp_f32_e32 v37, v37
	v_pk_fma_f32 v[40:41], v[34:35], v[40:41], s[48:49] op_sel_hi:[1,1,0]
	v_pk_fma_f32 v[38:39], v[22:23], v[38:39], s[50:51] op_sel_hi:[1,1,0]
	v_pk_fma_f32 v[40:41], v[34:35], v[40:41], s[50:51] op_sel_hi:[1,1,0]
	v_pk_fma_f32 v[38:39], v[22:23], v[38:39], s[56:57] op_sel_hi:[1,1,0]
	v_pk_fma_f32 v[40:41], v[34:35], v[40:41], s[56:57] op_sel_hi:[1,1,0]
	v_pk_mul_f32 v[22:23], v[22:23], v[38:39]
	v_pk_mul_f32 v[34:35], v[34:35], v[40:41]
	v_pk_mul_f32 v[22:23], v[24:25], v[22:23]
	v_pk_mul_f32 v[24:25], v[36:37], v[34:35]
	v_max_f32_e32 v108, 0, v8
	v_fma_f32 v8, -|v8|, v22, v108
	v_max_f32_e32 v109, 0, v9
	v_fma_f32 v9, -|v9|, v23, v109
	v_max_f32_e32 v110, 0, v4
	v_fma_f32 v4, -|v4|, v24, v110
	v_max_f32_e32 v111, 0, v5
	v_fma_f32 v5, -|v5|, v25, v111
	v_sub_f32_e32 v8, v8, v14
	v_mul_f32_e32 v8, v12, v8
	v_sub_f32_e32 v9, v9, v14
	v_mul_f32_e32 v9, v12, v9
	v_sub_f32_e32 v4, v4, v15
	v_mul_f32_e32 v4, v13, v4
	v_sub_f32_e32 v5, v5, v15
	ds_write_b32 v70, v3 offset:6800
	v_mul_f32_e32 v5, v13, v5
	s_waitcnt vmcnt(0)
	v_fma_f32 v3, v20, v8, v18
	v_fma_f32 v8, v21, v9, v19
	v_fma_f32 v4, v20, v4, v18
	v_cvt_pk_bf16_f32 v3, v3, v4
	v_fmac_f32_e32 v19, v21, v5
	ds_write_b32 v70, v3 offset:7072
	v_cvt_pk_bf16_f32 v3, v8, v19
	global_load_dwordx2 v[8:9], v2, s[0:1] offset:112
	global_load_dwordx2 v[4:5], v2, s[4:5] offset:112
	v_lshlrev_b32_e32 v18, 16, v10
	v_and_b32_e32 v19, 0xffff0000, v10
	v_lshlrev_b32_e32 v20, 16, v6
	v_and_b32_e32 v21, 0xffff0000, v6
	v_fma_f32 v22, |v18|, s40, 1.0
	v_fma_f32 v23, |v19|, s40, 1.0
	v_fma_f32 v34, |v20|, s40, 1.0
	v_fma_f32 v35, |v21|, s40, 1.0
	v_rcp_f32_e32 v22, v22
	v_rcp_f32_e32 v23, v23
	v_rcp_f32_e32 v34, v34
	v_rcp_f32_e32 v35, v35
	v_pk_mul_f32 v[24:25], v[18:19], v[18:19]
	v_pk_mul_f32 v[36:37], v[20:21], v[20:21]
	v_pk_mul_f32 v[24:25], v[24:25], s[64:65] op_sel_hi:[1,0]
	v_pk_fma_f32 v[38:39], v[22:23], s[42:43], v[16:17] op_sel_hi:[1,0,0]
	v_pk_mul_f32 v[36:37], v[36:37], s[64:65] op_sel_hi:[1,0]
	v_exp_f32_e32 v24, v24
	v_exp_f32_e32 v25, v25
	v_pk_fma_f32 v[40:41], v[34:35], s[42:43], v[16:17] op_sel_hi:[1,0,0]
	v_pk_fma_f32 v[38:39], v[22:23], v[38:39], s[48:49] op_sel_hi:[1,1,0]
	v_exp_f32_e32 v36, v36
	v_exp_f32_e32 v37, v37
	v_pk_fma_f32 v[40:41], v[34:35], v[40:41], s[48:49] op_sel_hi:[1,1,0]
	v_pk_fma_f32 v[38:39], v[22:23], v[38:39], s[50:51] op_sel_hi:[1,1,0]
	v_pk_fma_f32 v[40:41], v[34:35], v[40:41], s[50:51] op_sel_hi:[1,1,0]
	v_pk_fma_f32 v[38:39], v[22:23], v[38:39], s[56:57] op_sel_hi:[1,1,0]
	v_pk_fma_f32 v[40:41], v[34:35], v[40:41], s[56:57] op_sel_hi:[1,1,0]
	v_pk_mul_f32 v[22:23], v[22:23], v[38:39]
	v_pk_mul_f32 v[34:35], v[34:35], v[40:41]
	v_pk_mul_f32 v[22:23], v[24:25], v[22:23]
	v_pk_mul_f32 v[24:25], v[36:37], v[34:35]
	v_max_f32_e32 v112, 0, v18
	v_fma_f32 v6, -|v18|, v22, v112
	v_max_f32_e32 v113, 0, v19
	v_fma_f32 v10, -|v19|, v23, v113
	v_max_f32_e32 v114, 0, v20
	v_fma_f32 v18, -|v20|, v24, v114
	v_max_f32_e32 v115, 0, v21
	v_fma_f32 v19, -|v21|, v25, v115
	v_sub_f32_e32 v6, v6, v14
	v_mul_f32_e32 v6, v12, v6
	v_sub_f32_e32 v10, v10, v14
	v_mul_f32_e32 v10, v12, v10
	v_sub_f32_e32 v18, v18, v15
	v_mul_f32_e32 v18, v13, v18
	v_sub_f32_e32 v19, v19, v15
	v_mul_f32_e32 v19, v13, v19
	ds_write_b32 v70, v3 offset:7344
	s_andn2_b64 vcc, exec, s[80:81]
	s_waitcnt vmcnt(0)
	v_fma_f32 v3, v8, v6, v4
	v_fma_f32 v6, v9, v10, v5
	v_fma_f32 v4, v8, v18, v4
	v_fmac_f32_e32 v5, v9, v19
	v_cvt_pk_bf16_f32 v3, v3, v4
	ds_write_b32 v70, v3 offset:7616
	v_cvt_pk_bf16_f32 v3, v6, v5
	global_load_dwordx2 v[8:9], v2, s[0:1] offset:120
	global_load_dwordx2 v[4:5], v2, s[4:5] offset:120
	v_lshlrev_b32_e32 v10, 16, v11
	v_and_b32_e32 v11, 0xffff0000, v11
	v_cndmask_b32_e64 v6, 0, 1, s[80:81]
	v_cmp_ne_u32_e64 s[4:5], 1, v6
	v_lshlrev_b32_e32 v6, 16, v7
	v_and_b32_e32 v7, 0xffff0000, v7
	v_fma_f32 v18, |v10|, s40, 1.0
	v_fma_f32 v19, |v11|, s40, 1.0
	v_rcp_f32_e32 v18, v18
	v_rcp_f32_e32 v19, v19
	v_fma_f32 v22, |v6|, s40, 1.0
	v_fma_f32 v23, |v7|, s40, 1.0
	v_pk_mul_f32 v[20:21], v[10:11], v[10:11]
	v_rcp_f32_e32 v22, v22
	v_rcp_f32_e32 v23, v23
	v_pk_mul_f32 v[20:21], v[20:21], s[64:65] op_sel_hi:[1,0]
	v_pk_fma_f32 v[34:35], v[18:19], s[42:43], v[16:17] op_sel_hi:[1,0,0]
	v_pk_mul_f32 v[24:25], v[6:7], v[6:7]
	v_exp_f32_e32 v20, v20
	v_exp_f32_e32 v21, v21
	v_pk_fma_f32 v[34:35], v[18:19], v[34:35], s[48:49] op_sel_hi:[1,1,0]
	v_pk_mul_f32 v[24:25], v[24:25], s[64:65] op_sel_hi:[1,0]
	v_pk_fma_f32 v[16:17], v[22:23], s[42:43], v[16:17] op_sel_hi:[1,0,0]
	v_pk_fma_f32 v[34:35], v[18:19], v[34:35], s[50:51] op_sel_hi:[1,1,0]
	v_exp_f32_e32 v24, v24
	v_exp_f32_e32 v25, v25
	v_pk_fma_f32 v[16:17], v[22:23], v[16:17], s[48:49] op_sel_hi:[1,1,0]
	v_pk_fma_f32 v[34:35], v[18:19], v[34:35], s[56:57] op_sel_hi:[1,1,0]
	v_pk_fma_f32 v[16:17], v[22:23], v[16:17], s[50:51] op_sel_hi:[1,1,0]
	v_pk_mul_f32 v[18:19], v[18:19], v[34:35]
	v_pk_fma_f32 v[16:17], v[22:23], v[16:17], s[56:57] op_sel_hi:[1,1,0]
	v_pk_mul_f32 v[18:19], v[20:21], v[18:19]
	v_pk_mul_f32 v[16:17], v[22:23], v[16:17]
	v_max_f32_e32 v116, 0, v10
	v_fma_f32 v10, -|v10|, v18, v116
	v_max_f32_e32 v117, 0, v11
	v_fma_f32 v11, -|v11|, v19, v117
	v_pk_mul_f32 v[16:17], v[24:25], v[16:17]
	ds_write_b32 v70, v3 offset:7888
	v_max_f32_e32 v80, 0, v6
	v_fma_f32 v6, -|v6|, v16, v80
	v_max_f32_e32 v81, 0, v7
	v_fma_f32 v7, -|v7|, v17, v81
	v_sub_f32_e32 v10, v10, v14
	v_sub_f32_e32 v11, v11, v14
	v_sub_f32_e32 v6, v6, v15
	v_mul_f32_e32 v10, v12, v10
	v_sub_f32_e32 v7, v7, v15
	v_mul_f32_e32 v11, v12, v11
	v_mul_f32_e32 v6, v13, v6
	v_mul_f32_e32 v7, v13, v7
	s_waitcnt vmcnt(0)
	v_fma_f32 v3, v8, v10, v4
	v_fma_f32 v10, v9, v11, v5
	v_fma_f32 v4, v8, v6, v4
	v_fmac_f32_e32 v5, v9, v7
	v_cvt_pk_bf16_f32 v3, v3, v4
	ds_write_b32 v70, v3 offset:8160
	v_cvt_pk_bf16_f32 v3, v10, v5
	v_lshl_add_u64 v[4:5], s[12:13], 0, v[28:29]
	ds_write_b32 v70, v3 offset:8432
	s_cbranch_vccnz .LBB0_458
	v_add_co_u32_e32 v6, vcc, 0x2688000, v4
	s_nop 1
	v_addc_co_u32_e32 v7, vcc, 0, v5, vcc
	global_load_dwordx4 v[6:9], v[6:7], off
	v_cndmask_b32_e64 v3, 0, 1, s[82:83]
	v_cmp_ne_u32_e64 s[6:7], 1, v3
	s_andn2_b64 vcc, exec, s[82:83]
	s_cbranch_vccz .LBB0_459

.LBB0_470:
	s_waitcnt vmcnt(15)
	v_lshlrev_b32_e32 v4, 16, v66
	v_and_b32_e32 v5, 0xffff0000, v66
	v_fma_f32 v74, |v4|, s40, 1.0
	v_fma_f32 v75, |v5|, s40, 1.0
	v_mov_b64_e32 v[76:77], s[44:45]
	v_rcp_f32_e32 v74, v74
	v_rcp_f32_e32 v75, v75
	s_nop 0
	v_pk_fma_f32 v[78:79], v[74:75], s[42:43], v[76:77] op_sel_hi:[1,0,0]
	s_nop 0
	v_pk_fma_f32 v[78:79], v[74:75], v[78:79], s[48:49] op_sel_hi:[1,1,0]
	s_nop 0
	v_pk_fma_f32 v[78:79], v[74:75], v[78:79], s[50:51] op_sel_hi:[1,1,0]
	s_nop 0
	v_pk_fma_f32 v[78:79], v[74:75], v[78:79], s[56:57] op_sel_hi:[1,1,0]
	s_nop 0
	v_pk_mul_f32 v[74:75], v[74:75], v[78:79]
	v_pk_mul_f32 v[78:79], v[4:5], v[4:5]
	s_nop 0
	v_pk_mul_f32 v[78:79], v[78:79], s[64:65] op_sel_hi:[1,0]
	s_nop 0
	v_exp_f32_e32 v78, v78
	v_exp_f32_e32 v79, v79
	s_nop 0
	v_pk_mul_f32 v[74:75], v[78:79], v[74:75]
	s_nop 0
	v_max_f32_e32 v82, 0, v4
	v_fma_f32 v3, -|v4|, v74, v82
	v_max_f32_e32 v83, 0, v5
	v_fma_f32 v73, -|v5|, v75, v83
	v_lshlrev_b32_e32 v4, 16, v67
	v_and_b32_e32 v5, 0xffff0000, v67
	v_fma_f32 v66, |v4|, s40, 1.0
	v_fma_f32 v67, |v5|, s40, 1.0
	v_rcp_f32_e32 v66, v66
	v_rcp_f32_e32 v67, v67
	v_cmp_gt_f32_e32 vcc, 0, v4
	v_pk_fma_f32 v[74:75], v[66:67], s[42:43], v[76:77] op_sel_hi:[1,0,0]
	s_nop 0
	v_pk_fma_f32 v[74:75], v[66:67], v[74:75], s[48:49] op_sel_hi:[1,1,0]
	s_nop 0
	v_pk_fma_f32 v[74:75], v[66:67], v[74:75], s[50:51] op_sel_hi:[1,1,0]
	s_nop 0
	v_pk_fma_f32 v[74:75], v[66:67], v[74:75], s[56:57] op_sel_hi:[1,1,0]
	s_nop 0
	v_pk_mul_f32 v[66:67], v[66:67], v[74:75]
	v_pk_mul_f32 v[74:75], v[4:5], v[4:5]
	s_nop 0
	v_pk_mul_f32 v[74:75], v[74:75], s[64:65] op_sel_hi:[1,0]
	s_nop 0
	v_exp_f32_e32 v74, v74
	v_exp_f32_e32 v75, v75
	s_nop 0
	v_pk_mul_f32 v[66:67], v[74:75], v[66:67]
	s_nop 0
	v_pk_mul_f32 v[74:75], v[4:5], v[66:67]
	v_pk_fma_f32 v[66:67], v[4:5], v[66:67], v[4:5] neg_lo:[1,0,0] neg_hi:[1,0,0]
	v_add_f32_e32 v4, v72, v22
	v_cndmask_b32_e32 v66, v66, v74, vcc
	v_cmp_gt_f32_e32 vcc, 0, v5
	v_add_f32_e32 v22, v72, v25
	v_mul_f32_e32 v3, v3, v4
	v_cndmask_b32_e32 v5, v67, v75, vcc
	v_add_f32_e32 v4, v72, v23
	v_mul_f32_e32 v5, v5, v22
	v_add_co_u32_e32 v22, vcc, 0x1506e000, v34
	v_mul_f32_e32 v4, v73, v4
	s_nop 0
	v_addc_co_u32_e32 v23, vcc, 0, v35, vcc
	v_cvt_pk_bf16_f32 v4, v3, v4
	v_add_f32_e32 v3, v72, v24
	s_and_b64 vcc, exec, s[4:5]
	v_mul_f32_e32 v3, v66, v3
	v_cvt_pk_bf16_f32 v5, v3, v5
	global_store_dwordx2 v[22:23], v[4:5], off
	s_cbranch_vccnz .LBB0_472
	ds_read_b128 v[22:25], v71 offset:4352
	s_waitcnt lgkmcnt(0)
	v_mfma_f32_16x16x32_bf16 v[22:25], v[22:25], v[6:9], 0
	s_and_b64 vcc, exec, s[6:7]
	s_cbranch_vccz .LBB0_473
	s_branch .LBB0_474

.LBB0_478:
	s_waitcnt vmcnt(15)
	v_lshlrev_b32_e32 v4, 16, v64
	v_and_b32_e32 v5, 0xffff0000, v64
	v_fma_f32 v66, |v4|, s40, 1.0
	v_fma_f32 v67, |v5|, s40, 1.0
	v_mov_b64_e32 v[74:75], s[44:45]
	v_rcp_f32_e32 v66, v66
	v_rcp_f32_e32 v67, v67
	s_nop 0
	v_pk_fma_f32 v[76:77], v[66:67], s[42:43], v[74:75] op_sel_hi:[1,0,0]
	s_nop 0
	v_pk_fma_f32 v[76:77], v[66:67], v[76:77], s[48:49] op_sel_hi:[1,1,0]
	s_nop 0
	v_pk_fma_f32 v[76:77], v[66:67], v[76:77], s[50:51] op_sel_hi:[1,1,0]
	s_nop 0
	v_pk_fma_f32 v[76:77], v[66:67], v[76:77], s[56:57] op_sel_hi:[1,1,0]
	s_nop 0
	v_pk_mul_f32 v[66:67], v[66:67], v[76:77]
	v_pk_mul_f32 v[76:77], v[4:5], v[4:5]
	s_nop 0
	v_pk_mul_f32 v[76:77], v[76:77], s[64:65] op_sel_hi:[1,0]
	s_nop 0
	v_exp_f32_e32 v76, v76
	v_exp_f32_e32 v77, v77
	s_nop 0
	v_pk_mul_f32 v[66:67], v[76:77], v[66:67]
	s_nop 0
	v_max_f32_e32 v84, 0, v4
	v_fma_f32 v3, -|v4|, v66, v84
	v_max_f32_e32 v85, 0, v5
	v_fma_f32 v73, -|v5|, v67, v85
	v_lshlrev_b32_e32 v4, 16, v65
	v_and_b32_e32 v5, 0xffff0000, v65
	v_fma_f32 v64, |v4|, s40, 1.0
	v_fma_f32 v65, |v5|, s40, 1.0
	v_rcp_f32_e32 v64, v64
	v_rcp_f32_e32 v65, v65
	v_cmp_gt_f32_e32 vcc, 0, v4
	v_pk_fma_f32 v[66:67], v[64:65], s[42:43], v[74:75] op_sel_hi:[1,0,0]
	s_nop 0
	v_pk_fma_f32 v[66:67], v[64:65], v[66:67], s[48:49] op_sel_hi:[1,1,0]
	s_nop 0
	v_pk_fma_f32 v[66:67], v[64:65], v[66:67], s[50:51] op_sel_hi:[1,1,0]
	s_nop 0
	v_pk_fma_f32 v[66:67], v[64:65], v[66:67], s[56:57] op_sel_hi:[1,1,0]
	s_nop 0
	v_pk_mul_f32 v[64:65], v[64:65], v[66:67]
	v_pk_mul_f32 v[66:67], v[4:5], v[4:5]
	s_nop 0
	v_pk_mul_f32 v[66:67], v[66:67], s[64:65] op_sel_hi:[1,0]
	s_nop 0
	v_exp_f32_e32 v66, v66
	v_exp_f32_e32 v67, v67
	s_nop 0
	v_pk_mul_f32 v[64:65], v[66:67], v[64:65]
	s_nop 0
	v_pk_mul_f32 v[66:67], v[4:5], v[64:65]
	v_pk_fma_f32 v[64:65], v[4:5], v[64:65], v[4:5] neg_lo:[1,0,0] neg_hi:[1,0,0]
	v_add_f32_e32 v4, v72, v22
	v_cndmask_b32_e32 v64, v64, v66, vcc
	v_cmp_gt_f32_e32 vcc, 0, v5
	v_add_f32_e32 v22, v72, v25
	v_mul_f32_e32 v3, v3, v4
	v_cndmask_b32_e32 v5, v65, v67, vcc
	v_add_f32_e32 v4, v72, v23
	v_mul_f32_e32 v5, v5, v22
	v_add_co_u32_e32 v22, vcc, 0x1506e000, v34
	v_mul_f32_e32 v4, v73, v4
	s_nop 0
	v_addc_co_u32_e32 v23, vcc, 0, v35, vcc
	v_cvt_pk_bf16_f32 v4, v3, v4
	v_add_f32_e32 v3, v72, v24
	s_and_b64 vcc, exec, s[4:5]
	v_mul_f32_e32 v3, v64, v3
	v_cvt_pk_bf16_f32 v5, v3, v5
	global_store_dwordx2 v[22:23], v[4:5], off offset:32
	s_cbranch_vccnz .LBB0_480
	ds_read_b128 v[22:25], v71 offset:8704
	s_waitcnt lgkmcnt(0)
	v_mfma_f32_16x16x32_bf16 v[22:25], v[22:25], v[6:9], 0
	s_and_b64 vcc, exec, s[6:7]
	s_cbranch_vccz .LBB0_481
	s_branch .LBB0_482

.LBB0_486:
	s_waitcnt vmcnt(15)
	v_lshlrev_b32_e32 v4, 16, v62
	v_and_b32_e32 v5, 0xffff0000, v62
	v_fma_f32 v64, |v4|, s40, 1.0
	v_fma_f32 v65, |v5|, s40, 1.0
	v_mov_b64_e32 v[66:67], s[44:45]
	v_rcp_f32_e32 v64, v64
	v_rcp_f32_e32 v65, v65
	s_nop 0
	v_pk_fma_f32 v[74:75], v[64:65], s[42:43], v[66:67] op_sel_hi:[1,0,0]
	s_nop 0
	v_pk_fma_f32 v[74:75], v[64:65], v[74:75], s[48:49] op_sel_hi:[1,1,0]
	s_nop 0
	v_pk_fma_f32 v[74:75], v[64:65], v[74:75], s[50:51] op_sel_hi:[1,1,0]
	s_nop 0
	v_pk_fma_f32 v[74:75], v[64:65], v[74:75], s[56:57] op_sel_hi:[1,1,0]
	s_nop 0
	v_pk_mul_f32 v[64:65], v[64:65], v[74:75]
	v_pk_mul_f32 v[74:75], v[4:5], v[4:5]
	s_nop 0
	v_pk_mul_f32 v[74:75], v[74:75], s[64:65] op_sel_hi:[1,0]
	s_nop 0
	v_exp_f32_e32 v74, v74
	v_exp_f32_e32 v75, v75
	s_nop 0
	v_pk_mul_f32 v[64:65], v[74:75], v[64:65]
	s_nop 0
	v_max_f32_e32 v86, 0, v4
	v_fma_f32 v3, -|v4|, v64, v86
	v_max_f32_e32 v90, 0, v5
	v_fma_f32 v73, -|v5|, v65, v90
	v_lshlrev_b32_e32 v4, 16, v63
	v_and_b32_e32 v5, 0xffff0000, v63
	v_fma_f32 v62, |v4|, s40, 1.0
	v_fma_f32 v63, |v5|, s40, 1.0
	v_rcp_f32_e32 v62, v62
	v_rcp_f32_e32 v63, v63
	v_cmp_gt_f32_e32 vcc, 0, v4
	v_pk_fma_f32 v[64:65], v[62:63], s[42:43], v[66:67] op_sel_hi:[1,0,0]
	s_nop 0
	v_pk_fma_f32 v[64:65], v[62:63], v[64:65], s[48:49] op_sel_hi:[1,1,0]
	s_nop 0
	v_pk_fma_f32 v[64:65], v[62:63], v[64:65], s[50:51] op_sel_hi:[1,1,0]
	s_nop 0
	v_pk_fma_f32 v[64:65], v[62:63], v[64:65], s[56:57] op_sel_hi:[1,1,0]
	s_nop 0
	v_pk_mul_f32 v[62:63], v[62:63], v[64:65]
	v_pk_mul_f32 v[64:65], v[4:5], v[4:5]
	s_nop 0
	v_pk_mul_f32 v[64:65], v[64:65], s[64:65] op_sel_hi:[1,0]
	s_nop 0
	v_exp_f32_e32 v64, v64
	v_exp_f32_e32 v65, v65
	s_nop 0
	v_pk_mul_f32 v[62:63], v[64:65], v[62:63]
	s_nop 0
	v_pk_mul_f32 v[64:65], v[4:5], v[62:63]
	v_pk_fma_f32 v[62:63], v[4:5], v[62:63], v[4:5] neg_lo:[1,0,0] neg_hi:[1,0,0]
	v_add_f32_e32 v4, v72, v22
	v_cndmask_b32_e32 v62, v62, v64, vcc
	v_cmp_gt_f32_e32 vcc, 0, v5
	v_add_f32_e32 v22, v72, v25
	v_mul_f32_e32 v3, v3, v4
	v_cndmask_b32_e32 v5, v63, v65, vcc
	v_add_f32_e32 v4, v72, v23
	v_mul_f32_e32 v5, v5, v22
	v_add_co_u32_e32 v22, vcc, 0x1506e000, v34
	v_mul_f32_e32 v4, v73, v4
	s_nop 0
	v_addc_co_u32_e32 v23, vcc, 0, v35, vcc
	v_cvt_pk_bf16_f32 v4, v3, v4
	v_add_f32_e32 v3, v72, v24
	s_and_b64 vcc, exec, s[4:5]
	v_mul_f32_e32 v3, v62, v3
	v_cvt_pk_bf16_f32 v5, v3, v5
	global_store_dwordx2 v[22:23], v[4:5], off offset:64
	s_cbranch_vccnz .LBB0_488
	ds_read_b128 v[22:25], v71 offset:13056
	s_waitcnt lgkmcnt(0)
	v_mfma_f32_16x16x32_bf16 v[22:25], v[22:25], v[6:9], 0
	s_and_b64 vcc, exec, s[6:7]
	s_cbranch_vccz .LBB0_489
	s_branch .LBB0_490

.LBB0_494:
	s_waitcnt vmcnt(15)
	v_lshlrev_b32_e32 v4, 16, v60
	v_and_b32_e32 v5, 0xffff0000, v60
	v_fma_f32 v62, |v4|, s40, 1.0
	v_fma_f32 v63, |v5|, s40, 1.0
	v_mov_b64_e32 v[64:65], s[44:45]
	v_rcp_f32_e32 v62, v62
	v_rcp_f32_e32 v63, v63
	s_nop 0
	v_pk_fma_f32 v[66:67], v[62:63], s[42:43], v[64:65] op_sel_hi:[1,0,0]
	s_nop 0
	v_pk_fma_f32 v[66:67], v[62:63], v[66:67], s[48:49] op_sel_hi:[1,1,0]
	s_nop 0
	v_pk_fma_f32 v[66:67], v[62:63], v[66:67], s[50:51] op_sel_hi:[1,1,0]
	s_nop 0
	v_pk_fma_f32 v[66:67], v[62:63], v[66:67], s[56:57] op_sel_hi:[1,1,0]
	s_nop 0
	v_pk_mul_f32 v[62:63], v[62:63], v[66:67]
	v_pk_mul_f32 v[66:67], v[4:5], v[4:5]
	s_nop 0
	v_pk_mul_f32 v[66:67], v[66:67], s[64:65] op_sel_hi:[1,0]
	s_nop 0
	v_exp_f32_e32 v66, v66
	v_exp_f32_e32 v67, v67
	s_nop 0
	v_pk_mul_f32 v[62:63], v[66:67], v[62:63]
	s_nop 0
	v_max_f32_e32 v91, 0, v4
	v_fma_f32 v3, -|v4|, v62, v91
	v_max_f32_e32 v92, 0, v5
	v_fma_f32 v66, -|v5|, v63, v92
	v_lshlrev_b32_e32 v4, 16, v61
	v_and_b32_e32 v5, 0xffff0000, v61
	v_fma_f32 v60, |v4|, s40, 1.0
	v_fma_f32 v61, |v5|, s40, 1.0
	v_rcp_f32_e32 v60, v60
	v_rcp_f32_e32 v61, v61
	v_cmp_gt_f32_e32 vcc, 0, v4
	v_pk_fma_f32 v[62:63], v[60:61], s[42:43], v[64:65] op_sel_hi:[1,0,0]
	s_nop 0
	v_pk_fma_f32 v[62:63], v[60:61], v[62:63], s[48:49] op_sel_hi:[1,1,0]
	s_nop 0
	v_pk_fma_f32 v[62:63], v[60:61], v[62:63], s[50:51] op_sel_hi:[1,1,0]
	s_nop 0
	v_pk_fma_f32 v[62:63], v[60:61], v[62:63], s[56:57] op_sel_hi:[1,1,0]
	s_nop 0
	v_pk_mul_f32 v[60:61], v[60:61], v[62:63]
	v_pk_mul_f32 v[62:63], v[4:5], v[4:5]
	s_nop 0
	v_pk_mul_f32 v[62:63], v[62:63], s[64:65] op_sel_hi:[1,0]
	s_nop 0
	v_exp_f32_e32 v62, v62
	v_exp_f32_e32 v63, v63
	s_nop 0
	v_pk_mul_f32 v[60:61], v[62:63], v[60:61]
	s_nop 0
	v_pk_mul_f32 v[62:63], v[4:5], v[60:61]
	v_pk_fma_f32 v[60:61], v[4:5], v[60:61], v[4:5] neg_lo:[1,0,0] neg_hi:[1,0,0]
	v_add_f32_e32 v4, v72, v22
	v_cndmask_b32_e32 v60, v60, v62, vcc
	v_cmp_gt_f32_e32 vcc, 0, v5
	v_add_f32_e32 v22, v72, v25
	v_mul_f32_e32 v3, v3, v4
	v_cndmask_b32_e32 v5, v61, v63, vcc
	v_add_f32_e32 v4, v72, v23
	v_mul_f32_e32 v5, v5, v22
	v_add_co_u32_e32 v22, vcc, 0x1506e000, v34
	v_mul_f32_e32 v4, v66, v4
	s_nop 0
	v_addc_co_u32_e32 v23, vcc, 0, v35, vcc
	v_cvt_pk_bf16_f32 v4, v3, v4
	v_add_f32_e32 v3, v72, v24
	s_and_b64 vcc, exec, s[4:5]
	v_mul_f32_e32 v3, v60, v3
	v_cvt_pk_bf16_f32 v5, v3, v5
	global_store_dwordx2 v[22:23], v[4:5], off offset:96
	s_cbranch_vccnz .LBB0_496
	ds_read_b128 v[22:25], v71 offset:17408
	s_waitcnt lgkmcnt(0)
	v_mfma_f32_16x16x32_bf16 v[22:25], v[22:25], v[6:9], 0
	s_and_b64 vcc, exec, s[6:7]
	s_cbranch_vccz .LBB0_497
	s_branch .LBB0_498

.LBB0_502:
	s_waitcnt vmcnt(15)
	v_lshlrev_b32_e32 v4, 16, v58
	v_and_b32_e32 v5, 0xffff0000, v58
	v_fma_f32 v60, |v4|, s40, 1.0
	v_fma_f32 v61, |v5|, s40, 1.0
	v_mov_b64_e32 v[62:63], s[44:45]
	v_rcp_f32_e32 v60, v60
	v_rcp_f32_e32 v61, v61
	s_nop 0
	v_pk_fma_f32 v[64:65], v[60:61], s[42:43], v[62:63] op_sel_hi:[1,0,0]
	s_nop 0
	v_pk_fma_f32 v[64:65], v[60:61], v[64:65], s[48:49] op_sel_hi:[1,1,0]
	s_nop 0
	v_pk_fma_f32 v[64:65], v[60:61], v[64:65], s[50:51] op_sel_hi:[1,1,0]
	s_nop 0
	v_pk_fma_f32 v[64:65], v[60:61], v[64:65], s[56:57] op_sel_hi:[1,1,0]
	s_nop 0
	v_pk_mul_f32 v[60:61], v[60:61], v[64:65]
	v_pk_mul_f32 v[64:65], v[4:5], v[4:5]
	s_nop 0
	v_pk_mul_f32 v[64:65], v[64:65], s[64:65] op_sel_hi:[1,0]
	s_nop 0
	v_exp_f32_e32 v64, v64
	v_exp_f32_e32 v65, v65
	s_nop 0
	v_pk_mul_f32 v[60:61], v[64:65], v[60:61]
	s_nop 0
	v_max_f32_e32 v93, 0, v4
	v_fma_f32 v3, -|v4|, v60, v93
	v_max_f32_e32 v94, 0, v5
	v_fma_f32 v64, -|v5|, v61, v94
	v_lshlrev_b32_e32 v4, 16, v59
	v_and_b32_e32 v5, 0xffff0000, v59
	v_fma_f32 v58, |v4|, s40, 1.0
	v_fma_f32 v59, |v5|, s40, 1.0
	v_rcp_f32_e32 v58, v58
	v_rcp_f32_e32 v59, v59
	v_cmp_gt_f32_e32 vcc, 0, v4
	v_pk_fma_f32 v[60:61], v[58:59], s[42:43], v[62:63] op_sel_hi:[1,0,0]
	s_nop 0
	v_pk_fma_f32 v[60:61], v[58:59], v[60:61], s[48:49] op_sel_hi:[1,1,0]
	s_nop 0
	v_pk_fma_f32 v[60:61], v[58:59], v[60:61], s[50:51] op_sel_hi:[1,1,0]
	s_nop 0
	v_pk_fma_f32 v[60:61], v[58:59], v[60:61], s[56:57] op_sel_hi:[1,1,0]
	s_nop 0
	v_pk_mul_f32 v[58:59], v[58:59], v[60:61]
	v_pk_mul_f32 v[60:61], v[4:5], v[4:5]
	s_nop 0
	v_pk_mul_f32 v[60:61], v[60:61], s[64:65] op_sel_hi:[1,0]
	s_nop 0
	v_exp_f32_e32 v60, v60
	v_exp_f32_e32 v61, v61
	s_nop 0
	v_pk_mul_f32 v[58:59], v[60:61], v[58:59]
	s_nop 0
	v_pk_mul_f32 v[60:61], v[4:5], v[58:59]
	v_pk_fma_f32 v[58:59], v[4:5], v[58:59], v[4:5] neg_lo:[1,0,0] neg_hi:[1,0,0]
	v_add_f32_e32 v4, v72, v22
	v_cndmask_b32_e32 v58, v58, v60, vcc
	v_cmp_gt_f32_e32 vcc, 0, v5
	v_add_f32_e32 v22, v72, v25
	v_mul_f32_e32 v3, v3, v4
	v_cndmask_b32_e32 v5, v59, v61, vcc
	v_add_f32_e32 v4, v72, v23
	v_mul_f32_e32 v5, v5, v22
	v_add_co_u32_e32 v22, vcc, 0x1506e000, v34
	v_mul_f32_e32 v4, v64, v4
	s_nop 0
	v_addc_co_u32_e32 v23, vcc, 0, v35, vcc
	v_cvt_pk_bf16_f32 v4, v3, v4
	v_add_f32_e32 v3, v72, v24
	s_and_b64 vcc, exec, s[4:5]
	v_mul_f32_e32 v3, v58, v3
	v_cvt_pk_bf16_f32 v5, v3, v5
	global_store_dwordx2 v[22:23], v[4:5], off offset:128
	s_cbranch_vccnz .LBB0_504
	ds_read_b128 v[22:25], v71 offset:21760
	s_waitcnt lgkmcnt(0)
	v_mfma_f32_16x16x32_bf16 v[22:25], v[22:25], v[6:9], 0
	s_and_b64 vcc, exec, s[6:7]
	s_cbranch_vccz .LBB0_505
	s_branch .LBB0_506

.LBB0_510:
	s_waitcnt vmcnt(15)
	v_lshlrev_b32_e32 v4, 16, v56
	v_and_b32_e32 v5, 0xffff0000, v56
	v_fma_f32 v58, |v4|, s40, 1.0
	v_fma_f32 v59, |v5|, s40, 1.0
	v_mov_b64_e32 v[60:61], s[44:45]
	v_rcp_f32_e32 v58, v58
	v_rcp_f32_e32 v59, v59
	s_nop 0
	v_pk_fma_f32 v[62:63], v[58:59], s[42:43], v[60:61] op_sel_hi:[1,0,0]
	s_nop 0
	v_pk_fma_f32 v[62:63], v[58:59], v[62:63], s[48:49] op_sel_hi:[1,1,0]
	s_nop 0
	v_pk_fma_f32 v[62:63], v[58:59], v[62:63], s[50:51] op_sel_hi:[1,1,0]
	s_nop 0
	v_pk_fma_f32 v[62:63], v[58:59], v[62:63], s[56:57] op_sel_hi:[1,1,0]
	s_nop 0
	v_pk_mul_f32 v[58:59], v[58:59], v[62:63]
	v_pk_mul_f32 v[62:63], v[4:5], v[4:5]
	s_nop 0
	v_pk_mul_f32 v[62:63], v[62:63], s[64:65] op_sel_hi:[1,0]
	s_nop 0
	v_exp_f32_e32 v62, v62
	v_exp_f32_e32 v63, v63
	s_nop 0
	v_pk_mul_f32 v[58:59], v[62:63], v[58:59]
	s_nop 0
	v_max_f32_e32 v95, 0, v4
	v_fma_f32 v3, -|v4|, v58, v95
	v_max_f32_e32 v96, 0, v5
	v_fma_f32 v62, -|v5|, v59, v96
	v_lshlrev_b32_e32 v4, 16, v57
	v_and_b32_e32 v5, 0xffff0000, v57
	v_fma_f32 v56, |v4|, s40, 1.0
	v_fma_f32 v57, |v5|, s40, 1.0
	v_rcp_f32_e32 v56, v56
	v_rcp_f32_e32 v57, v57
	v_cmp_gt_f32_e32 vcc, 0, v4
	v_pk_fma_f32 v[58:59], v[56:57], s[42:43], v[60:61] op_sel_hi:[1,0,0]
	s_nop 0
	v_pk_fma_f32 v[58:59], v[56:57], v[58:59], s[48:49] op_sel_hi:[1,1,0]
	s_nop 0
	v_pk_fma_f32 v[58:59], v[56:57], v[58:59], s[50:51] op_sel_hi:[1,1,0]
	s_nop 0
	v_pk_fma_f32 v[58:59], v[56:57], v[58:59], s[56:57] op_sel_hi:[1,1,0]
	s_nop 0
	v_pk_mul_f32 v[56:57], v[56:57], v[58:59]
	v_pk_mul_f32 v[58:59], v[4:5], v[4:5]
	s_nop 0
	v_pk_mul_f32 v[58:59], v[58:59], s[64:65] op_sel_hi:[1,0]
	s_nop 0
	v_exp_f32_e32 v58, v58
	v_exp_f32_e32 v59, v59
	s_nop 0
	v_pk_mul_f32 v[56:57], v[58:59], v[56:57]
	s_nop 0
	v_pk_mul_f32 v[58:59], v[4:5], v[56:57]
	v_pk_fma_f32 v[56:57], v[4:5], v[56:57], v[4:5] neg_lo:[1,0,0] neg_hi:[1,0,0]
	v_add_f32_e32 v4, v72, v22
	v_cndmask_b32_e32 v56, v56, v58, vcc
	v_cmp_gt_f32_e32 vcc, 0, v5
	v_add_f32_e32 v22, v72, v25
	v_mul_f32_e32 v3, v3, v4
	v_cndmask_b32_e32 v5, v57, v59, vcc
	v_add_f32_e32 v4, v72, v23
	v_mul_f32_e32 v5, v5, v22
	v_add_co_u32_e32 v22, vcc, 0x1506e000, v34
	v_mul_f32_e32 v4, v62, v4
	s_nop 0
	v_addc_co_u32_e32 v23, vcc, 0, v35, vcc
	v_cvt_pk_bf16_f32 v4, v3, v4
	v_add_f32_e32 v3, v72, v24
	s_and_b64 vcc, exec, s[4:5]
	v_mul_f32_e32 v3, v56, v3
	v_cvt_pk_bf16_f32 v5, v3, v5
	global_store_dwordx2 v[22:23], v[4:5], off offset:160
	s_cbranch_vccnz .LBB0_512
	ds_read_b128 v[22:25], v71 offset:26112
	s_waitcnt lgkmcnt(0)
	v_mfma_f32_16x16x32_bf16 v[22:25], v[22:25], v[6:9], 0
	s_and_b64 vcc, exec, s[6:7]
	s_cbranch_vccz .LBB0_513
	s_branch .LBB0_514

.LBB0_518:
	s_waitcnt vmcnt(15)
	v_lshlrev_b32_e32 v4, 16, v54
	v_and_b32_e32 v5, 0xffff0000, v54
	v_fma_f32 v56, |v4|, s40, 1.0
	v_fma_f32 v57, |v5|, s40, 1.0
	v_mov_b64_e32 v[58:59], s[44:45]
	v_rcp_f32_e32 v56, v56
	v_rcp_f32_e32 v57, v57
	s_nop 0
	v_pk_fma_f32 v[60:61], v[56:57], s[42:43], v[58:59] op_sel_hi:[1,0,0]
	s_nop 0
	v_pk_fma_f32 v[60:61], v[56:57], v[60:61], s[48:49] op_sel_hi:[1,1,0]
	s_nop 0
	v_pk_fma_f32 v[60:61], v[56:57], v[60:61], s[50:51] op_sel_hi:[1,1,0]
	s_nop 0
	v_pk_fma_f32 v[60:61], v[56:57], v[60:61], s[56:57] op_sel_hi:[1,1,0]
	s_nop 0
	v_pk_mul_f32 v[56:57], v[56:57], v[60:61]
	v_pk_mul_f32 v[60:61], v[4:5], v[4:5]
	s_nop 0
	v_pk_mul_f32 v[60:61], v[60:61], s[64:65] op_sel_hi:[1,0]
	s_nop 0
	v_exp_f32_e32 v60, v60
	v_exp_f32_e32 v61, v61
	s_nop 0
	v_pk_mul_f32 v[56:57], v[60:61], v[56:57]
	s_nop 0
	v_max_f32_e32 v97, 0, v4
	v_fma_f32 v3, -|v4|, v56, v97
	v_max_f32_e32 v98, 0, v5
	v_fma_f32 v60, -|v5|, v57, v98
	v_lshlrev_b32_e32 v4, 16, v55
	v_and_b32_e32 v5, 0xffff0000, v55
	v_fma_f32 v54, |v4|, s40, 1.0
	v_fma_f32 v55, |v5|, s40, 1.0
	v_rcp_f32_e32 v54, v54
	v_rcp_f32_e32 v55, v55
	v_cmp_gt_f32_e32 vcc, 0, v4
	v_pk_fma_f32 v[56:57], v[54:55], s[42:43], v[58:59] op_sel_hi:[1,0,0]
	s_nop 0
	v_pk_fma_f32 v[56:57], v[54:55], v[56:57], s[48:49] op_sel_hi:[1,1,0]
	s_nop 0
	v_pk_fma_f32 v[56:57], v[54:55], v[56:57], s[50:51] op_sel_hi:[1,1,0]
	s_nop 0
	v_pk_fma_f32 v[56:57], v[54:55], v[56:57], s[56:57] op_sel_hi:[1,1,0]
	s_nop 0
	v_pk_mul_f32 v[54:55], v[54:55], v[56:57]
	v_pk_mul_f32 v[56:57], v[4:5], v[4:5]
	s_nop 0
	v_pk_mul_f32 v[56:57], v[56:57], s[64:65] op_sel_hi:[1,0]
	s_nop 0
	v_exp_f32_e32 v56, v56
	v_exp_f32_e32 v57, v57
	s_nop 0
	v_pk_mul_f32 v[54:55], v[56:57], v[54:55]
	s_nop 0
	v_pk_mul_f32 v[56:57], v[4:5], v[54:55]
	v_pk_fma_f32 v[54:55], v[4:5], v[54:55], v[4:5] neg_lo:[1,0,0] neg_hi:[1,0,0]
	v_add_f32_e32 v4, v72, v22
	v_cndmask_b32_e32 v54, v54, v56, vcc
	v_cmp_gt_f32_e32 vcc, 0, v5
	v_add_f32_e32 v22, v72, v25
	v_mul_f32_e32 v3, v3, v4
	v_cndmask_b32_e32 v5, v55, v57, vcc
	v_add_f32_e32 v4, v72, v23
	v_mul_f32_e32 v5, v5, v22
	v_add_co_u32_e32 v22, vcc, 0x1506e000, v34
	v_mul_f32_e32 v4, v60, v4
	s_nop 0
	v_addc_co_u32_e32 v23, vcc, 0, v35, vcc
	v_cvt_pk_bf16_f32 v4, v3, v4
	v_add_f32_e32 v3, v72, v24
	s_and_b64 vcc, exec, s[4:5]
	v_mul_f32_e32 v3, v54, v3
	v_cvt_pk_bf16_f32 v5, v3, v5
	global_store_dwordx2 v[22:23], v[4:5], off offset:192
	s_cbranch_vccnz .LBB0_520
	ds_read_b128 v[22:25], v71 offset:30464
	s_waitcnt lgkmcnt(0)
	v_mfma_f32_16x16x32_bf16 v[22:25], v[22:25], v[6:9], 0
	s_and_b64 vcc, exec, s[6:7]
	s_cbranch_vccz .LBB0_521
	s_branch .LBB0_522

.LBB0_526:
	s_waitcnt vmcnt(15)
	v_lshlrev_b32_e32 v4, 16, v52
	v_and_b32_e32 v5, 0xffff0000, v52
	v_fma_f32 v54, |v4|, s40, 1.0
	v_fma_f32 v55, |v5|, s40, 1.0
	v_mov_b64_e32 v[56:57], s[44:45]
	v_rcp_f32_e32 v54, v54
	v_rcp_f32_e32 v55, v55
	s_nop 0
	v_pk_fma_f32 v[58:59], v[54:55], s[42:43], v[56:57] op_sel_hi:[1,0,0]
	s_nop 0
	v_pk_fma_f32 v[58:59], v[54:55], v[58:59], s[48:49] op_sel_hi:[1,1,0]
	s_nop 0
	v_pk_fma_f32 v[58:59], v[54:55], v[58:59], s[50:51] op_sel_hi:[1,1,0]
	s_nop 0
	v_pk_fma_f32 v[58:59], v[54:55], v[58:59], s[56:57] op_sel_hi:[1,1,0]
	s_nop 0
	v_pk_mul_f32 v[54:55], v[54:55], v[58:59]
	v_pk_mul_f32 v[58:59], v[4:5], v[4:5]
	s_nop 0
	v_pk_mul_f32 v[58:59], v[58:59], s[64:65] op_sel_hi:[1,0]
	s_nop 0
	v_exp_f32_e32 v58, v58
	v_exp_f32_e32 v59, v59
	s_nop 0
	v_pk_mul_f32 v[54:55], v[58:59], v[54:55]
	s_nop 0
	v_max_f32_e32 v99, 0, v4
	v_fma_f32 v3, -|v4|, v54, v99
	v_max_f32_e32 v100, 0, v5
	v_fma_f32 v58, -|v5|, v55, v100
	v_lshlrev_b32_e32 v4, 16, v53
	v_and_b32_e32 v5, 0xffff0000, v53
	v_fma_f32 v52, |v4|, s40, 1.0
	v_fma_f32 v53, |v5|, s40, 1.0
	v_rcp_f32_e32 v52, v52
	v_rcp_f32_e32 v53, v53
	v_cmp_gt_f32_e32 vcc, 0, v4
	v_pk_fma_f32 v[54:55], v[52:53], s[42:43], v[56:57] op_sel_hi:[1,0,0]
	s_nop 0
	v_pk_fma_f32 v[54:55], v[52:53], v[54:55], s[48:49] op_sel_hi:[1,1,0]
	s_nop 0
	v_pk_fma_f32 v[54:55], v[52:53], v[54:55], s[50:51] op_sel_hi:[1,1,0]
	s_nop 0
	v_pk_fma_f32 v[54:55], v[52:53], v[54:55], s[56:57] op_sel_hi:[1,1,0]
	s_nop 0
	v_pk_mul_f32 v[52:53], v[52:53], v[54:55]
	v_pk_mul_f32 v[54:55], v[4:5], v[4:5]
	s_nop 0
	v_pk_mul_f32 v[54:55], v[54:55], s[64:65] op_sel_hi:[1,0]
	s_nop 0
	v_exp_f32_e32 v54, v54
	v_exp_f32_e32 v55, v55
	s_nop 0
	v_pk_mul_f32 v[52:53], v[54:55], v[52:53]
	s_nop 0
	v_pk_mul_f32 v[54:55], v[4:5], v[52:53]
	v_pk_fma_f32 v[52:53], v[4:5], v[52:53], v[4:5] neg_lo:[1,0,0] neg_hi:[1,0,0]
	v_add_f32_e32 v4, v72, v22
	v_cndmask_b32_e32 v52, v52, v54, vcc
	v_cmp_gt_f32_e32 vcc, 0, v5
	v_add_f32_e32 v22, v72, v25
	v_mul_f32_e32 v3, v3, v4
	v_cndmask_b32_e32 v5, v53, v55, vcc
	v_add_f32_e32 v4, v72, v23
	v_mul_f32_e32 v5, v5, v22
	v_add_co_u32_e32 v22, vcc, 0x1506e000, v34
	v_mul_f32_e32 v4, v58, v4
	s_nop 0
	v_addc_co_u32_e32 v23, vcc, 0, v35, vcc
	v_cvt_pk_bf16_f32 v4, v3, v4
	v_add_f32_e32 v3, v72, v24
	s_and_b64 vcc, exec, s[4:5]
	v_mul_f32_e32 v3, v52, v3
	v_cvt_pk_bf16_f32 v5, v3, v5
	global_store_dwordx2 v[22:23], v[4:5], off offset:224
	s_cbranch_vccnz .LBB0_528
	ds_read_b128 v[22:25], v71 offset:34816
	s_waitcnt lgkmcnt(0)
	v_mfma_f32_16x16x32_bf16 v[22:25], v[22:25], v[6:9], 0
	s_and_b64 vcc, exec, s[6:7]
	s_cbranch_vccz .LBB0_529
	s_branch .LBB0_530

.LBB0_534:
	s_waitcnt vmcnt(15)
	v_lshlrev_b32_e32 v4, 16, v50
	v_and_b32_e32 v5, 0xffff0000, v50
	v_fma_f32 v52, |v4|, s40, 1.0
	v_fma_f32 v53, |v5|, s40, 1.0
	v_mov_b64_e32 v[54:55], s[44:45]
	v_rcp_f32_e32 v52, v52
	v_rcp_f32_e32 v53, v53
	s_nop 0
	v_pk_fma_f32 v[56:57], v[52:53], s[42:43], v[54:55] op_sel_hi:[1,0,0]
	s_nop 0
	v_pk_fma_f32 v[56:57], v[52:53], v[56:57], s[48:49] op_sel_hi:[1,1,0]
	s_nop 0
	v_pk_fma_f32 v[56:57], v[52:53], v[56:57], s[50:51] op_sel_hi:[1,1,0]
	s_nop 0
	v_pk_fma_f32 v[56:57], v[52:53], v[56:57], s[56:57] op_sel_hi:[1,1,0]
	s_nop 0
	v_pk_mul_f32 v[52:53], v[52:53], v[56:57]
	v_pk_mul_f32 v[56:57], v[4:5], v[4:5]
	s_nop 0
	v_pk_mul_f32 v[56:57], v[56:57], s[64:65] op_sel_hi:[1,0]
	s_nop 0
	v_exp_f32_e32 v56, v56
	v_exp_f32_e32 v57, v57
	s_nop 0
	v_pk_mul_f32 v[52:53], v[56:57], v[52:53]
	s_nop 0
	v_max_f32_e32 v104, 0, v4
	v_fma_f32 v3, -|v4|, v52, v104
	v_max_f32_e32 v105, 0, v5
	v_fma_f32 v56, -|v5|, v53, v105
	v_lshlrev_b32_e32 v4, 16, v51
	v_and_b32_e32 v5, 0xffff0000, v51
	v_fma_f32 v50, |v4|, s40, 1.0
	v_fma_f32 v51, |v5|, s40, 1.0
	v_rcp_f32_e32 v50, v50
	v_rcp_f32_e32 v51, v51
	v_cmp_gt_f32_e32 vcc, 0, v4
	v_pk_fma_f32 v[52:53], v[50:51], s[42:43], v[54:55] op_sel_hi:[1,0,0]
	s_nop 0
	v_pk_fma_f32 v[52:53], v[50:51], v[52:53], s[48:49] op_sel_hi:[1,1,0]
	s_nop 0
	v_pk_fma_f32 v[52:53], v[50:51], v[52:53], s[50:51] op_sel_hi:[1,1,0]
	s_nop 0
	v_pk_fma_f32 v[52:53], v[50:51], v[52:53], s[56:57] op_sel_hi:[1,1,0]
	s_nop 0
	v_pk_mul_f32 v[50:51], v[50:51], v[52:53]
	v_pk_mul_f32 v[52:53], v[4:5], v[4:5]
	s_nop 0
	v_pk_mul_f32 v[52:53], v[52:53], s[64:65] op_sel_hi:[1,0]
	s_nop 0
	v_exp_f32_e32 v52, v52
	v_exp_f32_e32 v53, v53
	s_nop 0
	v_pk_mul_f32 v[50:51], v[52:53], v[50:51]
	s_nop 0
	v_pk_mul_f32 v[52:53], v[4:5], v[50:51]
	v_pk_fma_f32 v[50:51], v[4:5], v[50:51], v[4:5] neg_lo:[1,0,0] neg_hi:[1,0,0]
	v_add_f32_e32 v4, v72, v22
	v_cndmask_b32_e32 v50, v50, v52, vcc
	v_cmp_gt_f32_e32 vcc, 0, v5
	v_add_f32_e32 v22, v72, v25
	v_mul_f32_e32 v3, v3, v4
	v_cndmask_b32_e32 v5, v51, v53, vcc
	v_add_f32_e32 v4, v72, v23
	v_mul_f32_e32 v5, v5, v22
	v_add_co_u32_e32 v22, vcc, 0x1506e000, v34
	v_mul_f32_e32 v4, v56, v4
	s_nop 0
	v_addc_co_u32_e32 v23, vcc, 0, v35, vcc
	v_cvt_pk_bf16_f32 v4, v3, v4
	v_add_f32_e32 v3, v72, v24
	s_and_b64 vcc, exec, s[4:5]
	v_mul_f32_e32 v3, v50, v3
	v_cvt_pk_bf16_f32 v5, v3, v5
	global_store_dwordx2 v[22:23], v[4:5], off offset:256
	s_cbranch_vccnz .LBB0_536
	ds_read_b128 v[22:25], v71 offset:39168
	s_waitcnt lgkmcnt(0)
	v_mfma_f32_16x16x32_bf16 v[22:25], v[22:25], v[6:9], 0
	s_and_b64 vcc, exec, s[6:7]
	s_cbranch_vccz .LBB0_537
	s_branch .LBB0_538

.LBB0_542:
	s_waitcnt vmcnt(15)
	v_lshlrev_b32_e32 v4, 16, v48
	v_and_b32_e32 v5, 0xffff0000, v48
	v_fma_f32 v50, |v4|, s40, 1.0
	v_fma_f32 v51, |v5|, s40, 1.0
	v_mov_b64_e32 v[52:53], s[44:45]
	v_rcp_f32_e32 v50, v50
	v_rcp_f32_e32 v51, v51
	s_nop 0
	v_pk_fma_f32 v[54:55], v[50:51], s[42:43], v[52:53] op_sel_hi:[1,0,0]
	s_nop 0
	v_pk_fma_f32 v[54:55], v[50:51], v[54:55], s[48:49] op_sel_hi:[1,1,0]
	s_nop 0
	v_pk_fma_f32 v[54:55], v[50:51], v[54:55], s[50:51] op_sel_hi:[1,1,0]
	s_nop 0
	v_pk_fma_f32 v[54:55], v[50:51], v[54:55], s[56:57] op_sel_hi:[1,1,0]
	s_nop 0
	v_pk_mul_f32 v[50:51], v[50:51], v[54:55]
	v_pk_mul_f32 v[54:55], v[4:5], v[4:5]
	s_nop 0
	v_pk_mul_f32 v[54:55], v[54:55], s[64:65] op_sel_hi:[1,0]
	s_nop 0
	v_exp_f32_e32 v54, v54
	v_exp_f32_e32 v55, v55
	s_nop 0
	v_pk_mul_f32 v[50:51], v[54:55], v[50:51]
	s_nop 0
	v_max_f32_e32 v106, 0, v4
	v_fma_f32 v3, -|v4|, v50, v106
	v_max_f32_e32 v107, 0, v5
	v_fma_f32 v54, -|v5|, v51, v107
	v_lshlrev_b32_e32 v4, 16, v49
	v_and_b32_e32 v5, 0xffff0000, v49
	v_fma_f32 v48, |v4|, s40, 1.0
	v_fma_f32 v49, |v5|, s40, 1.0
	v_rcp_f32_e32 v48, v48
	v_rcp_f32_e32 v49, v49
	v_cmp_gt_f32_e32 vcc, 0, v4
	v_pk_fma_f32 v[50:51], v[48:49], s[42:43], v[52:53] op_sel_hi:[1,0,0]
	s_nop 0
	v_pk_fma_f32 v[50:51], v[48:49], v[50:51], s[48:49] op_sel_hi:[1,1,0]
	s_nop 0
	v_pk_fma_f32 v[50:51], v[48:49], v[50:51], s[50:51] op_sel_hi:[1,1,0]
	s_nop 0
	v_pk_fma_f32 v[50:51], v[48:49], v[50:51], s[56:57] op_sel_hi:[1,1,0]
	s_nop 0
	v_pk_mul_f32 v[48:49], v[48:49], v[50:51]
	v_pk_mul_f32 v[50:51], v[4:5], v[4:5]
	s_nop 0
	v_pk_mul_f32 v[50:51], v[50:51], s[64:65] op_sel_hi:[1,0]
	s_nop 0
	v_exp_f32_e32 v50, v50
	v_exp_f32_e32 v51, v51
	s_nop 0
	v_pk_mul_f32 v[48:49], v[50:51], v[48:49]
	s_nop 0
	v_pk_mul_f32 v[50:51], v[4:5], v[48:49]
	v_pk_fma_f32 v[48:49], v[4:5], v[48:49], v[4:5] neg_lo:[1,0,0] neg_hi:[1,0,0]
	v_add_f32_e32 v4, v72, v22
	v_cndmask_b32_e32 v48, v48, v50, vcc
	v_cmp_gt_f32_e32 vcc, 0, v5
	v_add_f32_e32 v22, v72, v25
	v_mul_f32_e32 v3, v3, v4
	v_cndmask_b32_e32 v5, v49, v51, vcc
	v_add_f32_e32 v4, v72, v23
	v_mul_f32_e32 v5, v5, v22
	v_add_co_u32_e32 v22, vcc, 0x1506e000, v34
	v_mul_f32_e32 v4, v54, v4
	s_nop 0
	v_addc_co_u32_e32 v23, vcc, 0, v35, vcc
	v_cvt_pk_bf16_f32 v4, v3, v4
	v_add_f32_e32 v3, v72, v24
	s_and_b64 vcc, exec, s[4:5]
	v_mul_f32_e32 v3, v48, v3
	v_cvt_pk_bf16_f32 v5, v3, v5
	global_store_dwordx2 v[22:23], v[4:5], off offset:288
	s_cbranch_vccnz .LBB0_544
	ds_read_b128 v[22:25], v71 offset:43520
	s_waitcnt lgkmcnt(0)
	v_mfma_f32_16x16x32_bf16 v[22:25], v[22:25], v[6:9], 0
	s_and_b64 vcc, exec, s[6:7]
	s_cbranch_vccz .LBB0_545
	s_branch .LBB0_546

.LBB0_550:
	s_waitcnt vmcnt(15)
	v_lshlrev_b32_e32 v4, 16, v46
	v_and_b32_e32 v5, 0xffff0000, v46
	v_fma_f32 v48, |v4|, s40, 1.0
	v_fma_f32 v49, |v5|, s40, 1.0
	v_mov_b64_e32 v[50:51], s[44:45]
	v_rcp_f32_e32 v48, v48
	v_rcp_f32_e32 v49, v49
	s_nop 0
	v_pk_fma_f32 v[52:53], v[48:49], s[42:43], v[50:51] op_sel_hi:[1,0,0]
	s_nop 0
	v_pk_fma_f32 v[52:53], v[48:49], v[52:53], s[48:49] op_sel_hi:[1,1,0]
	s_nop 0
	v_pk_fma_f32 v[52:53], v[48:49], v[52:53], s[50:51] op_sel_hi:[1,1,0]
	s_nop 0
	v_pk_fma_f32 v[52:53], v[48:49], v[52:53], s[56:57] op_sel_hi:[1,1,0]
	s_nop 0
	v_pk_mul_f32 v[48:49], v[48:49], v[52:53]
	v_pk_mul_f32 v[52:53], v[4:5], v[4:5]
	s_nop 0
	v_pk_mul_f32 v[52:53], v[52:53], s[64:65] op_sel_hi:[1,0]
	s_nop 0
	v_exp_f32_e32 v52, v52
	v_exp_f32_e32 v53, v53
	s_nop 0
	v_pk_mul_f32 v[48:49], v[52:53], v[48:49]
	s_nop 0
	v_max_f32_e32 v108, 0, v4
	v_fma_f32 v3, -|v4|, v48, v108
	v_max_f32_e32 v109, 0, v5
	v_fma_f32 v52, -|v5|, v49, v109
	v_lshlrev_b32_e32 v4, 16, v47
	v_and_b32_e32 v5, 0xffff0000, v47
	v_fma_f32 v46, |v4|, s40, 1.0
	v_fma_f32 v47, |v5|, s40, 1.0
	v_rcp_f32_e32 v46, v46
	v_rcp_f32_e32 v47, v47
	v_cmp_gt_f32_e32 vcc, 0, v4
	v_pk_fma_f32 v[48:49], v[46:47], s[42:43], v[50:51] op_sel_hi:[1,0,0]
	s_nop 0
	v_pk_fma_f32 v[48:49], v[46:47], v[48:49], s[48:49] op_sel_hi:[1,1,0]
	s_nop 0
	v_pk_fma_f32 v[48:49], v[46:47], v[48:49], s[50:51] op_sel_hi:[1,1,0]
	s_nop 0
	v_pk_fma_f32 v[48:49], v[46:47], v[48:49], s[56:57] op_sel_hi:[1,1,0]
	s_nop 0
	v_pk_mul_f32 v[46:47], v[46:47], v[48:49]
	v_pk_mul_f32 v[48:49], v[4:5], v[4:5]
	s_nop 0
	v_pk_mul_f32 v[48:49], v[48:49], s[64:65] op_sel_hi:[1,0]
	s_nop 0
	v_exp_f32_e32 v48, v48
	v_exp_f32_e32 v49, v49
	s_nop 0
	v_pk_mul_f32 v[46:47], v[48:49], v[46:47]
	s_nop 0
	v_pk_mul_f32 v[48:49], v[4:5], v[46:47]
	v_pk_fma_f32 v[46:47], v[4:5], v[46:47], v[4:5] neg_lo:[1,0,0] neg_hi:[1,0,0]
	v_add_f32_e32 v4, v72, v22
	v_cndmask_b32_e32 v46, v46, v48, vcc
	v_cmp_gt_f32_e32 vcc, 0, v5
	v_add_f32_e32 v22, v72, v25
	v_mul_f32_e32 v3, v3, v4
	v_cndmask_b32_e32 v5, v47, v49, vcc
	v_add_f32_e32 v4, v72, v23
	v_mul_f32_e32 v5, v5, v22
	v_add_co_u32_e32 v22, vcc, 0x1506e000, v34
	v_mul_f32_e32 v4, v52, v4
	s_nop 0
	v_addc_co_u32_e32 v23, vcc, 0, v35, vcc
	v_cvt_pk_bf16_f32 v4, v3, v4
	v_add_f32_e32 v3, v72, v24
	s_and_b64 vcc, exec, s[4:5]
	v_mul_f32_e32 v3, v46, v3
	v_cvt_pk_bf16_f32 v5, v3, v5
	global_store_dwordx2 v[22:23], v[4:5], off offset:320
	s_cbranch_vccnz .LBB0_552
	ds_read_b128 v[22:25], v71 offset:47872
	s_waitcnt lgkmcnt(0)
	v_mfma_f32_16x16x32_bf16 v[22:25], v[22:25], v[6:9], 0
	s_and_b64 vcc, exec, s[6:7]
	s_cbranch_vccz .LBB0_553
	s_branch .LBB0_554

.LBB0_558:
	s_waitcnt vmcnt(15)
	v_lshlrev_b32_e32 v4, 16, v44
	v_and_b32_e32 v5, 0xffff0000, v44
	v_fma_f32 v46, |v4|, s40, 1.0
	v_fma_f32 v47, |v5|, s40, 1.0
	v_mov_b64_e32 v[48:49], s[44:45]
	v_rcp_f32_e32 v46, v46
	v_rcp_f32_e32 v47, v47
	s_nop 0
	v_pk_fma_f32 v[50:51], v[46:47], s[42:43], v[48:49] op_sel_hi:[1,0,0]
	s_nop 0
	v_pk_fma_f32 v[50:51], v[46:47], v[50:51], s[48:49] op_sel_hi:[1,1,0]
	s_nop 0
	v_pk_fma_f32 v[50:51], v[46:47], v[50:51], s[50:51] op_sel_hi:[1,1,0]
	s_nop 0
	v_pk_fma_f32 v[50:51], v[46:47], v[50:51], s[56:57] op_sel_hi:[1,1,0]
	s_nop 0
	v_pk_mul_f32 v[46:47], v[46:47], v[50:51]
	v_pk_mul_f32 v[50:51], v[4:5], v[4:5]
	s_nop 0
	v_pk_mul_f32 v[50:51], v[50:51], s[64:65] op_sel_hi:[1,0]
	s_nop 0
	v_exp_f32_e32 v50, v50
	v_exp_f32_e32 v51, v51
	s_nop 0
	v_pk_mul_f32 v[46:47], v[50:51], v[46:47]
	s_nop 0
	v_max_f32_e32 v110, 0, v4
	v_fma_f32 v3, -|v4|, v46, v110
	v_max_f32_e32 v111, 0, v5
	v_fma_f32 v50, -|v5|, v47, v111
	v_lshlrev_b32_e32 v4, 16, v45
	v_and_b32_e32 v5, 0xffff0000, v45
	v_fma_f32 v44, |v4|, s40, 1.0
	v_fma_f32 v45, |v5|, s40, 1.0
	v_rcp_f32_e32 v44, v44
	v_rcp_f32_e32 v45, v45
	v_cmp_gt_f32_e32 vcc, 0, v4
	v_pk_fma_f32 v[46:47], v[44:45], s[42:43], v[48:49] op_sel_hi:[1,0,0]
	s_nop 0
	v_pk_fma_f32 v[46:47], v[44:45], v[46:47], s[48:49] op_sel_hi:[1,1,0]
	s_nop 0
	v_pk_fma_f32 v[46:47], v[44:45], v[46:47], s[50:51] op_sel_hi:[1,1,0]
	s_nop 0
	v_pk_fma_f32 v[46:47], v[44:45], v[46:47], s[56:57] op_sel_hi:[1,1,0]
	s_nop 0
	v_pk_mul_f32 v[44:45], v[44:45], v[46:47]
	v_pk_mul_f32 v[46:47], v[4:5], v[4:5]
	s_nop 0
	v_pk_mul_f32 v[46:47], v[46:47], s[64:65] op_sel_hi:[1,0]
	s_nop 0
	v_exp_f32_e32 v46, v46
	v_exp_f32_e32 v47, v47
	s_nop 0
	v_pk_mul_f32 v[44:45], v[46:47], v[44:45]
	s_nop 0
	v_pk_mul_f32 v[46:47], v[4:5], v[44:45]
	v_pk_fma_f32 v[44:45], v[4:5], v[44:45], v[4:5] neg_lo:[1,0,0] neg_hi:[1,0,0]
	v_add_f32_e32 v4, v72, v22
	v_cndmask_b32_e32 v44, v44, v46, vcc
	v_cmp_gt_f32_e32 vcc, 0, v5
	v_add_f32_e32 v22, v72, v25
	v_mul_f32_e32 v3, v3, v4
	v_cndmask_b32_e32 v5, v45, v47, vcc
	v_add_f32_e32 v4, v72, v23
	v_mul_f32_e32 v5, v5, v22
	v_add_co_u32_e32 v22, vcc, 0x1506e000, v34
	v_mul_f32_e32 v4, v50, v4
	s_nop 0
	v_addc_co_u32_e32 v23, vcc, 0, v35, vcc
	v_cvt_pk_bf16_f32 v4, v3, v4
	v_add_f32_e32 v3, v72, v24
	s_and_b64 vcc, exec, s[4:5]
	v_mul_f32_e32 v3, v44, v3
	v_cvt_pk_bf16_f32 v5, v3, v5
	global_store_dwordx2 v[22:23], v[4:5], off offset:352
	s_cbranch_vccnz .LBB0_560
	ds_read_b128 v[22:25], v71 offset:52224
	s_waitcnt lgkmcnt(0)
	v_mfma_f32_16x16x32_bf16 v[22:25], v[22:25], v[6:9], 0
	s_and_b64 vcc, exec, s[6:7]
	s_cbranch_vccz .LBB0_561
	s_branch .LBB0_562

.LBB0_566:
	s_waitcnt vmcnt(15)
	v_lshlrev_b32_e32 v4, 16, v42
	v_and_b32_e32 v5, 0xffff0000, v42
	v_fma_f32 v44, |v4|, s40, 1.0
	v_fma_f32 v45, |v5|, s40, 1.0
	v_mov_b64_e32 v[46:47], s[44:45]
	v_rcp_f32_e32 v44, v44
	v_rcp_f32_e32 v45, v45
	s_nop 0
	v_pk_fma_f32 v[48:49], v[44:45], s[42:43], v[46:47] op_sel_hi:[1,0,0]
	s_nop 0
	v_pk_fma_f32 v[48:49], v[44:45], v[48:49], s[48:49] op_sel_hi:[1,1,0]
	s_nop 0
	v_pk_fma_f32 v[48:49], v[44:45], v[48:49], s[50:51] op_sel_hi:[1,1,0]
	s_nop 0
	v_pk_fma_f32 v[48:49], v[44:45], v[48:49], s[56:57] op_sel_hi:[1,1,0]
	s_nop 0
	v_pk_mul_f32 v[44:45], v[44:45], v[48:49]
	v_pk_mul_f32 v[48:49], v[4:5], v[4:5]
	s_nop 0
	v_pk_mul_f32 v[48:49], v[48:49], s[64:65] op_sel_hi:[1,0]
	s_nop 0
	v_exp_f32_e32 v48, v48
	v_exp_f32_e32 v49, v49
	s_nop 0
	v_pk_mul_f32 v[44:45], v[48:49], v[44:45]
	s_nop 0
	v_max_f32_e32 v112, 0, v4
	v_fma_f32 v3, -|v4|, v44, v112
	v_max_f32_e32 v113, 0, v5
	v_fma_f32 v48, -|v5|, v45, v113
	v_lshlrev_b32_e32 v4, 16, v43
	v_and_b32_e32 v5, 0xffff0000, v43
	v_fma_f32 v42, |v4|, s40, 1.0
	v_fma_f32 v43, |v5|, s40, 1.0
	v_rcp_f32_e32 v42, v42
	v_rcp_f32_e32 v43, v43
	v_cmp_gt_f32_e32 vcc, 0, v4
	v_pk_fma_f32 v[44:45], v[42:43], s[42:43], v[46:47] op_sel_hi:[1,0,0]
	s_nop 0
	v_pk_fma_f32 v[44:45], v[42:43], v[44:45], s[48:49] op_sel_hi:[1,1,0]
	s_nop 0
	v_pk_fma_f32 v[44:45], v[42:43], v[44:45], s[50:51] op_sel_hi:[1,1,0]
	s_nop 0
	v_pk_fma_f32 v[44:45], v[42:43], v[44:45], s[56:57] op_sel_hi:[1,1,0]
	s_nop 0
	v_pk_mul_f32 v[42:43], v[42:43], v[44:45]
	v_pk_mul_f32 v[44:45], v[4:5], v[4:5]
	s_nop 0
	v_pk_mul_f32 v[44:45], v[44:45], s[64:65] op_sel_hi:[1,0]
	s_nop 0
	v_exp_f32_e32 v44, v44
	v_exp_f32_e32 v45, v45
	s_nop 0
	v_pk_mul_f32 v[42:43], v[44:45], v[42:43]
	s_nop 0
	v_pk_mul_f32 v[44:45], v[4:5], v[42:43]
	v_pk_fma_f32 v[42:43], v[4:5], v[42:43], v[4:5] neg_lo:[1,0,0] neg_hi:[1,0,0]
	v_add_f32_e32 v4, v72, v22
	v_cndmask_b32_e32 v42, v42, v44, vcc
	v_cmp_gt_f32_e32 vcc, 0, v5
	v_add_f32_e32 v22, v72, v25
	v_mul_f32_e32 v3, v3, v4
	v_cndmask_b32_e32 v5, v43, v45, vcc
	v_add_f32_e32 v4, v72, v23
	v_mul_f32_e32 v5, v5, v22
	v_add_co_u32_e32 v22, vcc, 0x1506e000, v34
	v_mul_f32_e32 v4, v48, v4
	s_nop 0
	v_addc_co_u32_e32 v23, vcc, 0, v35, vcc
	v_cvt_pk_bf16_f32 v4, v3, v4
	v_add_f32_e32 v3, v72, v24
	s_and_b64 vcc, exec, s[4:5]
	v_mul_f32_e32 v3, v42, v3
	v_cvt_pk_bf16_f32 v5, v3, v5
	global_store_dwordx2 v[22:23], v[4:5], off offset:384
	s_cbranch_vccnz .LBB0_568
	ds_read_b128 v[22:25], v71 offset:56576
	s_waitcnt lgkmcnt(0)
	v_mfma_f32_16x16x32_bf16 v[22:25], v[22:25], v[6:9], 0
	s_and_b64 vcc, exec, s[6:7]
	s_cbranch_vccz .LBB0_569
	s_branch .LBB0_570

.LBB0_574:
	s_waitcnt vmcnt(15)
	v_lshlrev_b32_e32 v4, 16, v40
	v_and_b32_e32 v5, 0xffff0000, v40
	v_fma_f32 v42, |v4|, s40, 1.0
	v_fma_f32 v43, |v5|, s40, 1.0
	v_mov_b64_e32 v[44:45], s[44:45]
	v_rcp_f32_e32 v42, v42
	v_rcp_f32_e32 v43, v43
	s_nop 0
	v_pk_fma_f32 v[46:47], v[42:43], s[42:43], v[44:45] op_sel_hi:[1,0,0]
	s_nop 0
	v_pk_fma_f32 v[46:47], v[42:43], v[46:47], s[48:49] op_sel_hi:[1,1,0]
	s_nop 0
	v_pk_fma_f32 v[46:47], v[42:43], v[46:47], s[50:51] op_sel_hi:[1,1,0]
	s_nop 0
	v_pk_fma_f32 v[46:47], v[42:43], v[46:47], s[56:57] op_sel_hi:[1,1,0]
	s_nop 0
	v_pk_mul_f32 v[42:43], v[42:43], v[46:47]
	v_pk_mul_f32 v[46:47], v[4:5], v[4:5]
	s_nop 0
	v_pk_mul_f32 v[46:47], v[46:47], s[64:65] op_sel_hi:[1,0]
	s_nop 0
	v_exp_f32_e32 v46, v46
	v_exp_f32_e32 v47, v47
	s_nop 0
	v_pk_mul_f32 v[42:43], v[46:47], v[42:43]
	s_nop 0
	v_max_f32_e32 v114, 0, v4
	v_fma_f32 v3, -|v4|, v42, v114
	v_max_f32_e32 v115, 0, v5
	v_fma_f32 v46, -|v5|, v43, v115
	v_lshlrev_b32_e32 v4, 16, v41
	v_and_b32_e32 v5, 0xffff0000, v41
	v_fma_f32 v40, |v4|, s40, 1.0
	v_fma_f32 v41, |v5|, s40, 1.0
	v_rcp_f32_e32 v40, v40
	v_rcp_f32_e32 v41, v41
	v_cmp_gt_f32_e32 vcc, 0, v4
	v_pk_fma_f32 v[42:43], v[40:41], s[42:43], v[44:45] op_sel_hi:[1,0,0]
	s_nop 0
	v_pk_fma_f32 v[42:43], v[40:41], v[42:43], s[48:49] op_sel_hi:[1,1,0]
	s_nop 0
	v_pk_fma_f32 v[42:43], v[40:41], v[42:43], s[50:51] op_sel_hi:[1,1,0]
	s_nop 0
	v_pk_fma_f32 v[42:43], v[40:41], v[42:43], s[56:57] op_sel_hi:[1,1,0]
	s_nop 0
	v_pk_mul_f32 v[40:41], v[40:41], v[42:43]
	v_pk_mul_f32 v[42:43], v[4:5], v[4:5]
	s_nop 0
	v_pk_mul_f32 v[42:43], v[42:43], s[64:65] op_sel_hi:[1,0]
	s_nop 0
	v_exp_f32_e32 v42, v42
	v_exp_f32_e32 v43, v43
	s_nop 0
	v_pk_mul_f32 v[40:41], v[42:43], v[40:41]
	s_nop 0
	v_pk_mul_f32 v[42:43], v[4:5], v[40:41]
	v_pk_fma_f32 v[40:41], v[4:5], v[40:41], v[4:5] neg_lo:[1,0,0] neg_hi:[1,0,0]
	v_add_f32_e32 v4, v72, v22
	v_cndmask_b32_e32 v40, v40, v42, vcc
	v_cmp_gt_f32_e32 vcc, 0, v5
	v_add_f32_e32 v22, v72, v25
	v_mul_f32_e32 v3, v3, v4
	v_cndmask_b32_e32 v5, v41, v43, vcc
	v_add_f32_e32 v4, v72, v23
	v_mul_f32_e32 v5, v5, v22
	v_add_co_u32_e32 v22, vcc, 0x1506e000, v34
	v_mul_f32_e32 v4, v46, v4
	s_nop 0
	v_addc_co_u32_e32 v23, vcc, 0, v35, vcc
	v_cvt_pk_bf16_f32 v4, v3, v4
	v_add_f32_e32 v3, v72, v24
	s_and_b64 vcc, exec, s[4:5]
	v_mul_f32_e32 v3, v40, v3
	v_cvt_pk_bf16_f32 v5, v3, v5
	global_store_dwordx2 v[22:23], v[4:5], off offset:416
	s_cbranch_vccnz .LBB0_576
	ds_read_b128 v[22:25], v71 offset:60928
	s_waitcnt lgkmcnt(0)
	v_mfma_f32_16x16x32_bf16 v[22:25], v[22:25], v[6:9], 0
	s_and_b64 vcc, exec, s[6:7]
	s_cbranch_vccz .LBB0_577
	s_branch .LBB0_578

.LBB0_582:
	s_waitcnt vmcnt(15)
	v_lshlrev_b32_e32 v4, 16, v38
	v_and_b32_e32 v5, 0xffff0000, v38
	v_fma_f32 v40, |v4|, s40, 1.0
	v_fma_f32 v41, |v5|, s40, 1.0
	v_mov_b64_e32 v[42:43], s[44:45]
	v_rcp_f32_e32 v40, v40
	v_rcp_f32_e32 v41, v41
	s_nop 0
	v_pk_fma_f32 v[44:45], v[40:41], s[42:43], v[42:43] op_sel_hi:[1,0,0]
	s_nop 0
	v_pk_fma_f32 v[44:45], v[40:41], v[44:45], s[48:49] op_sel_hi:[1,1,0]
	s_nop 0
	v_pk_fma_f32 v[44:45], v[40:41], v[44:45], s[50:51] op_sel_hi:[1,1,0]
	s_nop 0
	v_pk_fma_f32 v[44:45], v[40:41], v[44:45], s[56:57] op_sel_hi:[1,1,0]
	s_nop 0
	v_pk_mul_f32 v[40:41], v[40:41], v[44:45]
	v_pk_mul_f32 v[44:45], v[4:5], v[4:5]
	s_nop 0
	v_pk_mul_f32 v[44:45], v[44:45], s[64:65] op_sel_hi:[1,0]
	s_nop 0
	v_exp_f32_e32 v44, v44
	v_exp_f32_e32 v45, v45
	s_nop 0
	v_pk_mul_f32 v[40:41], v[44:45], v[40:41]
	s_nop 0
	v_max_f32_e32 v116, 0, v4
	v_fma_f32 v3, -|v4|, v40, v116
	v_max_f32_e32 v117, 0, v5
	v_fma_f32 v44, -|v5|, v41, v117
	v_lshlrev_b32_e32 v4, 16, v39
	v_and_b32_e32 v5, 0xffff0000, v39
	v_fma_f32 v38, |v4|, s40, 1.0
	v_fma_f32 v39, |v5|, s40, 1.0
	v_rcp_f32_e32 v38, v38
	v_rcp_f32_e32 v39, v39
	v_cmp_gt_f32_e32 vcc, 0, v4
	v_pk_fma_f32 v[40:41], v[38:39], s[42:43], v[42:43] op_sel_hi:[1,0,0]
	s_nop 0
	v_pk_fma_f32 v[40:41], v[38:39], v[40:41], s[48:49] op_sel_hi:[1,1,0]
	s_nop 0
	v_pk_fma_f32 v[40:41], v[38:39], v[40:41], s[50:51] op_sel_hi:[1,1,0]
	s_nop 0
	v_pk_fma_f32 v[40:41], v[38:39], v[40:41], s[56:57] op_sel_hi:[1,1,0]
	s_nop 0
	v_pk_mul_f32 v[38:39], v[38:39], v[40:41]
	v_pk_mul_f32 v[40:41], v[4:5], v[4:5]
	s_nop 0
	v_pk_mul_f32 v[40:41], v[40:41], s[64:65] op_sel_hi:[1,0]
	s_nop 0
	v_exp_f32_e32 v40, v40
	v_exp_f32_e32 v41, v41
	s_nop 0
	v_pk_mul_f32 v[38:39], v[40:41], v[38:39]
	s_nop 0
	v_pk_mul_f32 v[40:41], v[4:5], v[38:39]
	v_pk_fma_f32 v[38:39], v[4:5], v[38:39], v[4:5] neg_lo:[1,0,0] neg_hi:[1,0,0]
	v_add_f32_e32 v4, v72, v22
	v_cndmask_b32_e32 v38, v38, v40, vcc
	v_cmp_gt_f32_e32 vcc, 0, v5
	v_add_f32_e32 v22, v72, v25
	v_mul_f32_e32 v3, v3, v4
	v_cndmask_b32_e32 v5, v39, v41, vcc
	v_add_f32_e32 v4, v72, v23
	v_mul_f32_e32 v5, v5, v22
	v_add_co_u32_e32 v22, vcc, 0x1506e000, v34
	v_mul_f32_e32 v4, v44, v4
	s_nop 0
	v_addc_co_u32_e32 v23, vcc, 0, v35, vcc
	v_cvt_pk_bf16_f32 v4, v3, v4
	v_add_f32_e32 v3, v72, v24
	s_and_b64 vcc, exec, s[4:5]
	v_mul_f32_e32 v3, v38, v3
	v_cvt_pk_bf16_f32 v5, v3, v5
	global_store_dwordx2 v[22:23], v[4:5], off offset:448
	s_cbranch_vccnz .LBB0_584
	ds_read_b128 v[22:25], v71 offset:65280
	s_waitcnt lgkmcnt(0)
	v_mfma_f32_16x16x32_bf16 v[4:7], v[22:25], v[6:9], 0
	s_and_b64 vcc, exec, s[6:7]
	s_cbranch_vccz .LBB0_585
	s_branch .LBB0_586
